# pipelined hand-written adaLN-RMSNorm phases (next-row prefetch, gain kept in registers), mod_unit GEMV loop with 4 iterations of loads in flight
# speedup vs baseline: 1.1599x; 1.0177x over previous
.LBB0_21:
	v_mov_b32_e32 v58, 0x6000
	v_mov_b32_e32 v59, 0
	v_mov_b32_e32 v60, 0xc000
	v_mov_b32_e32 v61, 0
	v_mov_b32_e32 v62, 0x12000
	v_mov_b32_e32 v63, 0
	s_mov_b32 s98, 0
	s_mov_b32 s99, 0
	v_lshl_add_u64 v[50:51], v[12:13], 0, s[98:99]
	v_lshl_add_u64 v[52:53], v[50:51], 0, v[58:59]
	v_lshl_add_u64 v[54:55], v[50:51], 0, v[60:61]
	v_lshl_add_u64 v[56:57], v[50:51], 0, v[62:63]
	global_load_dwordx4 v[64:67], v[50:51], off
	global_load_dwordx4 v[68:71], v[52:53], off
	global_load_dwordx4 v[72:75], v[54:55], off
	global_load_dwordx4 v[76:79], v[56:57], off
	s_add_u32 s98, s98, 0x18000
	s_addc_u32 s99, s99, 0
	v_lshl_add_u64 v[50:51], v[12:13], 0, s[98:99]
	v_lshl_add_u64 v[52:53], v[50:51], 0, v[58:59]
	v_lshl_add_u64 v[54:55], v[50:51], 0, v[60:61]
	v_lshl_add_u64 v[56:57], v[50:51], 0, v[62:63]
	global_load_dwordx4 v[80:83], v[50:51], off
	global_load_dwordx4 v[84:87], v[52:53], off
	global_load_dwordx4 v[88:91], v[54:55], off
	global_load_dwordx4 v[92:95], v[56:57], off
	s_add_u32 s98, s98, 0x18000
	s_addc_u32 s99, s99, 0
	v_lshl_add_u64 v[50:51], v[12:13], 0, s[98:99]
	v_lshl_add_u64 v[52:53], v[50:51], 0, v[58:59]
	v_lshl_add_u64 v[54:55], v[50:51], 0, v[60:61]
	v_lshl_add_u64 v[56:57], v[50:51], 0, v[62:63]
	global_load_dwordx4 v[96:99], v[50:51], off
	global_load_dwordx4 v[100:103], v[52:53], off
	global_load_dwordx4 v[104:107], v[54:55], off
	global_load_dwordx4 v[108:111], v[56:57], off
	s_add_u32 s98, s98, 0x18000
	s_addc_u32 s99, s99, 0
	v_lshl_add_u64 v[50:51], v[12:13], 0, s[98:99]
	v_lshl_add_u64 v[52:53], v[50:51], 0, v[58:59]
	v_lshl_add_u64 v[54:55], v[50:51], 0, v[60:61]
	v_lshl_add_u64 v[56:57], v[50:51], 0, v[62:63]
	global_load_dwordx4 v[112:115], v[50:51], off
	global_load_dwordx4 v[116:119], v[52:53], off
	global_load_dwordx4 v[120:123], v[54:55], off
	global_load_dwordx4 v[124:127], v[56:57], off
	s_add_u32 s98, s98, 0x18000
	s_addc_u32 s99, s99, 0
	s_movk_i32 s100, 7
.Lmod_loop:
	ds_read_b128 v[32:35], v15
	ds_read_b128 v[36:39], v15 offset:4096
	ds_read_b128 v[40:43], v15 offset:8192
	v_add_u32_e32 v15, 16, v15
	s_waitcnt lgkmcnt(2)
	v_mov_b32_e32 v44, v35
	s_waitcnt lgkmcnt(1)
	v_mov_b32_e32 v46, v39
	s_waitcnt lgkmcnt(0)
	v_mov_b32_e32 v48, v43
	s_waitcnt vmcnt(12)
	v_pk_fma_f32 v[0:1], v[64:65], v[32:33], v[0:1] op_sel_hi:[1,0,1]
	v_pk_fma_f32 v[2:3], v[66:67], v[32:33], v[2:3] op_sel_hi:[1,0,1]
	v_pk_fma_f32 v[8:9], v[64:65], v[36:37], v[8:9] op_sel_hi:[1,0,1]
	v_pk_fma_f32 v[10:11], v[66:67], v[36:37], v[10:11] op_sel_hi:[1,0,1]
	v_pk_fma_f32 v[4:5], v[64:65], v[40:41], v[4:5] op_sel_hi:[1,0,1]
	v_pk_fma_f32 v[6:7], v[66:67], v[40:41], v[6:7] op_sel_hi:[1,0,1]
	v_pk_fma_f32 v[0:1], v[68:69], v[32:33], v[0:1] op_sel:[0,1,0]
	v_pk_fma_f32 v[2:3], v[70:71], v[32:33], v[2:3] op_sel:[0,1,0]
	v_pk_fma_f32 v[8:9], v[68:69], v[36:37], v[8:9] op_sel:[0,1,0]
	v_pk_fma_f32 v[10:11], v[70:71], v[36:37], v[10:11] op_sel:[0,1,0]
	v_pk_fma_f32 v[4:5], v[68:69], v[40:41], v[4:5] op_sel:[0,1,0]
	v_pk_fma_f32 v[6:7], v[70:71], v[40:41], v[6:7] op_sel:[0,1,0]
	v_pk_fma_f32 v[0:1], v[72:73], v[34:35], v[0:1] op_sel_hi:[1,0,1]
	v_pk_fma_f32 v[2:3], v[74:75], v[34:35], v[2:3] op_sel_hi:[1,0,1]
	v_pk_fma_f32 v[8:9], v[72:73], v[38:39], v[8:9] op_sel_hi:[1,0,1]
	v_pk_fma_f32 v[10:11], v[74:75], v[38:39], v[10:11] op_sel_hi:[1,0,1]
	v_pk_fma_f32 v[4:5], v[72:73], v[42:43], v[4:5] op_sel_hi:[1,0,1]
	v_pk_fma_f32 v[6:7], v[74:75], v[42:43], v[6:7] op_sel_hi:[1,0,1]
	v_pk_fma_f32 v[0:1], v[76:77], v[44:45], v[0:1] op_sel_hi:[1,0,1]
	v_pk_fma_f32 v[2:3], v[78:79], v[44:45], v[2:3] op_sel_hi:[1,0,1]
	v_pk_fma_f32 v[8:9], v[76:77], v[46:47], v[8:9] op_sel_hi:[1,0,1]
	v_pk_fma_f32 v[10:11], v[78:79], v[46:47], v[10:11] op_sel_hi:[1,0,1]
	v_pk_fma_f32 v[4:5], v[76:77], v[48:49], v[4:5] op_sel_hi:[1,0,1]
	v_pk_fma_f32 v[6:7], v[78:79], v[48:49], v[6:7] op_sel_hi:[1,0,1]
	v_lshl_add_u64 v[50:51], v[12:13], 0, s[98:99]
	v_lshl_add_u64 v[52:53], v[50:51], 0, v[58:59]
	v_lshl_add_u64 v[54:55], v[50:51], 0, v[60:61]
	v_lshl_add_u64 v[56:57], v[50:51], 0, v[62:63]
	global_load_dwordx4 v[64:67], v[50:51], off
	global_load_dwordx4 v[68:71], v[52:53], off
	global_load_dwordx4 v[72:75], v[54:55], off
	global_load_dwordx4 v[76:79], v[56:57], off
	s_add_u32 s98, s98, 0x18000
	s_addc_u32 s99, s99, 0
	ds_read_b128 v[32:35], v15
	ds_read_b128 v[36:39], v15 offset:4096
	ds_read_b128 v[40:43], v15 offset:8192
	v_add_u32_e32 v15, 16, v15
	s_waitcnt lgkmcnt(2)
	v_mov_b32_e32 v44, v35
	s_waitcnt lgkmcnt(1)
	v_mov_b32_e32 v46, v39
	s_waitcnt lgkmcnt(0)
	v_mov_b32_e32 v48, v43
	s_waitcnt vmcnt(12)
	v_pk_fma_f32 v[0:1], v[80:81], v[32:33], v[0:1] op_sel_hi:[1,0,1]
	v_pk_fma_f32 v[2:3], v[82:83], v[32:33], v[2:3] op_sel_hi:[1,0,1]
	v_pk_fma_f32 v[8:9], v[80:81], v[36:37], v[8:9] op_sel_hi:[1,0,1]
	v_pk_fma_f32 v[10:11], v[82:83], v[36:37], v[10:11] op_sel_hi:[1,0,1]
	v_pk_fma_f32 v[4:5], v[80:81], v[40:41], v[4:5] op_sel_hi:[1,0,1]
	v_pk_fma_f32 v[6:7], v[82:83], v[40:41], v[6:7] op_sel_hi:[1,0,1]
	v_pk_fma_f32 v[0:1], v[84:85], v[32:33], v[0:1] op_sel:[0,1,0]
	v_pk_fma_f32 v[2:3], v[86:87], v[32:33], v[2:3] op_sel:[0,1,0]
	v_pk_fma_f32 v[8:9], v[84:85], v[36:37], v[8:9] op_sel:[0,1,0]
	v_pk_fma_f32 v[10:11], v[86:87], v[36:37], v[10:11] op_sel:[0,1,0]
	v_pk_fma_f32 v[4:5], v[84:85], v[40:41], v[4:5] op_sel:[0,1,0]
	v_pk_fma_f32 v[6:7], v[86:87], v[40:41], v[6:7] op_sel:[0,1,0]
	v_pk_fma_f32 v[0:1], v[88:89], v[34:35], v[0:1] op_sel_hi:[1,0,1]
	v_pk_fma_f32 v[2:3], v[90:91], v[34:35], v[2:3] op_sel_hi:[1,0,1]
	v_pk_fma_f32 v[8:9], v[88:89], v[38:39], v[8:9] op_sel_hi:[1,0,1]
	v_pk_fma_f32 v[10:11], v[90:91], v[38:39], v[10:11] op_sel_hi:[1,0,1]
	v_pk_fma_f32 v[4:5], v[88:89], v[42:43], v[4:5] op_sel_hi:[1,0,1]
	v_pk_fma_f32 v[6:7], v[90:91], v[42:43], v[6:7] op_sel_hi:[1,0,1]
	v_pk_fma_f32 v[0:1], v[92:93], v[44:45], v[0:1] op_sel_hi:[1,0,1]
	v_pk_fma_f32 v[2:3], v[94:95], v[44:45], v[2:3] op_sel_hi:[1,0,1]
	v_pk_fma_f32 v[8:9], v[92:93], v[46:47], v[8:9] op_sel_hi:[1,0,1]
	v_pk_fma_f32 v[10:11], v[94:95], v[46:47], v[10:11] op_sel_hi:[1,0,1]
	v_pk_fma_f32 v[4:5], v[92:93], v[48:49], v[4:5] op_sel_hi:[1,0,1]
	v_pk_fma_f32 v[6:7], v[94:95], v[48:49], v[6:7] op_sel_hi:[1,0,1]
	v_lshl_add_u64 v[50:51], v[12:13], 0, s[98:99]
	v_lshl_add_u64 v[52:53], v[50:51], 0, v[58:59]
	v_lshl_add_u64 v[54:55], v[50:51], 0, v[60:61]
	v_lshl_add_u64 v[56:57], v[50:51], 0, v[62:63]
	global_load_dwordx4 v[80:83], v[50:51], off
	global_load_dwordx4 v[84:87], v[52:53], off
	global_load_dwordx4 v[88:91], v[54:55], off
	global_load_dwordx4 v[92:95], v[56:57], off
	s_add_u32 s98, s98, 0x18000
	s_addc_u32 s99, s99, 0
	ds_read_b128 v[32:35], v15
	ds_read_b128 v[36:39], v15 offset:4096
	ds_read_b128 v[40:43], v15 offset:8192
	v_add_u32_e32 v15, 16, v15
	s_waitcnt lgkmcnt(2)
	v_mov_b32_e32 v44, v35
	s_waitcnt lgkmcnt(1)
	v_mov_b32_e32 v46, v39
	s_waitcnt lgkmcnt(0)
	v_mov_b32_e32 v48, v43
	s_waitcnt vmcnt(12)
	v_pk_fma_f32 v[0:1], v[96:97], v[32:33], v[0:1] op_sel_hi:[1,0,1]
	v_pk_fma_f32 v[2:3], v[98:99], v[32:33], v[2:3] op_sel_hi:[1,0,1]
	v_pk_fma_f32 v[8:9], v[96:97], v[36:37], v[8:9] op_sel_hi:[1,0,1]
	v_pk_fma_f32 v[10:11], v[98:99], v[36:37], v[10:11] op_sel_hi:[1,0,1]
	v_pk_fma_f32 v[4:5], v[96:97], v[40:41], v[4:5] op_sel_hi:[1,0,1]
	v_pk_fma_f32 v[6:7], v[98:99], v[40:41], v[6:7] op_sel_hi:[1,0,1]
	v_pk_fma_f32 v[0:1], v[100:101], v[32:33], v[0:1] op_sel:[0,1,0]
	v_pk_fma_f32 v[2:3], v[102:103], v[32:33], v[2:3] op_sel:[0,1,0]
	v_pk_fma_f32 v[8:9], v[100:101], v[36:37], v[8:9] op_sel:[0,1,0]
	v_pk_fma_f32 v[10:11], v[102:103], v[36:37], v[10:11] op_sel:[0,1,0]
	v_pk_fma_f32 v[4:5], v[100:101], v[40:41], v[4:5] op_sel:[0,1,0]
	v_pk_fma_f32 v[6:7], v[102:103], v[40:41], v[6:7] op_sel:[0,1,0]
	v_pk_fma_f32 v[0:1], v[104:105], v[34:35], v[0:1] op_sel_hi:[1,0,1]
	v_pk_fma_f32 v[2:3], v[106:107], v[34:35], v[2:3] op_sel_hi:[1,0,1]
	v_pk_fma_f32 v[8:9], v[104:105], v[38:39], v[8:9] op_sel_hi:[1,0,1]
	v_pk_fma_f32 v[10:11], v[106:107], v[38:39], v[10:11] op_sel_hi:[1,0,1]
	v_pk_fma_f32 v[4:5], v[104:105], v[42:43], v[4:5] op_sel_hi:[1,0,1]
	v_pk_fma_f32 v[6:7], v[106:107], v[42:43], v[6:7] op_sel_hi:[1,0,1]
	v_pk_fma_f32 v[0:1], v[108:109], v[44:45], v[0:1] op_sel_hi:[1,0,1]
	v_pk_fma_f32 v[2:3], v[110:111], v[44:45], v[2:3] op_sel_hi:[1,0,1]
	v_pk_fma_f32 v[8:9], v[108:109], v[46:47], v[8:9] op_sel_hi:[1,0,1]
	v_pk_fma_f32 v[10:11], v[110:111], v[46:47], v[10:11] op_sel_hi:[1,0,1]
	v_pk_fma_f32 v[4:5], v[108:109], v[48:49], v[4:5] op_sel_hi:[1,0,1]
	v_pk_fma_f32 v[6:7], v[110:111], v[48:49], v[6:7] op_sel_hi:[1,0,1]
	v_lshl_add_u64 v[50:51], v[12:13], 0, s[98:99]
	v_lshl_add_u64 v[52:53], v[50:51], 0, v[58:59]
	v_lshl_add_u64 v[54:55], v[50:51], 0, v[60:61]
	v_lshl_add_u64 v[56:57], v[50:51], 0, v[62:63]
	global_load_dwordx4 v[96:99], v[50:51], off
	global_load_dwordx4 v[100:103], v[52:53], off
	global_load_dwordx4 v[104:107], v[54:55], off
	global_load_dwordx4 v[108:111], v[56:57], off
	s_add_u32 s98, s98, 0x18000
	s_addc_u32 s99, s99, 0
	ds_read_b128 v[32:35], v15
	ds_read_b128 v[36:39], v15 offset:4096
	ds_read_b128 v[40:43], v15 offset:8192
	v_add_u32_e32 v15, 16, v15
	s_waitcnt lgkmcnt(2)
	v_mov_b32_e32 v44, v35
	s_waitcnt lgkmcnt(1)
	v_mov_b32_e32 v46, v39
	s_waitcnt lgkmcnt(0)
	v_mov_b32_e32 v48, v43
	s_waitcnt vmcnt(12)
	v_pk_fma_f32 v[0:1], v[112:113], v[32:33], v[0:1] op_sel_hi:[1,0,1]
	v_pk_fma_f32 v[2:3], v[114:115], v[32:33], v[2:3] op_sel_hi:[1,0,1]
	v_pk_fma_f32 v[8:9], v[112:113], v[36:37], v[8:9] op_sel_hi:[1,0,1]
	v_pk_fma_f32 v[10:11], v[114:115], v[36:37], v[10:11] op_sel_hi:[1,0,1]
	v_pk_fma_f32 v[4:5], v[112:113], v[40:41], v[4:5] op_sel_hi:[1,0,1]
	v_pk_fma_f32 v[6:7], v[114:115], v[40:41], v[6:7] op_sel_hi:[1,0,1]
	v_pk_fma_f32 v[0:1], v[116:117], v[32:33], v[0:1] op_sel:[0,1,0]
	v_pk_fma_f32 v[2:3], v[118:119], v[32:33], v[2:3] op_sel:[0,1,0]
	v_pk_fma_f32 v[8:9], v[116:117], v[36:37], v[8:9] op_sel:[0,1,0]
	v_pk_fma_f32 v[10:11], v[118:119], v[36:37], v[10:11] op_sel:[0,1,0]
	v_pk_fma_f32 v[4:5], v[116:117], v[40:41], v[4:5] op_sel:[0,1,0]
	v_pk_fma_f32 v[6:7], v[118:119], v[40:41], v[6:7] op_sel:[0,1,0]
	v_pk_fma_f32 v[0:1], v[120:121], v[34:35], v[0:1] op_sel_hi:[1,0,1]
	v_pk_fma_f32 v[2:3], v[122:123], v[34:35], v[2:3] op_sel_hi:[1,0,1]
	v_pk_fma_f32 v[8:9], v[120:121], v[38:39], v[8:9] op_sel_hi:[1,0,1]
	v_pk_fma_f32 v[10:11], v[122:123], v[38:39], v[10:11] op_sel_hi:[1,0,1]
	v_pk_fma_f32 v[4:5], v[120:121], v[42:43], v[4:5] op_sel_hi:[1,0,1]
	v_pk_fma_f32 v[6:7], v[122:123], v[42:43], v[6:7] op_sel_hi:[1,0,1]
	v_pk_fma_f32 v[0:1], v[124:125], v[44:45], v[0:1] op_sel_hi:[1,0,1]
	v_pk_fma_f32 v[2:3], v[126:127], v[44:45], v[2:3] op_sel_hi:[1,0,1]
	v_pk_fma_f32 v[8:9], v[124:125], v[46:47], v[8:9] op_sel_hi:[1,0,1]
	v_pk_fma_f32 v[10:11], v[126:127], v[46:47], v[10:11] op_sel_hi:[1,0,1]
	v_pk_fma_f32 v[4:5], v[124:125], v[48:49], v[4:5] op_sel_hi:[1,0,1]
	v_pk_fma_f32 v[6:7], v[126:127], v[48:49], v[6:7] op_sel_hi:[1,0,1]
	v_lshl_add_u64 v[50:51], v[12:13], 0, s[98:99]
	v_lshl_add_u64 v[52:53], v[50:51], 0, v[58:59]
	v_lshl_add_u64 v[54:55], v[50:51], 0, v[60:61]
	v_lshl_add_u64 v[56:57], v[50:51], 0, v[62:63]
	global_load_dwordx4 v[112:115], v[50:51], off
	global_load_dwordx4 v[116:119], v[52:53], off
	global_load_dwordx4 v[120:123], v[54:55], off
	global_load_dwordx4 v[124:127], v[56:57], off
	s_add_u32 s98, s98, 0x18000
	s_addc_u32 s99, s99, 0
	s_sub_u32 s100, s100, 1
	s_cmp_lg_u32 s100, 0
	s_cbranch_scc1 .Lmod_loop
	ds_read_b128 v[32:35], v15
	ds_read_b128 v[36:39], v15 offset:4096
	ds_read_b128 v[40:43], v15 offset:8192
	v_add_u32_e32 v15, 16, v15
	s_waitcnt lgkmcnt(2)
	v_mov_b32_e32 v44, v35
	s_waitcnt lgkmcnt(1)
	v_mov_b32_e32 v46, v39
	s_waitcnt lgkmcnt(0)
	v_mov_b32_e32 v48, v43
	s_waitcnt vmcnt(12)
	v_pk_fma_f32 v[0:1], v[64:65], v[32:33], v[0:1] op_sel_hi:[1,0,1]
	v_pk_fma_f32 v[2:3], v[66:67], v[32:33], v[2:3] op_sel_hi:[1,0,1]
	v_pk_fma_f32 v[8:9], v[64:65], v[36:37], v[8:9] op_sel_hi:[1,0,1]
	v_pk_fma_f32 v[10:11], v[66:67], v[36:37], v[10:11] op_sel_hi:[1,0,1]
	v_pk_fma_f32 v[4:5], v[64:65], v[40:41], v[4:5] op_sel_hi:[1,0,1]
	v_pk_fma_f32 v[6:7], v[66:67], v[40:41], v[6:7] op_sel_hi:[1,0,1]
	v_pk_fma_f32 v[0:1], v[68:69], v[32:33], v[0:1] op_sel:[0,1,0]
	v_pk_fma_f32 v[2:3], v[70:71], v[32:33], v[2:3] op_sel:[0,1,0]
	v_pk_fma_f32 v[8:9], v[68:69], v[36:37], v[8:9] op_sel:[0,1,0]
	v_pk_fma_f32 v[10:11], v[70:71], v[36:37], v[10:11] op_sel:[0,1,0]
	v_pk_fma_f32 v[4:5], v[68:69], v[40:41], v[4:5] op_sel:[0,1,0]
	v_pk_fma_f32 v[6:7], v[70:71], v[40:41], v[6:7] op_sel:[0,1,0]
	v_pk_fma_f32 v[0:1], v[72:73], v[34:35], v[0:1] op_sel_hi:[1,0,1]
	v_pk_fma_f32 v[2:3], v[74:75], v[34:35], v[2:3] op_sel_hi:[1,0,1]
	v_pk_fma_f32 v[8:9], v[72:73], v[38:39], v[8:9] op_sel_hi:[1,0,1]
	v_pk_fma_f32 v[10:11], v[74:75], v[38:39], v[10:11] op_sel_hi:[1,0,1]
	v_pk_fma_f32 v[4:5], v[72:73], v[42:43], v[4:5] op_sel_hi:[1,0,1]
	v_pk_fma_f32 v[6:7], v[74:75], v[42:43], v[6:7] op_sel_hi:[1,0,1]
	v_pk_fma_f32 v[0:1], v[76:77], v[44:45], v[0:1] op_sel_hi:[1,0,1]
	v_pk_fma_f32 v[2:3], v[78:79], v[44:45], v[2:3] op_sel_hi:[1,0,1]
	v_pk_fma_f32 v[8:9], v[76:77], v[46:47], v[8:9] op_sel_hi:[1,0,1]
	v_pk_fma_f32 v[10:11], v[78:79], v[46:47], v[10:11] op_sel_hi:[1,0,1]
	v_pk_fma_f32 v[4:5], v[76:77], v[48:49], v[4:5] op_sel_hi:[1,0,1]
	v_pk_fma_f32 v[6:7], v[78:79], v[48:49], v[6:7] op_sel_hi:[1,0,1]
	ds_read_b128 v[32:35], v15
	ds_read_b128 v[36:39], v15 offset:4096
	ds_read_b128 v[40:43], v15 offset:8192
	v_add_u32_e32 v15, 16, v15
	s_waitcnt lgkmcnt(2)
	v_mov_b32_e32 v44, v35
	s_waitcnt lgkmcnt(1)
	v_mov_b32_e32 v46, v39
	s_waitcnt lgkmcnt(0)
	v_mov_b32_e32 v48, v43
	s_waitcnt vmcnt(8)
	v_pk_fma_f32 v[0:1], v[80:81], v[32:33], v[0:1] op_sel_hi:[1,0,1]
	v_pk_fma_f32 v[2:3], v[82:83], v[32:33], v[2:3] op_sel_hi:[1,0,1]
	v_pk_fma_f32 v[8:9], v[80:81], v[36:37], v[8:9] op_sel_hi:[1,0,1]
	v_pk_fma_f32 v[10:11], v[82:83], v[36:37], v[10:11] op_sel_hi:[1,0,1]
	v_pk_fma_f32 v[4:5], v[80:81], v[40:41], v[4:5] op_sel_hi:[1,0,1]
	v_pk_fma_f32 v[6:7], v[82:83], v[40:41], v[6:7] op_sel_hi:[1,0,1]
	v_pk_fma_f32 v[0:1], v[84:85], v[32:33], v[0:1] op_sel:[0,1,0]
	v_pk_fma_f32 v[2:3], v[86:87], v[32:33], v[2:3] op_sel:[0,1,0]
	v_pk_fma_f32 v[8:9], v[84:85], v[36:37], v[8:9] op_sel:[0,1,0]
	v_pk_fma_f32 v[10:11], v[86:87], v[36:37], v[10:11] op_sel:[0,1,0]
	v_pk_fma_f32 v[4:5], v[84:85], v[40:41], v[4:5] op_sel:[0,1,0]
	v_pk_fma_f32 v[6:7], v[86:87], v[40:41], v[6:7] op_sel:[0,1,0]
	v_pk_fma_f32 v[0:1], v[88:89], v[34:35], v[0:1] op_sel_hi:[1,0,1]
	v_pk_fma_f32 v[2:3], v[90:91], v[34:35], v[2:3] op_sel_hi:[1,0,1]
	v_pk_fma_f32 v[8:9], v[88:89], v[38:39], v[8:9] op_sel_hi:[1,0,1]
	v_pk_fma_f32 v[10:11], v[90:91], v[38:39], v[10:11] op_sel_hi:[1,0,1]
	v_pk_fma_f32 v[4:5], v[88:89], v[42:43], v[4:5] op_sel_hi:[1,0,1]
	v_pk_fma_f32 v[6:7], v[90:91], v[42:43], v[6:7] op_sel_hi:[1,0,1]
	v_pk_fma_f32 v[0:1], v[92:93], v[44:45], v[0:1] op_sel_hi:[1,0,1]
	v_pk_fma_f32 v[2:3], v[94:95], v[44:45], v[2:3] op_sel_hi:[1,0,1]
	v_pk_fma_f32 v[8:9], v[92:93], v[46:47], v[8:9] op_sel_hi:[1,0,1]
	v_pk_fma_f32 v[10:11], v[94:95], v[46:47], v[10:11] op_sel_hi:[1,0,1]
	v_pk_fma_f32 v[4:5], v[92:93], v[48:49], v[4:5] op_sel_hi:[1,0,1]
	v_pk_fma_f32 v[6:7], v[94:95], v[48:49], v[6:7] op_sel_hi:[1,0,1]
	ds_read_b128 v[32:35], v15
	ds_read_b128 v[36:39], v15 offset:4096
	ds_read_b128 v[40:43], v15 offset:8192
	v_add_u32_e32 v15, 16, v15
	s_waitcnt lgkmcnt(2)
	v_mov_b32_e32 v44, v35
	s_waitcnt lgkmcnt(1)
	v_mov_b32_e32 v46, v39
	s_waitcnt lgkmcnt(0)
	v_mov_b32_e32 v48, v43
	s_waitcnt vmcnt(4)
	v_pk_fma_f32 v[0:1], v[96:97], v[32:33], v[0:1] op_sel_hi:[1,0,1]
	v_pk_fma_f32 v[2:3], v[98:99], v[32:33], v[2:3] op_sel_hi:[1,0,1]
	v_pk_fma_f32 v[8:9], v[96:97], v[36:37], v[8:9] op_sel_hi:[1,0,1]
	v_pk_fma_f32 v[10:11], v[98:99], v[36:37], v[10:11] op_sel_hi:[1,0,1]
	v_pk_fma_f32 v[4:5], v[96:97], v[40:41], v[4:5] op_sel_hi:[1,0,1]
	v_pk_fma_f32 v[6:7], v[98:99], v[40:41], v[6:7] op_sel_hi:[1,0,1]
	v_pk_fma_f32 v[0:1], v[100:101], v[32:33], v[0:1] op_sel:[0,1,0]
	v_pk_fma_f32 v[2:3], v[102:103], v[32:33], v[2:3] op_sel:[0,1,0]
	v_pk_fma_f32 v[8:9], v[100:101], v[36:37], v[8:9] op_sel:[0,1,0]
	v_pk_fma_f32 v[10:11], v[102:103], v[36:37], v[10:11] op_sel:[0,1,0]
	v_pk_fma_f32 v[4:5], v[100:101], v[40:41], v[4:5] op_sel:[0,1,0]
	v_pk_fma_f32 v[6:7], v[102:103], v[40:41], v[6:7] op_sel:[0,1,0]
	v_pk_fma_f32 v[0:1], v[104:105], v[34:35], v[0:1] op_sel_hi:[1,0,1]
	v_pk_fma_f32 v[2:3], v[106:107], v[34:35], v[2:3] op_sel_hi:[1,0,1]
	v_pk_fma_f32 v[8:9], v[104:105], v[38:39], v[8:9] op_sel_hi:[1,0,1]
	v_pk_fma_f32 v[10:11], v[106:107], v[38:39], v[10:11] op_sel_hi:[1,0,1]
	v_pk_fma_f32 v[4:5], v[104:105], v[42:43], v[4:5] op_sel_hi:[1,0,1]
	v_pk_fma_f32 v[6:7], v[106:107], v[42:43], v[6:7] op_sel_hi:[1,0,1]
	v_pk_fma_f32 v[0:1], v[108:109], v[44:45], v[0:1] op_sel_hi:[1,0,1]
	v_pk_fma_f32 v[2:3], v[110:111], v[44:45], v[2:3] op_sel_hi:[1,0,1]
	v_pk_fma_f32 v[8:9], v[108:109], v[46:47], v[8:9] op_sel_hi:[1,0,1]
	v_pk_fma_f32 v[10:11], v[110:111], v[46:47], v[10:11] op_sel_hi:[1,0,1]
	v_pk_fma_f32 v[4:5], v[108:109], v[48:49], v[4:5] op_sel_hi:[1,0,1]
	v_pk_fma_f32 v[6:7], v[110:111], v[48:49], v[6:7] op_sel_hi:[1,0,1]
	ds_read_b128 v[32:35], v15
	ds_read_b128 v[36:39], v15 offset:4096
	ds_read_b128 v[40:43], v15 offset:8192
	v_add_u32_e32 v15, 16, v15
	s_waitcnt lgkmcnt(2)
	v_mov_b32_e32 v44, v35
	s_waitcnt lgkmcnt(1)
	v_mov_b32_e32 v46, v39
	s_waitcnt lgkmcnt(0)
	v_mov_b32_e32 v48, v43
	s_waitcnt vmcnt(0)
	v_pk_fma_f32 v[0:1], v[112:113], v[32:33], v[0:1] op_sel_hi:[1,0,1]
	v_pk_fma_f32 v[2:3], v[114:115], v[32:33], v[2:3] op_sel_hi:[1,0,1]
	v_pk_fma_f32 v[8:9], v[112:113], v[36:37], v[8:9] op_sel_hi:[1,0,1]
	v_pk_fma_f32 v[10:11], v[114:115], v[36:37], v[10:11] op_sel_hi:[1,0,1]
	v_pk_fma_f32 v[4:5], v[112:113], v[40:41], v[4:5] op_sel_hi:[1,0,1]
	v_pk_fma_f32 v[6:7], v[114:115], v[40:41], v[6:7] op_sel_hi:[1,0,1]
	v_pk_fma_f32 v[0:1], v[116:117], v[32:33], v[0:1] op_sel:[0,1,0]
	v_pk_fma_f32 v[2:3], v[118:119], v[32:33], v[2:3] op_sel:[0,1,0]
	v_pk_fma_f32 v[8:9], v[116:117], v[36:37], v[8:9] op_sel:[0,1,0]
	v_pk_fma_f32 v[10:11], v[118:119], v[36:37], v[10:11] op_sel:[0,1,0]
	v_pk_fma_f32 v[4:5], v[116:117], v[40:41], v[4:5] op_sel:[0,1,0]
	v_pk_fma_f32 v[6:7], v[118:119], v[40:41], v[6:7] op_sel:[0,1,0]
	v_pk_fma_f32 v[0:1], v[120:121], v[34:35], v[0:1] op_sel_hi:[1,0,1]
	v_pk_fma_f32 v[2:3], v[122:123], v[34:35], v[2:3] op_sel_hi:[1,0,1]
	v_pk_fma_f32 v[8:9], v[120:121], v[38:39], v[8:9] op_sel_hi:[1,0,1]
	v_pk_fma_f32 v[10:11], v[122:123], v[38:39], v[10:11] op_sel_hi:[1,0,1]
	v_pk_fma_f32 v[4:5], v[120:121], v[42:43], v[4:5] op_sel_hi:[1,0,1]
	v_pk_fma_f32 v[6:7], v[122:123], v[42:43], v[6:7] op_sel_hi:[1,0,1]
	v_pk_fma_f32 v[0:1], v[124:125], v[44:45], v[0:1] op_sel_hi:[1,0,1]
	v_pk_fma_f32 v[2:3], v[126:127], v[44:45], v[2:3] op_sel_hi:[1,0,1]
	v_pk_fma_f32 v[8:9], v[124:125], v[46:47], v[8:9] op_sel_hi:[1,0,1]
	v_pk_fma_f32 v[10:11], v[126:127], v[46:47], v[10:11] op_sel_hi:[1,0,1]
	v_pk_fma_f32 v[4:5], v[124:125], v[48:49], v[4:5] op_sel_hi:[1,0,1]
	v_pk_fma_f32 v[6:7], v[126:127], v[48:49], v[6:7] op_sel_hi:[1,0,1]
	v_and_b32_e32 v12, 0x7c, v149
	v_mul_u32_u24_e32 v13, 0x600, v14
	s_movk_i32 s3, 0x180
	v_lshl_or_b32 v12, v12, 2, v13
	v_cmp_gt_u32_e32 vcc, s3, v128
	ds_write_b128 v12, v[0:3] offset:12288
	ds_write_b128 v12, v[8:11] offset:12800
	ds_write_b128 v12, v[4:7] offset:13312
	s_waitcnt lgkmcnt(0)
	s_barrier
	s_and_saveexec_b64 s[4:5], vcc
	s_cbranch_execz .LBB0_25
	s_mul_i32 s7, s6, 0x1800
	s_add_i32 s7, s7, s2
	v_or_b32_e32 v2, s7, v168
	s_mulk_i32 s6, 0x3000
	s_lshl_b32 s7, s33, 7
	v_mov_b32_e32 v0, s22
	v_mov_b32_e32 v1, s23
	v_ashrrev_i32_e32 v3, 31, v2
	s_add_i32 s6, s7, s6
	s_movk_i32 s3, 0x1800
	v_lshl_add_u64 v[0:1], v[2:3], 2, v[0:1]
	v_lshrrev_b32_e32 v3, 7, v128
	v_mov_b32_e32 v2, s6
	s_movk_i32 s2, 0x3000
	v_mad_u32_u24 v2, v3, s3, v2
	v_lshlrev_b32_e32 v3, 9, v3
	v_lshlrev_b32_e32 v5, 2, v168
	v_add_u32_e32 v4, 0xffffff00, v128
	v_or_b32_e32 v2, v2, v168
	v_or3_b32 v5, v3, v5, s2
	s_mov_b64 s[2:3], 0
	s_movk_i32 s6, 0x7f

.LBB0_198:
	s_or_b64 exec, exec, s[0:1]
	s_add_u32 s0, s90, 0xb171900
	s_addc_u32 s1, s91, 0
	v_writelane_b32 v250, s0, 19
	v_lshrrev_b32_e32 v174, 6, v128
	v_lshl_add_u32 v148, s33, 2, v174
	v_writelane_b32 v250, s1, 20
	s_movk_i32 s0, 0x3000
	v_mbcnt_lo_u32_b32 v182, -1, 0
	s_waitcnt lgkmcnt(0)
	s_barrier
	v_cmp_gt_i32_e64 s[0:1], s0, v148
	s_mov_b64 s[2:3], exec
	s_nop 0
	v_writelane_b32 v250, s0, 21
	s_nop 1
	v_writelane_b32 v250, s1, 22
	s_and_b64 s[0:1], s[2:3], s[0:1]
	s_mov_b64 exec, s[0:1]
	s_cbranch_execz .LBB0_205
	s_waitcnt vmcnt(5)
	v_mbcnt_hi_u32_b32 v0, -1, v182
	v_and_b32_e32 v2, 64, v0
	v_add_u32_e32 v2, 64, v2
	v_xor_b32_e32 v3, 32, v0
	v_cmp_lt_i32_e32 vcc, v3, v2
	s_waitcnt vmcnt(4)
	v_and_b32_e32 v6, 0xfc, v149
	v_readlane_b32 s12, v250, 3
	v_cndmask_b32_e32 v3, v0, v3, vcc
	v_lshlrev_b32_e32 v18, 2, v3
	v_xor_b32_e32 v3, 16, v0
	v_cmp_lt_i32_e32 vcc, v3, v2
	v_mov_b32_e32 v1, 0
	v_readlane_b32 s20, v250, 11
	v_cndmask_b32_e32 v3, v0, v3, vcc
	v_lshlrev_b32_e32 v19, 2, v3
	v_xor_b32_e32 v3, 8, v0
	v_cmp_lt_i32_e32 vcc, v3, v2
	v_readlane_b32 s21, v250, 12
	v_readlane_b32 s0, v250, 19
	v_cndmask_b32_e32 v3, v0, v3, vcc
	v_lshlrev_b32_e32 v20, 2, v3
	v_xor_b32_e32 v3, 4, v0
	v_cmp_lt_i32_e32 vcc, v3, v2
	v_readlane_b32 s13, v250, 4
	s_waitcnt vmcnt(3)
	v_or_b32_e32 v8, 0x100, v6
	v_cndmask_b32_e32 v3, v0, v3, vcc
	v_lshlrev_b32_e32 v21, 2, v3
	v_xor_b32_e32 v3, 2, v0
	v_cmp_lt_i32_e32 vcc, v3, v2
	v_or_b32_e32 v10, 0x200, v6
	s_waitcnt vmcnt(2)
	v_or_b32_e32 v12, 0x300, v6
	v_cndmask_b32_e32 v3, v0, v3, vcc
	v_lshlrev_b32_e32 v22, 2, v3
	v_xor_b32_e32 v3, 1, v0
	v_cmp_lt_i32_e32 vcc, v3, v2
	v_readlane_b32 s1, v250, 20
	s_lshl_b32 s8, s92, 2
	v_cndmask_b32_e32 v0, v0, v3, vcc
	v_lshlrev_b32_e32 v23, 2, v0
	v_lshlrev_b32_e32 v0, 2, v6
	v_lshl_add_u64 v[2:3], s[20:21], 0, v[0:1]
	v_lshlrev_b32_e32 v0, 1, v6
	v_lshl_add_u64 v[4:5], s[0:1], 0, v[0:1]
	s_mov_b64 s[4:5], 0
	s_movk_i32 s9, 0x2000
	s_movk_i32 s10, 0x1fff
	v_lshlrev_b32_e32 v6, 2, v6
	v_mov_b32_e32 v7, v1
	s_movk_i32 s11, 0x1800
	s_mov_b64 s[6:7], 0x1000
	v_lshlrev_b32_e32 v8, 2, v8
	v_mov_b32_e32 v9, v1
	v_lshlrev_b32_e32 v10, 2, v10
	v_mov_b32_e32 v11, v1
	v_lshlrev_b32_e32 v12, 2, v12
	v_mov_b32_e32 v13, v1
	v_mov_b32_e32 v24, 0x358637bd
	s_mov_b32 s12, 0x800000
	s_movk_i32 s13, 0x2fff
	v_mov_b32_e32 v14, v148
	v_readlane_b32 s14, v250, 5
	v_readlane_b32 s15, v250, 6
	v_readlane_b32 s16, v250, 7
	v_readlane_b32 s17, v250, 8
	v_readlane_b32 s18, v250, 9
	v_readlane_b32 s19, v250, 10
	v_readlane_b32 s22, v250, 13
	v_readlane_b32 s23, v250, 14
	v_readlane_b32 s24, v250, 15
	v_readlane_b32 s25, v250, 16
	v_readlane_b32 s26, v250, 17
	v_readlane_b32 s27, v250, 18
	v_mbcnt_lo_u32_b32 v80, -1, 0
	v_mbcnt_hi_u32_b32 v80, -1, v80
	v_lshlrev_b32_e32 v96, 4, v80
	v_lshlrev_b32_e32 v97, 3, v80
	v_xor_b32_e32 v98, 32, v80
	v_lshlrev_b32_e32 v98, 2, v98
	v_xor_b32_e32 v99, 16, v80
	v_lshlrev_b32_e32 v99, 2, v99
	v_xor_b32_e32 v100, 8, v80
	v_lshlrev_b32_e32 v100, 2, v100
	v_xor_b32_e32 v101, 4, v80
	v_lshlrev_b32_e32 v101, 2, v101
	v_xor_b32_e32 v102, 2, v80
	v_lshlrev_b32_e32 v102, 2, v102
	v_xor_b32_e32 v103, 1, v80
	v_lshlrev_b32_e32 v103, 2, v103
	v_mov_b32_e32 v104, 0x358637bd
	v_mov_b32_e32 v107, 0
	v_readlane_b32 s100, v250, 11
	v_readlane_b32 s101, v250, 12
	s_nop 5
	global_load_dwordx4 v[32:35], v96, s[100:101] offset:0
	global_load_dwordx4 v[36:39], v96, s[100:101] offset:1024
	global_load_dwordx4 v[40:43], v96, s[100:101] offset:2048
	global_load_dwordx4 v[44:47], v96, s[100:101] offset:3072
	v_readfirstlane_b32 s98, v148
	s_nop 3
	s_lshl_b32 s99, s98, 12
	s_sub_u32 vcc_lo, s99, 0x2000000
	s_cmp_lt_u32 s98, 0x2000
	s_cselect_b32 s99, s99, vcc_lo
	s_cselect_b32 s100, s72, s74
	s_cselect_b32 s101, s73, s75
	s_add_u32 s100, s100, s99
	s_addc_u32 s101, s101, 0
	global_load_dwordx4 v[0:3], v96, s[100:101] offset:0
	global_load_dwordx4 v[4:7], v96, s[100:101] offset:1024
	global_load_dwordx4 v[8:11], v96, s[100:101] offset:2048
	global_load_dwordx4 v[12:15], v96, s[100:101] offset:3072
	s_sub_u32 s99, s98, 0x2000
	s_lshr_b32 s99, s99, 11
	s_add_u32 s99, s99, 1
	s_cmp_lt_u32 s98, 0x2000
	s_cmov_b32 s99, 0
	s_mul_i32 s99, s99, 0x6000
	s_add_u32 s99, s99, 0x3441000
	s_add_u32 s100, s90, s99
	s_addc_u32 s101, s91, 0
	global_load_dwordx4 v[48:51], v96, s[100:101] offset:0
	global_load_dwordx4 v[52:55], v96, s[100:101] offset:1024
	global_load_dwordx4 v[56:59], v96, s[100:101] offset:2048
	global_load_dwordx4 v[60:63], v96, s[100:101] offset:3072
	s_sub_u32 s99, s98, 0x2000
	s_lshr_b32 s99, s99, 11
	s_add_u32 s99, s99, 1
	s_cmp_lt_u32 s98, 0x2000
	s_cmov_b32 s99, 0
	s_mul_i32 s99, s99, 0x6000
	s_add_u32 s99, s99, 0x3440000
	s_add_u32 s100, s90, s99
	s_addc_u32 s101, s91, 0
	global_load_dwordx4 v[64:67], v96, s[100:101] offset:0
	global_load_dwordx4 v[68:71], v96, s[100:101] offset:1024
	global_load_dwordx4 v[72:75], v96, s[100:101] offset:2048
	global_load_dwordx4 v[76:79], v96, s[100:101] offset:3072
	s_add_u32 s98, s98, 0x800
	s_lshl_b32 s99, s98, 12
	s_sub_u32 vcc_lo, s99, 0x2000000
	s_cmp_lt_u32 s98, 0x2000
	s_cselect_b32 s99, s99, vcc_lo
	s_cselect_b32 s100, s72, s74
	s_cselect_b32 s101, s73, s75
	s_add_u32 s100, s100, s99
	s_addc_u32 s101, s101, 0
	global_load_dwordx4 v[16:19], v96, s[100:101] offset:0
	global_load_dwordx4 v[20:23], v96, s[100:101] offset:1024
	global_load_dwordx4 v[24:27], v96, s[100:101] offset:2048
	global_load_dwordx4 v[28:31], v96, s[100:101] offset:3072
	s_sub_u32 s98, s98, 0x800
	s_waitcnt vmcnt(12)
	v_mul_f32_e32 v80, v1, v1
	v_mul_f32_e32 v81, v5, v5
	v_mul_f32_e32 v82, v9, v9
	v_mul_f32_e32 v83, v13, v13
	v_fmac_f32_e32 v80, v0, v0
	v_fmac_f32_e32 v81, v4, v4
	v_fmac_f32_e32 v82, v8, v8
	v_fmac_f32_e32 v83, v12, v12
	v_fmac_f32_e32 v80, v2, v2
	v_fmac_f32_e32 v81, v6, v6
	v_fmac_f32_e32 v82, v10, v10
	v_fmac_f32_e32 v83, v14, v14
	v_fmac_f32_e32 v80, v3, v3
	v_fmac_f32_e32 v81, v7, v7
	v_fmac_f32_e32 v82, v11, v11
	v_fmac_f32_e32 v83, v15, v15
	v_add_f32_e32 v84, v80, v81
	v_add_f32_e32 v84, v84, v82
	v_add_f32_e32 v84, v84, v83
	ds_bpermute_b32 v85, v98, v84
	s_waitcnt lgkmcnt(0)
	v_add_f32_e32 v84, v84, v85
	ds_bpermute_b32 v85, v99, v84
	s_waitcnt lgkmcnt(0)
	v_add_f32_e32 v84, v84, v85
	ds_bpermute_b32 v85, v100, v84
	s_waitcnt lgkmcnt(0)
	v_add_f32_e32 v84, v84, v85
	ds_bpermute_b32 v85, v101, v84
	s_waitcnt lgkmcnt(0)
	v_add_f32_e32 v84, v84, v85
	ds_bpermute_b32 v85, v102, v84
	s_waitcnt lgkmcnt(0)
	v_add_f32_e32 v84, v84, v85
	ds_bpermute_b32 v85, v103, v84
	s_waitcnt lgkmcnt(0)
	v_add_f32_e32 v84, v84, v85
	v_fmamk_f32 v84, v84, 0x3a800000, v104
	v_mul_f32_e32 v85, 0x4b800000, v84
	v_cmp_gt_f32_e32 vcc, 0x800000, v84
	s_nop 1
	v_cndmask_b32_e32 v84, v84, v85, vcc
	v_rsq_f32_e32 v84, v84
	s_nop 0
	v_mul_f32_e32 v85, 0x45800000, v84
	v_cndmask_b32_e32 v106, v84, v85, vcc
	s_waitcnt vmcnt(4)
	s_lshl_b32 s99, s98, 11
	s_add_u32 s99, s99, 0xb171900
	s_add_u32 s100, s90, s99
	s_addc_u32 s101, s91, 0
	v_pk_mul_f32 v[0:1], v[0:1], v[106:107] op_sel_hi:[1,0]
	v_pk_mul_f32 v[2:3], v[2:3], v[106:107] op_sel_hi:[1,0]
	v_pk_mul_f32 v[0:1], v[32:33], v[0:1]
	v_pk_mul_f32 v[2:3], v[34:35], v[2:3]
	v_pk_add_f32 v[48:49], v[48:49], 1.0 op_sel_hi:[1,0]
	v_pk_add_f32 v[50:51], v[50:51], 1.0 op_sel_hi:[1,0]
	v_pk_fma_f32 v[0:1], v[48:49], v[0:1], v[64:65]
	v_pk_fma_f32 v[2:3], v[50:51], v[2:3], v[66:67]
	v_cvt_pk_bf16_f32 v0, v0, v1
	v_cvt_pk_bf16_f32 v1, v2, v3
	global_store_dwordx2 v97, v[0:1], s[100:101] offset:0
	v_pk_mul_f32 v[4:5], v[4:5], v[106:107] op_sel_hi:[1,0]
	v_pk_mul_f32 v[6:7], v[6:7], v[106:107] op_sel_hi:[1,0]
	v_pk_mul_f32 v[4:5], v[36:37], v[4:5]
	v_pk_mul_f32 v[6:7], v[38:39], v[6:7]
	v_pk_add_f32 v[52:53], v[52:53], 1.0 op_sel_hi:[1,0]
	v_pk_add_f32 v[54:55], v[54:55], 1.0 op_sel_hi:[1,0]
	v_pk_fma_f32 v[4:5], v[52:53], v[4:5], v[68:69]
	v_pk_fma_f32 v[6:7], v[54:55], v[6:7], v[70:71]
	v_cvt_pk_bf16_f32 v4, v4, v5
	v_cvt_pk_bf16_f32 v5, v6, v7
	global_store_dwordx2 v97, v[4:5], s[100:101] offset:512
	v_pk_mul_f32 v[8:9], v[8:9], v[106:107] op_sel_hi:[1,0]
	v_pk_mul_f32 v[10:11], v[10:11], v[106:107] op_sel_hi:[1,0]
	v_pk_mul_f32 v[8:9], v[40:41], v[8:9]
	v_pk_mul_f32 v[10:11], v[42:43], v[10:11]
	v_pk_add_f32 v[56:57], v[56:57], 1.0 op_sel_hi:[1,0]
	v_pk_add_f32 v[58:59], v[58:59], 1.0 op_sel_hi:[1,0]
	v_pk_fma_f32 v[8:9], v[56:57], v[8:9], v[72:73]
	v_pk_fma_f32 v[10:11], v[58:59], v[10:11], v[74:75]
	v_cvt_pk_bf16_f32 v8, v8, v9
	v_cvt_pk_bf16_f32 v9, v10, v11
	global_store_dwordx2 v97, v[8:9], s[100:101] offset:1024
	v_pk_mul_f32 v[12:13], v[12:13], v[106:107] op_sel_hi:[1,0]
	v_pk_mul_f32 v[14:15], v[14:15], v[106:107] op_sel_hi:[1,0]
	v_pk_mul_f32 v[12:13], v[44:45], v[12:13]
	v_pk_mul_f32 v[14:15], v[46:47], v[14:15]
	v_pk_add_f32 v[60:61], v[60:61], 1.0 op_sel_hi:[1,0]
	v_pk_add_f32 v[62:63], v[62:63], 1.0 op_sel_hi:[1,0]
	v_pk_fma_f32 v[12:13], v[60:61], v[12:13], v[76:77]
	v_pk_fma_f32 v[14:15], v[62:63], v[14:15], v[78:79]
	v_cvt_pk_bf16_f32 v12, v12, v13
	v_cvt_pk_bf16_f32 v13, v14, v15
	global_store_dwordx2 v97, v[12:13], s[100:101] offset:1536
	s_add_u32 s98, s98, 0x800
	s_sub_u32 s99, s98, 0x2000
	s_lshr_b32 s99, s99, 11
	s_add_u32 s99, s99, 1
	s_cmp_lt_u32 s98, 0x2000
	s_cmov_b32 s99, 0
	s_mul_i32 s99, s99, 0x6000
	s_add_u32 s99, s99, 0x3441000
	s_add_u32 s100, s90, s99
	s_addc_u32 s101, s91, 0
	global_load_dwordx4 v[48:51], v96, s[100:101] offset:0
	global_load_dwordx4 v[52:55], v96, s[100:101] offset:1024
	global_load_dwordx4 v[56:59], v96, s[100:101] offset:2048
	global_load_dwordx4 v[60:63], v96, s[100:101] offset:3072
	s_sub_u32 s99, s98, 0x2000
	s_lshr_b32 s99, s99, 11
	s_add_u32 s99, s99, 1
	s_cmp_lt_u32 s98, 0x2000
	s_cmov_b32 s99, 0
	s_mul_i32 s99, s99, 0x6000
	s_add_u32 s99, s99, 0x3440000
	s_add_u32 s100, s90, s99
	s_addc_u32 s101, s91, 0
	global_load_dwordx4 v[64:67], v96, s[100:101] offset:0
	global_load_dwordx4 v[68:71], v96, s[100:101] offset:1024
	global_load_dwordx4 v[72:75], v96, s[100:101] offset:2048
	global_load_dwordx4 v[76:79], v96, s[100:101] offset:3072
	s_add_u32 s98, s98, 0x800
	s_lshl_b32 s99, s98, 12
	s_sub_u32 vcc_lo, s99, 0x2000000
	s_cmp_lt_u32 s98, 0x2000
	s_cselect_b32 s99, s99, vcc_lo
	s_cselect_b32 s100, s72, s74
	s_cselect_b32 s101, s73, s75
	s_add_u32 s100, s100, s99
	s_addc_u32 s101, s101, 0
	global_load_dwordx4 v[0:3], v96, s[100:101] offset:0
	global_load_dwordx4 v[4:7], v96, s[100:101] offset:1024
	global_load_dwordx4 v[8:11], v96, s[100:101] offset:2048
	global_load_dwordx4 v[12:15], v96, s[100:101] offset:3072
	s_sub_u32 s98, s98, 0x800
	s_waitcnt vmcnt(16)
	v_mul_f32_e32 v80, v17, v17
	v_mul_f32_e32 v81, v21, v21
	v_mul_f32_e32 v82, v25, v25
	v_mul_f32_e32 v83, v29, v29
	v_fmac_f32_e32 v80, v16, v16
	v_fmac_f32_e32 v81, v20, v20
	v_fmac_f32_e32 v82, v24, v24
	v_fmac_f32_e32 v83, v28, v28
	v_fmac_f32_e32 v80, v18, v18
	v_fmac_f32_e32 v81, v22, v22
	v_fmac_f32_e32 v82, v26, v26
	v_fmac_f32_e32 v83, v30, v30
	v_fmac_f32_e32 v80, v19, v19
	v_fmac_f32_e32 v81, v23, v23
	v_fmac_f32_e32 v82, v27, v27
	v_fmac_f32_e32 v83, v31, v31
	v_add_f32_e32 v84, v80, v81
	v_add_f32_e32 v84, v84, v82
	v_add_f32_e32 v84, v84, v83
	ds_bpermute_b32 v85, v98, v84
	s_waitcnt lgkmcnt(0)
	v_add_f32_e32 v84, v84, v85
	ds_bpermute_b32 v85, v99, v84
	s_waitcnt lgkmcnt(0)
	v_add_f32_e32 v84, v84, v85
	ds_bpermute_b32 v85, v100, v84
	s_waitcnt lgkmcnt(0)
	v_add_f32_e32 v84, v84, v85
	ds_bpermute_b32 v85, v101, v84
	s_waitcnt lgkmcnt(0)
	v_add_f32_e32 v84, v84, v85
	ds_bpermute_b32 v85, v102, v84
	s_waitcnt lgkmcnt(0)
	v_add_f32_e32 v84, v84, v85
	ds_bpermute_b32 v85, v103, v84
	s_waitcnt lgkmcnt(0)
	v_add_f32_e32 v84, v84, v85
	v_fmamk_f32 v84, v84, 0x3a800000, v104
	v_mul_f32_e32 v85, 0x4b800000, v84
	v_cmp_gt_f32_e32 vcc, 0x800000, v84
	s_nop 1
	v_cndmask_b32_e32 v84, v84, v85, vcc
	v_rsq_f32_e32 v84, v84
	s_nop 0
	v_mul_f32_e32 v85, 0x45800000, v84
	v_cndmask_b32_e32 v106, v84, v85, vcc
	s_waitcnt vmcnt(4)
	s_lshl_b32 s99, s98, 11
	s_add_u32 s99, s99, 0xb171900
	s_add_u32 s100, s90, s99
	s_addc_u32 s101, s91, 0
	v_pk_mul_f32 v[16:17], v[16:17], v[106:107] op_sel_hi:[1,0]
	v_pk_mul_f32 v[18:19], v[18:19], v[106:107] op_sel_hi:[1,0]
	v_pk_mul_f32 v[16:17], v[32:33], v[16:17]
	v_pk_mul_f32 v[18:19], v[34:35], v[18:19]
	v_pk_add_f32 v[48:49], v[48:49], 1.0 op_sel_hi:[1,0]
	v_pk_add_f32 v[50:51], v[50:51], 1.0 op_sel_hi:[1,0]
	v_pk_fma_f32 v[16:17], v[48:49], v[16:17], v[64:65]
	v_pk_fma_f32 v[18:19], v[50:51], v[18:19], v[66:67]
	v_cvt_pk_bf16_f32 v16, v16, v17
	v_cvt_pk_bf16_f32 v17, v18, v19
	global_store_dwordx2 v97, v[16:17], s[100:101] offset:0
	v_pk_mul_f32 v[20:21], v[20:21], v[106:107] op_sel_hi:[1,0]
	v_pk_mul_f32 v[22:23], v[22:23], v[106:107] op_sel_hi:[1,0]
	v_pk_mul_f32 v[20:21], v[36:37], v[20:21]
	v_pk_mul_f32 v[22:23], v[38:39], v[22:23]
	v_pk_add_f32 v[52:53], v[52:53], 1.0 op_sel_hi:[1,0]
	v_pk_add_f32 v[54:55], v[54:55], 1.0 op_sel_hi:[1,0]
	v_pk_fma_f32 v[20:21], v[52:53], v[20:21], v[68:69]
	v_pk_fma_f32 v[22:23], v[54:55], v[22:23], v[70:71]
	v_cvt_pk_bf16_f32 v20, v20, v21
	v_cvt_pk_bf16_f32 v21, v22, v23
	global_store_dwordx2 v97, v[20:21], s[100:101] offset:512
	v_pk_mul_f32 v[24:25], v[24:25], v[106:107] op_sel_hi:[1,0]
	v_pk_mul_f32 v[26:27], v[26:27], v[106:107] op_sel_hi:[1,0]
	v_pk_mul_f32 v[24:25], v[40:41], v[24:25]
	v_pk_mul_f32 v[26:27], v[42:43], v[26:27]
	v_pk_add_f32 v[56:57], v[56:57], 1.0 op_sel_hi:[1,0]
	v_pk_add_f32 v[58:59], v[58:59], 1.0 op_sel_hi:[1,0]
	v_pk_fma_f32 v[24:25], v[56:57], v[24:25], v[72:73]
	v_pk_fma_f32 v[26:27], v[58:59], v[26:27], v[74:75]
	v_cvt_pk_bf16_f32 v24, v24, v25
	v_cvt_pk_bf16_f32 v25, v26, v27
	global_store_dwordx2 v97, v[24:25], s[100:101] offset:1024
	v_pk_mul_f32 v[28:29], v[28:29], v[106:107] op_sel_hi:[1,0]
	v_pk_mul_f32 v[30:31], v[30:31], v[106:107] op_sel_hi:[1,0]
	v_pk_mul_f32 v[28:29], v[44:45], v[28:29]
	v_pk_mul_f32 v[30:31], v[46:47], v[30:31]
	v_pk_add_f32 v[60:61], v[60:61], 1.0 op_sel_hi:[1,0]
	v_pk_add_f32 v[62:63], v[62:63], 1.0 op_sel_hi:[1,0]
	v_pk_fma_f32 v[28:29], v[60:61], v[28:29], v[76:77]
	v_pk_fma_f32 v[30:31], v[62:63], v[30:31], v[78:79]
	v_cvt_pk_bf16_f32 v28, v28, v29
	v_cvt_pk_bf16_f32 v29, v30, v31
	global_store_dwordx2 v97, v[28:29], s[100:101] offset:1536
	s_add_u32 s98, s98, 0x800
	s_sub_u32 s99, s98, 0x2000
	s_lshr_b32 s99, s99, 11
	s_add_u32 s99, s99, 1
	s_cmp_lt_u32 s98, 0x2000
	s_cmov_b32 s99, 0
	s_mul_i32 s99, s99, 0x6000
	s_add_u32 s99, s99, 0x3441000
	s_add_u32 s100, s90, s99
	s_addc_u32 s101, s91, 0
	global_load_dwordx4 v[48:51], v96, s[100:101] offset:0
	global_load_dwordx4 v[52:55], v96, s[100:101] offset:1024
	global_load_dwordx4 v[56:59], v96, s[100:101] offset:2048
	global_load_dwordx4 v[60:63], v96, s[100:101] offset:3072
	s_sub_u32 s99, s98, 0x2000
	s_lshr_b32 s99, s99, 11
	s_add_u32 s99, s99, 1
	s_cmp_lt_u32 s98, 0x2000
	s_cmov_b32 s99, 0
	s_mul_i32 s99, s99, 0x6000
	s_add_u32 s99, s99, 0x3440000
	s_add_u32 s100, s90, s99
	s_addc_u32 s101, s91, 0
	global_load_dwordx4 v[64:67], v96, s[100:101] offset:0
	global_load_dwordx4 v[68:71], v96, s[100:101] offset:1024
	global_load_dwordx4 v[72:75], v96, s[100:101] offset:2048
	global_load_dwordx4 v[76:79], v96, s[100:101] offset:3072
	s_add_u32 s98, s98, 0x800
	s_lshl_b32 s99, s98, 12
	s_sub_u32 vcc_lo, s99, 0x2000000
	s_cmp_lt_u32 s98, 0x2000
	s_cselect_b32 s99, s99, vcc_lo
	s_cselect_b32 s100, s72, s74
	s_cselect_b32 s101, s73, s75
	s_add_u32 s100, s100, s99
	s_addc_u32 s101, s101, 0
	global_load_dwordx4 v[16:19], v96, s[100:101] offset:0
	global_load_dwordx4 v[20:23], v96, s[100:101] offset:1024
	global_load_dwordx4 v[24:27], v96, s[100:101] offset:2048
	global_load_dwordx4 v[28:31], v96, s[100:101] offset:3072
	s_sub_u32 s98, s98, 0x800
	s_waitcnt vmcnt(16)
	v_mul_f32_e32 v80, v1, v1
	v_mul_f32_e32 v81, v5, v5
	v_mul_f32_e32 v82, v9, v9
	v_mul_f32_e32 v83, v13, v13
	v_fmac_f32_e32 v80, v0, v0
	v_fmac_f32_e32 v81, v4, v4
	v_fmac_f32_e32 v82, v8, v8
	v_fmac_f32_e32 v83, v12, v12
	v_fmac_f32_e32 v80, v2, v2
	v_fmac_f32_e32 v81, v6, v6
	v_fmac_f32_e32 v82, v10, v10
	v_fmac_f32_e32 v83, v14, v14
	v_fmac_f32_e32 v80, v3, v3
	v_fmac_f32_e32 v81, v7, v7
	v_fmac_f32_e32 v82, v11, v11
	v_fmac_f32_e32 v83, v15, v15
	v_add_f32_e32 v84, v80, v81
	v_add_f32_e32 v84, v84, v82
	v_add_f32_e32 v84, v84, v83
	ds_bpermute_b32 v85, v98, v84
	s_waitcnt lgkmcnt(0)
	v_add_f32_e32 v84, v84, v85
	ds_bpermute_b32 v85, v99, v84
	s_waitcnt lgkmcnt(0)
	v_add_f32_e32 v84, v84, v85
	ds_bpermute_b32 v85, v100, v84
	s_waitcnt lgkmcnt(0)
	v_add_f32_e32 v84, v84, v85
	ds_bpermute_b32 v85, v101, v84
	s_waitcnt lgkmcnt(0)
	v_add_f32_e32 v84, v84, v85
	ds_bpermute_b32 v85, v102, v84
	s_waitcnt lgkmcnt(0)
	v_add_f32_e32 v84, v84, v85
	ds_bpermute_b32 v85, v103, v84
	s_waitcnt lgkmcnt(0)
	v_add_f32_e32 v84, v84, v85
	v_fmamk_f32 v84, v84, 0x3a800000, v104
	v_mul_f32_e32 v85, 0x4b800000, v84
	v_cmp_gt_f32_e32 vcc, 0x800000, v84
	s_nop 1
	v_cndmask_b32_e32 v84, v84, v85, vcc
	v_rsq_f32_e32 v84, v84
	s_nop 0
	v_mul_f32_e32 v85, 0x45800000, v84
	v_cndmask_b32_e32 v106, v84, v85, vcc
	s_waitcnt vmcnt(4)
	s_lshl_b32 s99, s98, 11
	s_add_u32 s99, s99, 0xb171900
	s_add_u32 s100, s90, s99
	s_addc_u32 s101, s91, 0
	v_pk_mul_f32 v[0:1], v[0:1], v[106:107] op_sel_hi:[1,0]
	v_pk_mul_f32 v[2:3], v[2:3], v[106:107] op_sel_hi:[1,0]
	v_pk_mul_f32 v[0:1], v[32:33], v[0:1]
	v_pk_mul_f32 v[2:3], v[34:35], v[2:3]
	v_pk_add_f32 v[48:49], v[48:49], 1.0 op_sel_hi:[1,0]
	v_pk_add_f32 v[50:51], v[50:51], 1.0 op_sel_hi:[1,0]
	v_pk_fma_f32 v[0:1], v[48:49], v[0:1], v[64:65]
	v_pk_fma_f32 v[2:3], v[50:51], v[2:3], v[66:67]
	v_cvt_pk_bf16_f32 v0, v0, v1
	v_cvt_pk_bf16_f32 v1, v2, v3
	global_store_dwordx2 v97, v[0:1], s[100:101] offset:0
	v_pk_mul_f32 v[4:5], v[4:5], v[106:107] op_sel_hi:[1,0]
	v_pk_mul_f32 v[6:7], v[6:7], v[106:107] op_sel_hi:[1,0]
	v_pk_mul_f32 v[4:5], v[36:37], v[4:5]
	v_pk_mul_f32 v[6:7], v[38:39], v[6:7]
	v_pk_add_f32 v[52:53], v[52:53], 1.0 op_sel_hi:[1,0]
	v_pk_add_f32 v[54:55], v[54:55], 1.0 op_sel_hi:[1,0]
	v_pk_fma_f32 v[4:5], v[52:53], v[4:5], v[68:69]
	v_pk_fma_f32 v[6:7], v[54:55], v[6:7], v[70:71]
	v_cvt_pk_bf16_f32 v4, v4, v5
	v_cvt_pk_bf16_f32 v5, v6, v7
	global_store_dwordx2 v97, v[4:5], s[100:101] offset:512
	v_pk_mul_f32 v[8:9], v[8:9], v[106:107] op_sel_hi:[1,0]
	v_pk_mul_f32 v[10:11], v[10:11], v[106:107] op_sel_hi:[1,0]
	v_pk_mul_f32 v[8:9], v[40:41], v[8:9]
	v_pk_mul_f32 v[10:11], v[42:43], v[10:11]
	v_pk_add_f32 v[56:57], v[56:57], 1.0 op_sel_hi:[1,0]
	v_pk_add_f32 v[58:59], v[58:59], 1.0 op_sel_hi:[1,0]
	v_pk_fma_f32 v[8:9], v[56:57], v[8:9], v[72:73]
	v_pk_fma_f32 v[10:11], v[58:59], v[10:11], v[74:75]
	v_cvt_pk_bf16_f32 v8, v8, v9
	v_cvt_pk_bf16_f32 v9, v10, v11
	global_store_dwordx2 v97, v[8:9], s[100:101] offset:1024
	v_pk_mul_f32 v[12:13], v[12:13], v[106:107] op_sel_hi:[1,0]
	v_pk_mul_f32 v[14:15], v[14:15], v[106:107] op_sel_hi:[1,0]
	v_pk_mul_f32 v[12:13], v[44:45], v[12:13]
	v_pk_mul_f32 v[14:15], v[46:47], v[14:15]
	v_pk_add_f32 v[60:61], v[60:61], 1.0 op_sel_hi:[1,0]
	v_pk_add_f32 v[62:63], v[62:63], 1.0 op_sel_hi:[1,0]
	v_pk_fma_f32 v[12:13], v[60:61], v[12:13], v[76:77]
	v_pk_fma_f32 v[14:15], v[62:63], v[14:15], v[78:79]
	v_cvt_pk_bf16_f32 v12, v12, v13
	v_cvt_pk_bf16_f32 v13, v14, v15
	global_store_dwordx2 v97, v[12:13], s[100:101] offset:1536
	s_add_u32 s98, s98, 0x800
	s_sub_u32 s99, s98, 0x2000
	s_lshr_b32 s99, s99, 11
	s_add_u32 s99, s99, 1
	s_cmp_lt_u32 s98, 0x2000
	s_cmov_b32 s99, 0
	s_mul_i32 s99, s99, 0x6000
	s_add_u32 s99, s99, 0x3441000
	s_add_u32 s100, s90, s99
	s_addc_u32 s101, s91, 0
	global_load_dwordx4 v[48:51], v96, s[100:101] offset:0
	global_load_dwordx4 v[52:55], v96, s[100:101] offset:1024
	global_load_dwordx4 v[56:59], v96, s[100:101] offset:2048
	global_load_dwordx4 v[60:63], v96, s[100:101] offset:3072
	s_sub_u32 s99, s98, 0x2000
	s_lshr_b32 s99, s99, 11
	s_add_u32 s99, s99, 1
	s_cmp_lt_u32 s98, 0x2000
	s_cmov_b32 s99, 0
	s_mul_i32 s99, s99, 0x6000
	s_add_u32 s99, s99, 0x3440000
	s_add_u32 s100, s90, s99
	s_addc_u32 s101, s91, 0
	global_load_dwordx4 v[64:67], v96, s[100:101] offset:0
	global_load_dwordx4 v[68:71], v96, s[100:101] offset:1024
	global_load_dwordx4 v[72:75], v96, s[100:101] offset:2048
	global_load_dwordx4 v[76:79], v96, s[100:101] offset:3072
	s_add_u32 s98, s98, 0x800
	s_lshl_b32 s99, s98, 12
	s_sub_u32 vcc_lo, s99, 0x2000000
	s_cmp_lt_u32 s98, 0x2000
	s_cselect_b32 s99, s99, vcc_lo
	s_cselect_b32 s100, s72, s74
	s_cselect_b32 s101, s73, s75
	s_add_u32 s100, s100, s99
	s_addc_u32 s101, s101, 0
	global_load_dwordx4 v[0:3], v96, s[100:101] offset:0
	global_load_dwordx4 v[4:7], v96, s[100:101] offset:1024
	global_load_dwordx4 v[8:11], v96, s[100:101] offset:2048
	global_load_dwordx4 v[12:15], v96, s[100:101] offset:3072
	s_sub_u32 s98, s98, 0x800
	s_waitcnt vmcnt(16)
	v_mul_f32_e32 v80, v17, v17
	v_mul_f32_e32 v81, v21, v21
	v_mul_f32_e32 v82, v25, v25
	v_mul_f32_e32 v83, v29, v29
	v_fmac_f32_e32 v80, v16, v16
	v_fmac_f32_e32 v81, v20, v20
	v_fmac_f32_e32 v82, v24, v24
	v_fmac_f32_e32 v83, v28, v28
	v_fmac_f32_e32 v80, v18, v18
	v_fmac_f32_e32 v81, v22, v22
	v_fmac_f32_e32 v82, v26, v26
	v_fmac_f32_e32 v83, v30, v30
	v_fmac_f32_e32 v80, v19, v19
	v_fmac_f32_e32 v81, v23, v23
	v_fmac_f32_e32 v82, v27, v27
	v_fmac_f32_e32 v83, v31, v31
	v_add_f32_e32 v84, v80, v81
	v_add_f32_e32 v84, v84, v82
	v_add_f32_e32 v84, v84, v83
	ds_bpermute_b32 v85, v98, v84
	s_waitcnt lgkmcnt(0)
	v_add_f32_e32 v84, v84, v85
	ds_bpermute_b32 v85, v99, v84
	s_waitcnt lgkmcnt(0)
	v_add_f32_e32 v84, v84, v85
	ds_bpermute_b32 v85, v100, v84
	s_waitcnt lgkmcnt(0)
	v_add_f32_e32 v84, v84, v85
	ds_bpermute_b32 v85, v101, v84
	s_waitcnt lgkmcnt(0)
	v_add_f32_e32 v84, v84, v85
	ds_bpermute_b32 v85, v102, v84
	s_waitcnt lgkmcnt(0)
	v_add_f32_e32 v84, v84, v85
	ds_bpermute_b32 v85, v103, v84
	s_waitcnt lgkmcnt(0)
	v_add_f32_e32 v84, v84, v85
	v_fmamk_f32 v84, v84, 0x3a800000, v104
	v_mul_f32_e32 v85, 0x4b800000, v84
	v_cmp_gt_f32_e32 vcc, 0x800000, v84
	s_nop 1
	v_cndmask_b32_e32 v84, v84, v85, vcc
	v_rsq_f32_e32 v84, v84
	s_nop 0
	v_mul_f32_e32 v85, 0x45800000, v84
	v_cndmask_b32_e32 v106, v84, v85, vcc
	s_waitcnt vmcnt(4)
	s_lshl_b32 s99, s98, 11
	s_add_u32 s99, s99, 0xb171900
	s_add_u32 s100, s90, s99
	s_addc_u32 s101, s91, 0
	v_pk_mul_f32 v[16:17], v[16:17], v[106:107] op_sel_hi:[1,0]
	v_pk_mul_f32 v[18:19], v[18:19], v[106:107] op_sel_hi:[1,0]
	v_pk_mul_f32 v[16:17], v[32:33], v[16:17]
	v_pk_mul_f32 v[18:19], v[34:35], v[18:19]
	v_pk_add_f32 v[48:49], v[48:49], 1.0 op_sel_hi:[1,0]
	v_pk_add_f32 v[50:51], v[50:51], 1.0 op_sel_hi:[1,0]
	v_pk_fma_f32 v[16:17], v[48:49], v[16:17], v[64:65]
	v_pk_fma_f32 v[18:19], v[50:51], v[18:19], v[66:67]
	v_cvt_pk_bf16_f32 v16, v16, v17
	v_cvt_pk_bf16_f32 v17, v18, v19
	global_store_dwordx2 v97, v[16:17], s[100:101] offset:0
	v_pk_mul_f32 v[20:21], v[20:21], v[106:107] op_sel_hi:[1,0]
	v_pk_mul_f32 v[22:23], v[22:23], v[106:107] op_sel_hi:[1,0]
	v_pk_mul_f32 v[20:21], v[36:37], v[20:21]
	v_pk_mul_f32 v[22:23], v[38:39], v[22:23]
	v_pk_add_f32 v[52:53], v[52:53], 1.0 op_sel_hi:[1,0]
	v_pk_add_f32 v[54:55], v[54:55], 1.0 op_sel_hi:[1,0]
	v_pk_fma_f32 v[20:21], v[52:53], v[20:21], v[68:69]
	v_pk_fma_f32 v[22:23], v[54:55], v[22:23], v[70:71]
	v_cvt_pk_bf16_f32 v20, v20, v21
	v_cvt_pk_bf16_f32 v21, v22, v23
	global_store_dwordx2 v97, v[20:21], s[100:101] offset:512
	v_pk_mul_f32 v[24:25], v[24:25], v[106:107] op_sel_hi:[1,0]
	v_pk_mul_f32 v[26:27], v[26:27], v[106:107] op_sel_hi:[1,0]
	v_pk_mul_f32 v[24:25], v[40:41], v[24:25]
	v_pk_mul_f32 v[26:27], v[42:43], v[26:27]
	v_pk_add_f32 v[56:57], v[56:57], 1.0 op_sel_hi:[1,0]
	v_pk_add_f32 v[58:59], v[58:59], 1.0 op_sel_hi:[1,0]
	v_pk_fma_f32 v[24:25], v[56:57], v[24:25], v[72:73]
	v_pk_fma_f32 v[26:27], v[58:59], v[26:27], v[74:75]
	v_cvt_pk_bf16_f32 v24, v24, v25
	v_cvt_pk_bf16_f32 v25, v26, v27
	global_store_dwordx2 v97, v[24:25], s[100:101] offset:1024
	v_pk_mul_f32 v[28:29], v[28:29], v[106:107] op_sel_hi:[1,0]
	v_pk_mul_f32 v[30:31], v[30:31], v[106:107] op_sel_hi:[1,0]
	v_pk_mul_f32 v[28:29], v[44:45], v[28:29]
	v_pk_mul_f32 v[30:31], v[46:47], v[30:31]
	v_pk_add_f32 v[60:61], v[60:61], 1.0 op_sel_hi:[1,0]
	v_pk_add_f32 v[62:63], v[62:63], 1.0 op_sel_hi:[1,0]
	v_pk_fma_f32 v[28:29], v[60:61], v[28:29], v[76:77]
	v_pk_fma_f32 v[30:31], v[62:63], v[30:31], v[78:79]
	v_cvt_pk_bf16_f32 v28, v28, v29
	v_cvt_pk_bf16_f32 v29, v30, v31
	global_store_dwordx2 v97, v[28:29], s[100:101] offset:1536
	s_add_u32 s98, s98, 0x800
	s_sub_u32 s99, s98, 0x2000
	s_lshr_b32 s99, s99, 11
	s_add_u32 s99, s99, 1
	s_cmp_lt_u32 s98, 0x2000
	s_cmov_b32 s99, 0
	s_mul_i32 s99, s99, 0x6000
	s_add_u32 s99, s99, 0x3441000
	s_add_u32 s100, s90, s99
	s_addc_u32 s101, s91, 0
	global_load_dwordx4 v[48:51], v96, s[100:101] offset:0
	global_load_dwordx4 v[52:55], v96, s[100:101] offset:1024
	global_load_dwordx4 v[56:59], v96, s[100:101] offset:2048
	global_load_dwordx4 v[60:63], v96, s[100:101] offset:3072
	s_sub_u32 s99, s98, 0x2000
	s_lshr_b32 s99, s99, 11
	s_add_u32 s99, s99, 1
	s_cmp_lt_u32 s98, 0x2000
	s_cmov_b32 s99, 0
	s_mul_i32 s99, s99, 0x6000
	s_add_u32 s99, s99, 0x3440000
	s_add_u32 s100, s90, s99
	s_addc_u32 s101, s91, 0
	global_load_dwordx4 v[64:67], v96, s[100:101] offset:0
	global_load_dwordx4 v[68:71], v96, s[100:101] offset:1024
	global_load_dwordx4 v[72:75], v96, s[100:101] offset:2048
	global_load_dwordx4 v[76:79], v96, s[100:101] offset:3072
	s_add_u32 s98, s98, 0x800
	s_lshl_b32 s99, s98, 12
	s_sub_u32 vcc_lo, s99, 0x2000000
	s_cmp_lt_u32 s98, 0x2000
	s_cselect_b32 s99, s99, vcc_lo
	s_cselect_b32 s100, s72, s74
	s_cselect_b32 s101, s73, s75
	s_add_u32 s100, s100, s99
	s_addc_u32 s101, s101, 0
	global_load_dwordx4 v[16:19], v96, s[100:101] offset:0
	global_load_dwordx4 v[20:23], v96, s[100:101] offset:1024
	global_load_dwordx4 v[24:27], v96, s[100:101] offset:2048
	global_load_dwordx4 v[28:31], v96, s[100:101] offset:3072
	s_sub_u32 s98, s98, 0x800
	s_waitcnt vmcnt(16)
	v_mul_f32_e32 v80, v1, v1
	v_mul_f32_e32 v81, v5, v5
	v_mul_f32_e32 v82, v9, v9
	v_mul_f32_e32 v83, v13, v13
	v_fmac_f32_e32 v80, v0, v0
	v_fmac_f32_e32 v81, v4, v4
	v_fmac_f32_e32 v82, v8, v8
	v_fmac_f32_e32 v83, v12, v12
	v_fmac_f32_e32 v80, v2, v2
	v_fmac_f32_e32 v81, v6, v6
	v_fmac_f32_e32 v82, v10, v10
	v_fmac_f32_e32 v83, v14, v14
	v_fmac_f32_e32 v80, v3, v3
	v_fmac_f32_e32 v81, v7, v7
	v_fmac_f32_e32 v82, v11, v11
	v_fmac_f32_e32 v83, v15, v15
	v_add_f32_e32 v84, v80, v81
	v_add_f32_e32 v84, v84, v82
	v_add_f32_e32 v84, v84, v83
	ds_bpermute_b32 v85, v98, v84
	s_waitcnt lgkmcnt(0)
	v_add_f32_e32 v84, v84, v85
	ds_bpermute_b32 v85, v99, v84
	s_waitcnt lgkmcnt(0)
	v_add_f32_e32 v84, v84, v85
	ds_bpermute_b32 v85, v100, v84
	s_waitcnt lgkmcnt(0)
	v_add_f32_e32 v84, v84, v85
	ds_bpermute_b32 v85, v101, v84
	s_waitcnt lgkmcnt(0)
	v_add_f32_e32 v84, v84, v85
	ds_bpermute_b32 v85, v102, v84
	s_waitcnt lgkmcnt(0)
	v_add_f32_e32 v84, v84, v85
	ds_bpermute_b32 v85, v103, v84
	s_waitcnt lgkmcnt(0)
	v_add_f32_e32 v84, v84, v85
	v_fmamk_f32 v84, v84, 0x3a800000, v104
	v_mul_f32_e32 v85, 0x4b800000, v84
	v_cmp_gt_f32_e32 vcc, 0x800000, v84
	s_nop 1
	v_cndmask_b32_e32 v84, v84, v85, vcc
	v_rsq_f32_e32 v84, v84
	s_nop 0
	v_mul_f32_e32 v85, 0x45800000, v84
	v_cndmask_b32_e32 v106, v84, v85, vcc
	s_waitcnt vmcnt(4)
	s_lshl_b32 s99, s98, 11
	s_add_u32 s99, s99, 0xb171900
	s_add_u32 s100, s90, s99
	s_addc_u32 s101, s91, 0
	v_pk_mul_f32 v[0:1], v[0:1], v[106:107] op_sel_hi:[1,0]
	v_pk_mul_f32 v[2:3], v[2:3], v[106:107] op_sel_hi:[1,0]
	v_pk_mul_f32 v[0:1], v[32:33], v[0:1]
	v_pk_mul_f32 v[2:3], v[34:35], v[2:3]
	v_pk_add_f32 v[48:49], v[48:49], 1.0 op_sel_hi:[1,0]
	v_pk_add_f32 v[50:51], v[50:51], 1.0 op_sel_hi:[1,0]
	v_pk_fma_f32 v[0:1], v[48:49], v[0:1], v[64:65]
	v_pk_fma_f32 v[2:3], v[50:51], v[2:3], v[66:67]
	v_cvt_pk_bf16_f32 v0, v0, v1
	v_cvt_pk_bf16_f32 v1, v2, v3
	global_store_dwordx2 v97, v[0:1], s[100:101] offset:0
	v_pk_mul_f32 v[4:5], v[4:5], v[106:107] op_sel_hi:[1,0]
	v_pk_mul_f32 v[6:7], v[6:7], v[106:107] op_sel_hi:[1,0]
	v_pk_mul_f32 v[4:5], v[36:37], v[4:5]
	v_pk_mul_f32 v[6:7], v[38:39], v[6:7]
	v_pk_add_f32 v[52:53], v[52:53], 1.0 op_sel_hi:[1,0]
	v_pk_add_f32 v[54:55], v[54:55], 1.0 op_sel_hi:[1,0]
	v_pk_fma_f32 v[4:5], v[52:53], v[4:5], v[68:69]
	v_pk_fma_f32 v[6:7], v[54:55], v[6:7], v[70:71]
	v_cvt_pk_bf16_f32 v4, v4, v5
	v_cvt_pk_bf16_f32 v5, v6, v7
	global_store_dwordx2 v97, v[4:5], s[100:101] offset:512
	v_pk_mul_f32 v[8:9], v[8:9], v[106:107] op_sel_hi:[1,0]
	v_pk_mul_f32 v[10:11], v[10:11], v[106:107] op_sel_hi:[1,0]
	v_pk_mul_f32 v[8:9], v[40:41], v[8:9]
	v_pk_mul_f32 v[10:11], v[42:43], v[10:11]
	v_pk_add_f32 v[56:57], v[56:57], 1.0 op_sel_hi:[1,0]
	v_pk_add_f32 v[58:59], v[58:59], 1.0 op_sel_hi:[1,0]
	v_pk_fma_f32 v[8:9], v[56:57], v[8:9], v[72:73]
	v_pk_fma_f32 v[10:11], v[58:59], v[10:11], v[74:75]
	v_cvt_pk_bf16_f32 v8, v8, v9
	v_cvt_pk_bf16_f32 v9, v10, v11
	global_store_dwordx2 v97, v[8:9], s[100:101] offset:1024
	v_pk_mul_f32 v[12:13], v[12:13], v[106:107] op_sel_hi:[1,0]
	v_pk_mul_f32 v[14:15], v[14:15], v[106:107] op_sel_hi:[1,0]
	v_pk_mul_f32 v[12:13], v[44:45], v[12:13]
	v_pk_mul_f32 v[14:15], v[46:47], v[14:15]
	v_pk_add_f32 v[60:61], v[60:61], 1.0 op_sel_hi:[1,0]
	v_pk_add_f32 v[62:63], v[62:63], 1.0 op_sel_hi:[1,0]
	v_pk_fma_f32 v[12:13], v[60:61], v[12:13], v[76:77]
	v_pk_fma_f32 v[14:15], v[62:63], v[14:15], v[78:79]
	v_cvt_pk_bf16_f32 v12, v12, v13
	v_cvt_pk_bf16_f32 v13, v14, v15
	global_store_dwordx2 v97, v[12:13], s[100:101] offset:1536
	s_add_u32 s98, s98, 0x800
	s_sub_u32 s99, s98, 0x2000
	s_lshr_b32 s99, s99, 11
	s_add_u32 s99, s99, 1
	s_cmp_lt_u32 s98, 0x2000
	s_cmov_b32 s99, 0
	s_mul_i32 s99, s99, 0x6000
	s_add_u32 s99, s99, 0x3441000
	s_add_u32 s100, s90, s99
	s_addc_u32 s101, s91, 0
	global_load_dwordx4 v[48:51], v96, s[100:101] offset:0
	global_load_dwordx4 v[52:55], v96, s[100:101] offset:1024
	global_load_dwordx4 v[56:59], v96, s[100:101] offset:2048
	global_load_dwordx4 v[60:63], v96, s[100:101] offset:3072
	s_sub_u32 s99, s98, 0x2000
	s_lshr_b32 s99, s99, 11
	s_add_u32 s99, s99, 1
	s_cmp_lt_u32 s98, 0x2000
	s_cmov_b32 s99, 0
	s_mul_i32 s99, s99, 0x6000
	s_add_u32 s99, s99, 0x3440000
	s_add_u32 s100, s90, s99
	s_addc_u32 s101, s91, 0
	global_load_dwordx4 v[64:67], v96, s[100:101] offset:0
	global_load_dwordx4 v[68:71], v96, s[100:101] offset:1024
	global_load_dwordx4 v[72:75], v96, s[100:101] offset:2048
	global_load_dwordx4 v[76:79], v96, s[100:101] offset:3072
	s_waitcnt vmcnt(12)
	v_mul_f32_e32 v80, v17, v17
	v_mul_f32_e32 v81, v21, v21
	v_mul_f32_e32 v82, v25, v25
	v_mul_f32_e32 v83, v29, v29
	v_fmac_f32_e32 v80, v16, v16
	v_fmac_f32_e32 v81, v20, v20
	v_fmac_f32_e32 v82, v24, v24
	v_fmac_f32_e32 v83, v28, v28
	v_fmac_f32_e32 v80, v18, v18
	v_fmac_f32_e32 v81, v22, v22
	v_fmac_f32_e32 v82, v26, v26
	v_fmac_f32_e32 v83, v30, v30
	v_fmac_f32_e32 v80, v19, v19
	v_fmac_f32_e32 v81, v23, v23
	v_fmac_f32_e32 v82, v27, v27
	v_fmac_f32_e32 v83, v31, v31
	v_add_f32_e32 v84, v80, v81
	v_add_f32_e32 v84, v84, v82
	v_add_f32_e32 v84, v84, v83
	ds_bpermute_b32 v85, v98, v84
	s_waitcnt lgkmcnt(0)
	v_add_f32_e32 v84, v84, v85
	ds_bpermute_b32 v85, v99, v84
	s_waitcnt lgkmcnt(0)
	v_add_f32_e32 v84, v84, v85
	ds_bpermute_b32 v85, v100, v84
	s_waitcnt lgkmcnt(0)
	v_add_f32_e32 v84, v84, v85
	ds_bpermute_b32 v85, v101, v84
	s_waitcnt lgkmcnt(0)
	v_add_f32_e32 v84, v84, v85
	ds_bpermute_b32 v85, v102, v84
	s_waitcnt lgkmcnt(0)
	v_add_f32_e32 v84, v84, v85
	ds_bpermute_b32 v85, v103, v84
	s_waitcnt lgkmcnt(0)
	v_add_f32_e32 v84, v84, v85
	v_fmamk_f32 v84, v84, 0x3a800000, v104
	v_mul_f32_e32 v85, 0x4b800000, v84
	v_cmp_gt_f32_e32 vcc, 0x800000, v84
	s_nop 1
	v_cndmask_b32_e32 v84, v84, v85, vcc
	v_rsq_f32_e32 v84, v84
	s_nop 0
	v_mul_f32_e32 v85, 0x45800000, v84
	v_cndmask_b32_e32 v106, v84, v85, vcc
	s_waitcnt vmcnt(0)
	s_lshl_b32 s99, s98, 11
	s_add_u32 s99, s99, 0xb171900
	s_add_u32 s100, s90, s99
	s_addc_u32 s101, s91, 0
	v_pk_mul_f32 v[16:17], v[16:17], v[106:107] op_sel_hi:[1,0]
	v_pk_mul_f32 v[18:19], v[18:19], v[106:107] op_sel_hi:[1,0]
	v_pk_mul_f32 v[16:17], v[32:33], v[16:17]
	v_pk_mul_f32 v[18:19], v[34:35], v[18:19]
	v_pk_add_f32 v[48:49], v[48:49], 1.0 op_sel_hi:[1,0]
	v_pk_add_f32 v[50:51], v[50:51], 1.0 op_sel_hi:[1,0]
	v_pk_fma_f32 v[16:17], v[48:49], v[16:17], v[64:65]
	v_pk_fma_f32 v[18:19], v[50:51], v[18:19], v[66:67]
	v_cvt_pk_bf16_f32 v16, v16, v17
	v_cvt_pk_bf16_f32 v17, v18, v19
	global_store_dwordx2 v97, v[16:17], s[100:101] offset:0
	v_pk_mul_f32 v[20:21], v[20:21], v[106:107] op_sel_hi:[1,0]
	v_pk_mul_f32 v[22:23], v[22:23], v[106:107] op_sel_hi:[1,0]
	v_pk_mul_f32 v[20:21], v[36:37], v[20:21]
	v_pk_mul_f32 v[22:23], v[38:39], v[22:23]
	v_pk_add_f32 v[52:53], v[52:53], 1.0 op_sel_hi:[1,0]
	v_pk_add_f32 v[54:55], v[54:55], 1.0 op_sel_hi:[1,0]
	v_pk_fma_f32 v[20:21], v[52:53], v[20:21], v[68:69]
	v_pk_fma_f32 v[22:23], v[54:55], v[22:23], v[70:71]
	v_cvt_pk_bf16_f32 v20, v20, v21
	v_cvt_pk_bf16_f32 v21, v22, v23
	global_store_dwordx2 v97, v[20:21], s[100:101] offset:512
	v_pk_mul_f32 v[24:25], v[24:25], v[106:107] op_sel_hi:[1,0]
	v_pk_mul_f32 v[26:27], v[26:27], v[106:107] op_sel_hi:[1,0]
	v_pk_mul_f32 v[24:25], v[40:41], v[24:25]
	v_pk_mul_f32 v[26:27], v[42:43], v[26:27]
	v_pk_add_f32 v[56:57], v[56:57], 1.0 op_sel_hi:[1,0]
	v_pk_add_f32 v[58:59], v[58:59], 1.0 op_sel_hi:[1,0]
	v_pk_fma_f32 v[24:25], v[56:57], v[24:25], v[72:73]
	v_pk_fma_f32 v[26:27], v[58:59], v[26:27], v[74:75]
	v_cvt_pk_bf16_f32 v24, v24, v25
	v_cvt_pk_bf16_f32 v25, v26, v27
	global_store_dwordx2 v97, v[24:25], s[100:101] offset:1024
	v_pk_mul_f32 v[28:29], v[28:29], v[106:107] op_sel_hi:[1,0]
	v_pk_mul_f32 v[30:31], v[30:31], v[106:107] op_sel_hi:[1,0]
	v_pk_mul_f32 v[28:29], v[44:45], v[28:29]
	v_pk_mul_f32 v[30:31], v[46:47], v[30:31]
	v_pk_add_f32 v[60:61], v[60:61], 1.0 op_sel_hi:[1,0]
	v_pk_add_f32 v[62:63], v[62:63], 1.0 op_sel_hi:[1,0]
	v_pk_fma_f32 v[28:29], v[60:61], v[28:29], v[76:77]
	v_pk_fma_f32 v[30:31], v[62:63], v[30:31], v[78:79]
	v_cvt_pk_bf16_f32 v28, v28, v29
	v_cvt_pk_bf16_f32 v29, v30, v31
	global_store_dwordx2 v97, v[28:29], s[100:101] offset:1536

.LBB0_973:
	s_or_b64 exec, exec, s[0:1]
	s_add_u32 s20, s88, 0x2000000
	s_addc_u32 s21, s89, 0
	s_waitcnt lgkmcnt(0)
	s_barrier
	s_and_saveexec_b64 s[2:3], s[78:79]
	s_cbranch_execz .LBB0_980
	v_mbcnt_hi_u32_b32 v0, -1, v182
	v_and_b32_e32 v2, 64, v0
	v_add_u32_e32 v2, 64, v2
	v_xor_b32_e32 v3, 32, v0
	v_cmp_lt_i32_e32 vcc, v3, v2
	s_mov_b64 s[0:1], s[78:79]
	s_mov_b64 s[6:7], s[80:81]
	v_cndmask_b32_e32 v3, v0, v3, vcc
	s_waitcnt vmcnt(1)
	v_lshlrev_b32_e32 v18, 2, v3
	v_xor_b32_e32 v3, 16, v0
	v_cmp_lt_i32_e32 vcc, v3, v2
	v_readlane_b32 s72, v250, 3
	v_and_b32_e32 v6, 0xfc, v149
	v_cndmask_b32_e32 v3, v0, v3, vcc
	v_lshlrev_b32_e32 v19, 2, v3
	v_xor_b32_e32 v3, 8, v0
	v_cmp_lt_i32_e32 vcc, v3, v2
	v_readlane_b32 s78, v250, 9
	v_readlane_b32 s79, v250, 10
	v_cndmask_b32_e32 v3, v0, v3, vcc
	v_lshlrev_b32_e32 v20, 2, v3
	v_xor_b32_e32 v3, 4, v0
	v_cmp_lt_i32_e32 vcc, v3, v2
	v_mov_b32_e32 v1, 0
	v_readlane_b32 s76, v250, 7
	v_cndmask_b32_e32 v3, v0, v3, vcc
	v_lshlrev_b32_e32 v21, 2, v3
	v_xor_b32_e32 v3, 2, v0
	v_cmp_lt_i32_e32 vcc, v3, v2
	v_readlane_b32 s77, v250, 8
	v_readlane_b32 s82, v250, 13
	v_cndmask_b32_e32 v3, v0, v3, vcc
	v_lshlrev_b32_e32 v22, 2, v3
	v_xor_b32_e32 v3, 1, v0
	v_cmp_lt_i32_e32 vcc, v3, v2
	v_readlane_b32 s83, v250, 14
	s_mov_b64 s[78:79], s[0:1]
	v_cndmask_b32_e32 v0, v0, v3, vcc
	v_lshlrev_b32_e32 v23, 2, v0
	v_lshlrev_b32_e32 v0, 2, v6
	v_readlane_b32 s0, v250, 19
	v_readlane_b32 s80, v250, 11
	v_readlane_b32 s81, v250, 12
	v_readlane_b32 s76, v250, 25
	v_lshl_add_u64 v[2:3], s[82:83], 0, v[0:1]
	v_or_b32_e32 v8, 0x100, v6
	v_or_b32_e32 v10, 0x200, v6
	v_or_b32_e32 v12, 0x300, v6
	v_lshlrev_b32_e32 v0, 1, v6
	v_readlane_b32 s1, v250, 20
	s_lshl_b32 s12, s92, 2
	s_mov_b64 s[80:81], s[6:7]
	v_readlane_b32 s77, v250, 26
	v_lshl_add_u64 v[4:5], s[0:1], 0, v[0:1]
	s_mov_b64 s[6:7], 0
	s_movk_i32 s13, 0x2000
	s_movk_i32 s14, 0x1fff
	v_lshlrev_b32_e32 v6, 2, v6
	v_mov_b32_e32 v7, v1
	s_movk_i32 s15, 0x1800
	s_mov_b64 s[8:9], 0x4000
	s_mov_b64 s[10:11], 0x3000
	v_lshlrev_b32_e32 v8, 2, v8
	v_mov_b32_e32 v9, v1
	v_lshlrev_b32_e32 v10, 2, v10
	v_mov_b32_e32 v11, v1
	v_lshlrev_b32_e32 v12, 2, v12
	v_mov_b32_e32 v13, v1
	v_mov_b32_e32 v24, 0x358637bd
	s_mov_b32 s16, 0x800000
	s_movk_i32 s17, 0x2fff
	v_mov_b32_e32 v14, v148
	v_readlane_b32 s73, v250, 4
	v_readlane_b32 s74, v250, 5
	v_readlane_b32 s75, v250, 6
	v_readlane_b32 s84, v250, 15
	v_readlane_b32 s85, v250, 16
	v_readlane_b32 s86, v250, 17
	v_readlane_b32 s87, v250, 18
	v_mbcnt_lo_u32_b32 v80, -1, 0
	v_mbcnt_hi_u32_b32 v80, -1, v80
	v_lshlrev_b32_e32 v96, 4, v80
	v_lshlrev_b32_e32 v97, 3, v80
	v_xor_b32_e32 v98, 32, v80
	v_lshlrev_b32_e32 v98, 2, v98
	v_xor_b32_e32 v99, 16, v80
	v_lshlrev_b32_e32 v99, 2, v99
	v_xor_b32_e32 v100, 8, v80
	v_lshlrev_b32_e32 v100, 2, v100
	v_xor_b32_e32 v101, 4, v80
	v_lshlrev_b32_e32 v101, 2, v101
	v_xor_b32_e32 v102, 2, v80
	v_lshlrev_b32_e32 v102, 2, v102
	v_xor_b32_e32 v103, 1, v80
	v_lshlrev_b32_e32 v103, 2, v103
	v_mov_b32_e32 v104, 0x358637bd
	v_mov_b32_e32 v107, 0
	v_readlane_b32 s100, v250, 13
	v_readlane_b32 s101, v250, 14
	s_nop 5
	global_load_dwordx4 v[32:35], v96, s[100:101] offset:0
	global_load_dwordx4 v[36:39], v96, s[100:101] offset:1024
	global_load_dwordx4 v[40:43], v96, s[100:101] offset:2048
	global_load_dwordx4 v[44:47], v96, s[100:101] offset:3072
	v_readfirstlane_b32 s98, v148
	s_nop 3
	s_lshl_b32 s99, s98, 12
	s_add_u32 s100, s88, s99
	s_addc_u32 s101, s89, 0
	global_load_dwordx4 v[0:3], v96, s[100:101] offset:0
	global_load_dwordx4 v[4:7], v96, s[100:101] offset:1024
	global_load_dwordx4 v[8:11], v96, s[100:101] offset:2048
	global_load_dwordx4 v[12:15], v96, s[100:101] offset:3072
	s_sub_u32 s99, s98, 0x2000
	s_lshr_b32 s99, s99, 11
	s_add_u32 s99, s99, 1
	s_cmp_lt_u32 s98, 0x2000
	s_cmov_b32 s99, 0
	s_mul_i32 s99, s99, 0x6000
	s_add_u32 s99, s99, 0x3444000
	s_add_u32 s100, s90, s99
	s_addc_u32 s101, s91, 0
	global_load_dwordx4 v[48:51], v96, s[100:101] offset:0
	global_load_dwordx4 v[52:55], v96, s[100:101] offset:1024
	global_load_dwordx4 v[56:59], v96, s[100:101] offset:2048
	global_load_dwordx4 v[60:63], v96, s[100:101] offset:3072
	s_sub_u32 s99, s98, 0x2000
	s_lshr_b32 s99, s99, 11
	s_add_u32 s99, s99, 1
	s_cmp_lt_u32 s98, 0x2000
	s_cmov_b32 s99, 0
	s_mul_i32 s99, s99, 0x6000
	s_add_u32 s99, s99, 0x3443000
	s_add_u32 s100, s90, s99
	s_addc_u32 s101, s91, 0
	global_load_dwordx4 v[64:67], v96, s[100:101] offset:0
	global_load_dwordx4 v[68:71], v96, s[100:101] offset:1024
	global_load_dwordx4 v[72:75], v96, s[100:101] offset:2048
	global_load_dwordx4 v[76:79], v96, s[100:101] offset:3072
	s_add_u32 s98, s98, 0x800
	s_lshl_b32 s99, s98, 12
	s_add_u32 s100, s88, s99
	s_addc_u32 s101, s89, 0
	global_load_dwordx4 v[16:19], v96, s[100:101] offset:0
	global_load_dwordx4 v[20:23], v96, s[100:101] offset:1024
	global_load_dwordx4 v[24:27], v96, s[100:101] offset:2048
	global_load_dwordx4 v[28:31], v96, s[100:101] offset:3072
	s_sub_u32 s98, s98, 0x800
	s_waitcnt vmcnt(12)
	v_mul_f32_e32 v80, v1, v1
	v_mul_f32_e32 v81, v5, v5
	v_mul_f32_e32 v82, v9, v9
	v_mul_f32_e32 v83, v13, v13
	v_fmac_f32_e32 v80, v0, v0
	v_fmac_f32_e32 v81, v4, v4
	v_fmac_f32_e32 v82, v8, v8
	v_fmac_f32_e32 v83, v12, v12
	v_fmac_f32_e32 v80, v2, v2
	v_fmac_f32_e32 v81, v6, v6
	v_fmac_f32_e32 v82, v10, v10
	v_fmac_f32_e32 v83, v14, v14
	v_fmac_f32_e32 v80, v3, v3
	v_fmac_f32_e32 v81, v7, v7
	v_fmac_f32_e32 v82, v11, v11
	v_fmac_f32_e32 v83, v15, v15
	v_add_f32_e32 v84, v80, v81
	v_add_f32_e32 v84, v84, v82
	v_add_f32_e32 v84, v84, v83
	ds_bpermute_b32 v85, v98, v84
	s_waitcnt lgkmcnt(0)
	v_add_f32_e32 v84, v84, v85
	ds_bpermute_b32 v85, v99, v84
	s_waitcnt lgkmcnt(0)
	v_add_f32_e32 v84, v84, v85
	ds_bpermute_b32 v85, v100, v84
	s_waitcnt lgkmcnt(0)
	v_add_f32_e32 v84, v84, v85
	ds_bpermute_b32 v85, v101, v84
	s_waitcnt lgkmcnt(0)
	v_add_f32_e32 v84, v84, v85
	ds_bpermute_b32 v85, v102, v84
	s_waitcnt lgkmcnt(0)
	v_add_f32_e32 v84, v84, v85
	ds_bpermute_b32 v85, v103, v84
	s_waitcnt lgkmcnt(0)
	v_add_f32_e32 v84, v84, v85
	v_fmamk_f32 v84, v84, 0x3a800000, v104
	v_mul_f32_e32 v85, 0x4b800000, v84
	v_cmp_gt_f32_e32 vcc, 0x800000, v84
	s_nop 1
	v_cndmask_b32_e32 v84, v84, v85, vcc
	v_rsq_f32_e32 v84, v84
	s_nop 0
	v_mul_f32_e32 v85, 0x45800000, v84
	v_cndmask_b32_e32 v106, v84, v85, vcc
	s_waitcnt vmcnt(4)
	s_lshl_b32 s99, s98, 11
	s_add_u32 s99, s99, 0xb171900
	s_add_u32 s100, s90, s99
	s_addc_u32 s101, s91, 0
	v_pk_mul_f32 v[0:1], v[0:1], v[106:107] op_sel_hi:[1,0]
	v_pk_mul_f32 v[2:3], v[2:3], v[106:107] op_sel_hi:[1,0]
	v_pk_mul_f32 v[0:1], v[32:33], v[0:1]
	v_pk_mul_f32 v[2:3], v[34:35], v[2:3]
	v_pk_add_f32 v[48:49], v[48:49], 1.0 op_sel_hi:[1,0]
	v_pk_add_f32 v[50:51], v[50:51], 1.0 op_sel_hi:[1,0]
	v_pk_fma_f32 v[0:1], v[48:49], v[0:1], v[64:65]
	v_pk_fma_f32 v[2:3], v[50:51], v[2:3], v[66:67]
	v_cvt_pk_bf16_f32 v0, v0, v1
	v_cvt_pk_bf16_f32 v1, v2, v3
	global_store_dwordx2 v97, v[0:1], s[100:101] offset:0
	v_pk_mul_f32 v[4:5], v[4:5], v[106:107] op_sel_hi:[1,0]
	v_pk_mul_f32 v[6:7], v[6:7], v[106:107] op_sel_hi:[1,0]
	v_pk_mul_f32 v[4:5], v[36:37], v[4:5]
	v_pk_mul_f32 v[6:7], v[38:39], v[6:7]
	v_pk_add_f32 v[52:53], v[52:53], 1.0 op_sel_hi:[1,0]
	v_pk_add_f32 v[54:55], v[54:55], 1.0 op_sel_hi:[1,0]
	v_pk_fma_f32 v[4:5], v[52:53], v[4:5], v[68:69]
	v_pk_fma_f32 v[6:7], v[54:55], v[6:7], v[70:71]
	v_cvt_pk_bf16_f32 v4, v4, v5
	v_cvt_pk_bf16_f32 v5, v6, v7
	global_store_dwordx2 v97, v[4:5], s[100:101] offset:512
	v_pk_mul_f32 v[8:9], v[8:9], v[106:107] op_sel_hi:[1,0]
	v_pk_mul_f32 v[10:11], v[10:11], v[106:107] op_sel_hi:[1,0]
	v_pk_mul_f32 v[8:9], v[40:41], v[8:9]
	v_pk_mul_f32 v[10:11], v[42:43], v[10:11]
	v_pk_add_f32 v[56:57], v[56:57], 1.0 op_sel_hi:[1,0]
	v_pk_add_f32 v[58:59], v[58:59], 1.0 op_sel_hi:[1,0]
	v_pk_fma_f32 v[8:9], v[56:57], v[8:9], v[72:73]
	v_pk_fma_f32 v[10:11], v[58:59], v[10:11], v[74:75]
	v_cvt_pk_bf16_f32 v8, v8, v9
	v_cvt_pk_bf16_f32 v9, v10, v11
	global_store_dwordx2 v97, v[8:9], s[100:101] offset:1024
	v_pk_mul_f32 v[12:13], v[12:13], v[106:107] op_sel_hi:[1,0]
	v_pk_mul_f32 v[14:15], v[14:15], v[106:107] op_sel_hi:[1,0]
	v_pk_mul_f32 v[12:13], v[44:45], v[12:13]
	v_pk_mul_f32 v[14:15], v[46:47], v[14:15]
	v_pk_add_f32 v[60:61], v[60:61], 1.0 op_sel_hi:[1,0]
	v_pk_add_f32 v[62:63], v[62:63], 1.0 op_sel_hi:[1,0]
	v_pk_fma_f32 v[12:13], v[60:61], v[12:13], v[76:77]
	v_pk_fma_f32 v[14:15], v[62:63], v[14:15], v[78:79]
	v_cvt_pk_bf16_f32 v12, v12, v13
	v_cvt_pk_bf16_f32 v13, v14, v15
	global_store_dwordx2 v97, v[12:13], s[100:101] offset:1536
	s_add_u32 s98, s98, 0x800
	s_sub_u32 s99, s98, 0x2000
	s_lshr_b32 s99, s99, 11
	s_add_u32 s99, s99, 1
	s_cmp_lt_u32 s98, 0x2000
	s_cmov_b32 s99, 0
	s_mul_i32 s99, s99, 0x6000
	s_add_u32 s99, s99, 0x3444000
	s_add_u32 s100, s90, s99
	s_addc_u32 s101, s91, 0
	global_load_dwordx4 v[48:51], v96, s[100:101] offset:0
	global_load_dwordx4 v[52:55], v96, s[100:101] offset:1024
	global_load_dwordx4 v[56:59], v96, s[100:101] offset:2048
	global_load_dwordx4 v[60:63], v96, s[100:101] offset:3072
	s_sub_u32 s99, s98, 0x2000
	s_lshr_b32 s99, s99, 11
	s_add_u32 s99, s99, 1
	s_cmp_lt_u32 s98, 0x2000
	s_cmov_b32 s99, 0
	s_mul_i32 s99, s99, 0x6000
	s_add_u32 s99, s99, 0x3443000
	s_add_u32 s100, s90, s99
	s_addc_u32 s101, s91, 0
	global_load_dwordx4 v[64:67], v96, s[100:101] offset:0
	global_load_dwordx4 v[68:71], v96, s[100:101] offset:1024
	global_load_dwordx4 v[72:75], v96, s[100:101] offset:2048
	global_load_dwordx4 v[76:79], v96, s[100:101] offset:3072
	s_add_u32 s98, s98, 0x800
	s_lshl_b32 s99, s98, 12
	s_add_u32 s100, s88, s99
	s_addc_u32 s101, s89, 0
	global_load_dwordx4 v[0:3], v96, s[100:101] offset:0
	global_load_dwordx4 v[4:7], v96, s[100:101] offset:1024
	global_load_dwordx4 v[8:11], v96, s[100:101] offset:2048
	global_load_dwordx4 v[12:15], v96, s[100:101] offset:3072
	s_sub_u32 s98, s98, 0x800
	s_waitcnt vmcnt(16)
	v_mul_f32_e32 v80, v17, v17
	v_mul_f32_e32 v81, v21, v21
	v_mul_f32_e32 v82, v25, v25
	v_mul_f32_e32 v83, v29, v29
	v_fmac_f32_e32 v80, v16, v16
	v_fmac_f32_e32 v81, v20, v20
	v_fmac_f32_e32 v82, v24, v24
	v_fmac_f32_e32 v83, v28, v28
	v_fmac_f32_e32 v80, v18, v18
	v_fmac_f32_e32 v81, v22, v22
	v_fmac_f32_e32 v82, v26, v26
	v_fmac_f32_e32 v83, v30, v30
	v_fmac_f32_e32 v80, v19, v19
	v_fmac_f32_e32 v81, v23, v23
	v_fmac_f32_e32 v82, v27, v27
	v_fmac_f32_e32 v83, v31, v31
	v_add_f32_e32 v84, v80, v81
	v_add_f32_e32 v84, v84, v82
	v_add_f32_e32 v84, v84, v83
	ds_bpermute_b32 v85, v98, v84
	s_waitcnt lgkmcnt(0)
	v_add_f32_e32 v84, v84, v85
	ds_bpermute_b32 v85, v99, v84
	s_waitcnt lgkmcnt(0)
	v_add_f32_e32 v84, v84, v85
	ds_bpermute_b32 v85, v100, v84
	s_waitcnt lgkmcnt(0)
	v_add_f32_e32 v84, v84, v85
	ds_bpermute_b32 v85, v101, v84
	s_waitcnt lgkmcnt(0)
	v_add_f32_e32 v84, v84, v85
	ds_bpermute_b32 v85, v102, v84
	s_waitcnt lgkmcnt(0)
	v_add_f32_e32 v84, v84, v85
	ds_bpermute_b32 v85, v103, v84
	s_waitcnt lgkmcnt(0)
	v_add_f32_e32 v84, v84, v85
	v_fmamk_f32 v84, v84, 0x3a800000, v104
	v_mul_f32_e32 v85, 0x4b800000, v84
	v_cmp_gt_f32_e32 vcc, 0x800000, v84
	s_nop 1
	v_cndmask_b32_e32 v84, v84, v85, vcc
	v_rsq_f32_e32 v84, v84
	s_nop 0
	v_mul_f32_e32 v85, 0x45800000, v84
	v_cndmask_b32_e32 v106, v84, v85, vcc
	s_waitcnt vmcnt(4)
	s_lshl_b32 s99, s98, 11
	s_add_u32 s99, s99, 0xb171900
	s_add_u32 s100, s90, s99
	s_addc_u32 s101, s91, 0
	v_pk_mul_f32 v[16:17], v[16:17], v[106:107] op_sel_hi:[1,0]
	v_pk_mul_f32 v[18:19], v[18:19], v[106:107] op_sel_hi:[1,0]
	v_pk_mul_f32 v[16:17], v[32:33], v[16:17]
	v_pk_mul_f32 v[18:19], v[34:35], v[18:19]
	v_pk_add_f32 v[48:49], v[48:49], 1.0 op_sel_hi:[1,0]
	v_pk_add_f32 v[50:51], v[50:51], 1.0 op_sel_hi:[1,0]
	v_pk_fma_f32 v[16:17], v[48:49], v[16:17], v[64:65]
	v_pk_fma_f32 v[18:19], v[50:51], v[18:19], v[66:67]
	v_cvt_pk_bf16_f32 v16, v16, v17
	v_cvt_pk_bf16_f32 v17, v18, v19
	global_store_dwordx2 v97, v[16:17], s[100:101] offset:0
	v_pk_mul_f32 v[20:21], v[20:21], v[106:107] op_sel_hi:[1,0]
	v_pk_mul_f32 v[22:23], v[22:23], v[106:107] op_sel_hi:[1,0]
	v_pk_mul_f32 v[20:21], v[36:37], v[20:21]
	v_pk_mul_f32 v[22:23], v[38:39], v[22:23]
	v_pk_add_f32 v[52:53], v[52:53], 1.0 op_sel_hi:[1,0]
	v_pk_add_f32 v[54:55], v[54:55], 1.0 op_sel_hi:[1,0]
	v_pk_fma_f32 v[20:21], v[52:53], v[20:21], v[68:69]
	v_pk_fma_f32 v[22:23], v[54:55], v[22:23], v[70:71]
	v_cvt_pk_bf16_f32 v20, v20, v21
	v_cvt_pk_bf16_f32 v21, v22, v23
	global_store_dwordx2 v97, v[20:21], s[100:101] offset:512
	v_pk_mul_f32 v[24:25], v[24:25], v[106:107] op_sel_hi:[1,0]
	v_pk_mul_f32 v[26:27], v[26:27], v[106:107] op_sel_hi:[1,0]
	v_pk_mul_f32 v[24:25], v[40:41], v[24:25]
	v_pk_mul_f32 v[26:27], v[42:43], v[26:27]
	v_pk_add_f32 v[56:57], v[56:57], 1.0 op_sel_hi:[1,0]
	v_pk_add_f32 v[58:59], v[58:59], 1.0 op_sel_hi:[1,0]
	v_pk_fma_f32 v[24:25], v[56:57], v[24:25], v[72:73]
	v_pk_fma_f32 v[26:27], v[58:59], v[26:27], v[74:75]
	v_cvt_pk_bf16_f32 v24, v24, v25
	v_cvt_pk_bf16_f32 v25, v26, v27
	global_store_dwordx2 v97, v[24:25], s[100:101] offset:1024
	v_pk_mul_f32 v[28:29], v[28:29], v[106:107] op_sel_hi:[1,0]
	v_pk_mul_f32 v[30:31], v[30:31], v[106:107] op_sel_hi:[1,0]
	v_pk_mul_f32 v[28:29], v[44:45], v[28:29]
	v_pk_mul_f32 v[30:31], v[46:47], v[30:31]
	v_pk_add_f32 v[60:61], v[60:61], 1.0 op_sel_hi:[1,0]
	v_pk_add_f32 v[62:63], v[62:63], 1.0 op_sel_hi:[1,0]
	v_pk_fma_f32 v[28:29], v[60:61], v[28:29], v[76:77]
	v_pk_fma_f32 v[30:31], v[62:63], v[30:31], v[78:79]
	v_cvt_pk_bf16_f32 v28, v28, v29
	v_cvt_pk_bf16_f32 v29, v30, v31
	global_store_dwordx2 v97, v[28:29], s[100:101] offset:1536
	s_add_u32 s98, s98, 0x800
	s_sub_u32 s99, s98, 0x2000
	s_lshr_b32 s99, s99, 11
	s_add_u32 s99, s99, 1
	s_cmp_lt_u32 s98, 0x2000
	s_cmov_b32 s99, 0
	s_mul_i32 s99, s99, 0x6000
	s_add_u32 s99, s99, 0x3444000
	s_add_u32 s100, s90, s99
	s_addc_u32 s101, s91, 0
	global_load_dwordx4 v[48:51], v96, s[100:101] offset:0
	global_load_dwordx4 v[52:55], v96, s[100:101] offset:1024
	global_load_dwordx4 v[56:59], v96, s[100:101] offset:2048
	global_load_dwordx4 v[60:63], v96, s[100:101] offset:3072
	s_sub_u32 s99, s98, 0x2000
	s_lshr_b32 s99, s99, 11
	s_add_u32 s99, s99, 1
	s_cmp_lt_u32 s98, 0x2000
	s_cmov_b32 s99, 0
	s_mul_i32 s99, s99, 0x6000
	s_add_u32 s99, s99, 0x3443000
	s_add_u32 s100, s90, s99
	s_addc_u32 s101, s91, 0
	global_load_dwordx4 v[64:67], v96, s[100:101] offset:0
	global_load_dwordx4 v[68:71], v96, s[100:101] offset:1024
	global_load_dwordx4 v[72:75], v96, s[100:101] offset:2048
	global_load_dwordx4 v[76:79], v96, s[100:101] offset:3072
	s_add_u32 s98, s98, 0x800
	s_lshl_b32 s99, s98, 12
	s_add_u32 s100, s88, s99
	s_addc_u32 s101, s89, 0
	global_load_dwordx4 v[16:19], v96, s[100:101] offset:0
	global_load_dwordx4 v[20:23], v96, s[100:101] offset:1024
	global_load_dwordx4 v[24:27], v96, s[100:101] offset:2048
	global_load_dwordx4 v[28:31], v96, s[100:101] offset:3072
	s_sub_u32 s98, s98, 0x800
	s_waitcnt vmcnt(16)
	v_mul_f32_e32 v80, v1, v1
	v_mul_f32_e32 v81, v5, v5
	v_mul_f32_e32 v82, v9, v9
	v_mul_f32_e32 v83, v13, v13
	v_fmac_f32_e32 v80, v0, v0
	v_fmac_f32_e32 v81, v4, v4
	v_fmac_f32_e32 v82, v8, v8
	v_fmac_f32_e32 v83, v12, v12
	v_fmac_f32_e32 v80, v2, v2
	v_fmac_f32_e32 v81, v6, v6
	v_fmac_f32_e32 v82, v10, v10
	v_fmac_f32_e32 v83, v14, v14
	v_fmac_f32_e32 v80, v3, v3
	v_fmac_f32_e32 v81, v7, v7
	v_fmac_f32_e32 v82, v11, v11
	v_fmac_f32_e32 v83, v15, v15
	v_add_f32_e32 v84, v80, v81
	v_add_f32_e32 v84, v84, v82
	v_add_f32_e32 v84, v84, v83
	ds_bpermute_b32 v85, v98, v84
	s_waitcnt lgkmcnt(0)
	v_add_f32_e32 v84, v84, v85
	ds_bpermute_b32 v85, v99, v84
	s_waitcnt lgkmcnt(0)
	v_add_f32_e32 v84, v84, v85
	ds_bpermute_b32 v85, v100, v84
	s_waitcnt lgkmcnt(0)
	v_add_f32_e32 v84, v84, v85
	ds_bpermute_b32 v85, v101, v84
	s_waitcnt lgkmcnt(0)
	v_add_f32_e32 v84, v84, v85
	ds_bpermute_b32 v85, v102, v84
	s_waitcnt lgkmcnt(0)
	v_add_f32_e32 v84, v84, v85
	ds_bpermute_b32 v85, v103, v84
	s_waitcnt lgkmcnt(0)
	v_add_f32_e32 v84, v84, v85
	v_fmamk_f32 v84, v84, 0x3a800000, v104
	v_mul_f32_e32 v85, 0x4b800000, v84
	v_cmp_gt_f32_e32 vcc, 0x800000, v84
	s_nop 1
	v_cndmask_b32_e32 v84, v84, v85, vcc
	v_rsq_f32_e32 v84, v84
	s_nop 0
	v_mul_f32_e32 v85, 0x45800000, v84
	v_cndmask_b32_e32 v106, v84, v85, vcc
	s_waitcnt vmcnt(4)
	s_lshl_b32 s99, s98, 11
	s_add_u32 s99, s99, 0xb171900
	s_add_u32 s100, s90, s99
	s_addc_u32 s101, s91, 0
	v_pk_mul_f32 v[0:1], v[0:1], v[106:107] op_sel_hi:[1,0]
	v_pk_mul_f32 v[2:3], v[2:3], v[106:107] op_sel_hi:[1,0]
	v_pk_mul_f32 v[0:1], v[32:33], v[0:1]
	v_pk_mul_f32 v[2:3], v[34:35], v[2:3]
	v_pk_add_f32 v[48:49], v[48:49], 1.0 op_sel_hi:[1,0]
	v_pk_add_f32 v[50:51], v[50:51], 1.0 op_sel_hi:[1,0]
	v_pk_fma_f32 v[0:1], v[48:49], v[0:1], v[64:65]
	v_pk_fma_f32 v[2:3], v[50:51], v[2:3], v[66:67]
	v_cvt_pk_bf16_f32 v0, v0, v1
	v_cvt_pk_bf16_f32 v1, v2, v3
	global_store_dwordx2 v97, v[0:1], s[100:101] offset:0
	v_pk_mul_f32 v[4:5], v[4:5], v[106:107] op_sel_hi:[1,0]
	v_pk_mul_f32 v[6:7], v[6:7], v[106:107] op_sel_hi:[1,0]
	v_pk_mul_f32 v[4:5], v[36:37], v[4:5]
	v_pk_mul_f32 v[6:7], v[38:39], v[6:7]
	v_pk_add_f32 v[52:53], v[52:53], 1.0 op_sel_hi:[1,0]
	v_pk_add_f32 v[54:55], v[54:55], 1.0 op_sel_hi:[1,0]
	v_pk_fma_f32 v[4:5], v[52:53], v[4:5], v[68:69]
	v_pk_fma_f32 v[6:7], v[54:55], v[6:7], v[70:71]
	v_cvt_pk_bf16_f32 v4, v4, v5
	v_cvt_pk_bf16_f32 v5, v6, v7
	global_store_dwordx2 v97, v[4:5], s[100:101] offset:512
	v_pk_mul_f32 v[8:9], v[8:9], v[106:107] op_sel_hi:[1,0]
	v_pk_mul_f32 v[10:11], v[10:11], v[106:107] op_sel_hi:[1,0]
	v_pk_mul_f32 v[8:9], v[40:41], v[8:9]
	v_pk_mul_f32 v[10:11], v[42:43], v[10:11]
	v_pk_add_f32 v[56:57], v[56:57], 1.0 op_sel_hi:[1,0]
	v_pk_add_f32 v[58:59], v[58:59], 1.0 op_sel_hi:[1,0]
	v_pk_fma_f32 v[8:9], v[56:57], v[8:9], v[72:73]
	v_pk_fma_f32 v[10:11], v[58:59], v[10:11], v[74:75]
	v_cvt_pk_bf16_f32 v8, v8, v9
	v_cvt_pk_bf16_f32 v9, v10, v11
	global_store_dwordx2 v97, v[8:9], s[100:101] offset:1024
	v_pk_mul_f32 v[12:13], v[12:13], v[106:107] op_sel_hi:[1,0]
	v_pk_mul_f32 v[14:15], v[14:15], v[106:107] op_sel_hi:[1,0]
	v_pk_mul_f32 v[12:13], v[44:45], v[12:13]
	v_pk_mul_f32 v[14:15], v[46:47], v[14:15]
	v_pk_add_f32 v[60:61], v[60:61], 1.0 op_sel_hi:[1,0]
	v_pk_add_f32 v[62:63], v[62:63], 1.0 op_sel_hi:[1,0]
	v_pk_fma_f32 v[12:13], v[60:61], v[12:13], v[76:77]
	v_pk_fma_f32 v[14:15], v[62:63], v[14:15], v[78:79]
	v_cvt_pk_bf16_f32 v12, v12, v13
	v_cvt_pk_bf16_f32 v13, v14, v15
	global_store_dwordx2 v97, v[12:13], s[100:101] offset:1536
	s_add_u32 s98, s98, 0x800
	s_sub_u32 s99, s98, 0x2000
	s_lshr_b32 s99, s99, 11
	s_add_u32 s99, s99, 1
	s_cmp_lt_u32 s98, 0x2000
	s_cmov_b32 s99, 0
	s_mul_i32 s99, s99, 0x6000
	s_add_u32 s99, s99, 0x3444000
	s_add_u32 s100, s90, s99
	s_addc_u32 s101, s91, 0
	global_load_dwordx4 v[48:51], v96, s[100:101] offset:0
	global_load_dwordx4 v[52:55], v96, s[100:101] offset:1024
	global_load_dwordx4 v[56:59], v96, s[100:101] offset:2048
	global_load_dwordx4 v[60:63], v96, s[100:101] offset:3072
	s_sub_u32 s99, s98, 0x2000
	s_lshr_b32 s99, s99, 11
	s_add_u32 s99, s99, 1
	s_cmp_lt_u32 s98, 0x2000
	s_cmov_b32 s99, 0
	s_mul_i32 s99, s99, 0x6000
	s_add_u32 s99, s99, 0x3443000
	s_add_u32 s100, s90, s99
	s_addc_u32 s101, s91, 0
	global_load_dwordx4 v[64:67], v96, s[100:101] offset:0
	global_load_dwordx4 v[68:71], v96, s[100:101] offset:1024
	global_load_dwordx4 v[72:75], v96, s[100:101] offset:2048
	global_load_dwordx4 v[76:79], v96, s[100:101] offset:3072
	s_add_u32 s98, s98, 0x800
	s_lshl_b32 s99, s98, 12
	s_add_u32 s100, s88, s99
	s_addc_u32 s101, s89, 0
	global_load_dwordx4 v[0:3], v96, s[100:101] offset:0
	global_load_dwordx4 v[4:7], v96, s[100:101] offset:1024
	global_load_dwordx4 v[8:11], v96, s[100:101] offset:2048
	global_load_dwordx4 v[12:15], v96, s[100:101] offset:3072
	s_sub_u32 s98, s98, 0x800
	s_waitcnt vmcnt(16)
	v_mul_f32_e32 v80, v17, v17
	v_mul_f32_e32 v81, v21, v21
	v_mul_f32_e32 v82, v25, v25
	v_mul_f32_e32 v83, v29, v29
	v_fmac_f32_e32 v80, v16, v16
	v_fmac_f32_e32 v81, v20, v20
	v_fmac_f32_e32 v82, v24, v24
	v_fmac_f32_e32 v83, v28, v28
	v_fmac_f32_e32 v80, v18, v18
	v_fmac_f32_e32 v81, v22, v22
	v_fmac_f32_e32 v82, v26, v26
	v_fmac_f32_e32 v83, v30, v30
	v_fmac_f32_e32 v80, v19, v19
	v_fmac_f32_e32 v81, v23, v23
	v_fmac_f32_e32 v82, v27, v27
	v_fmac_f32_e32 v83, v31, v31
	v_add_f32_e32 v84, v80, v81
	v_add_f32_e32 v84, v84, v82
	v_add_f32_e32 v84, v84, v83
	ds_bpermute_b32 v85, v98, v84
	s_waitcnt lgkmcnt(0)
	v_add_f32_e32 v84, v84, v85
	ds_bpermute_b32 v85, v99, v84
	s_waitcnt lgkmcnt(0)
	v_add_f32_e32 v84, v84, v85
	ds_bpermute_b32 v85, v100, v84
	s_waitcnt lgkmcnt(0)
	v_add_f32_e32 v84, v84, v85
	ds_bpermute_b32 v85, v101, v84
	s_waitcnt lgkmcnt(0)
	v_add_f32_e32 v84, v84, v85
	ds_bpermute_b32 v85, v102, v84
	s_waitcnt lgkmcnt(0)
	v_add_f32_e32 v84, v84, v85
	ds_bpermute_b32 v85, v103, v84
	s_waitcnt lgkmcnt(0)
	v_add_f32_e32 v84, v84, v85
	v_fmamk_f32 v84, v84, 0x3a800000, v104
	v_mul_f32_e32 v85, 0x4b800000, v84
	v_cmp_gt_f32_e32 vcc, 0x800000, v84
	s_nop 1
	v_cndmask_b32_e32 v84, v84, v85, vcc
	v_rsq_f32_e32 v84, v84
	s_nop 0
	v_mul_f32_e32 v85, 0x45800000, v84
	v_cndmask_b32_e32 v106, v84, v85, vcc
	s_waitcnt vmcnt(4)
	s_lshl_b32 s99, s98, 11
	s_add_u32 s99, s99, 0xb171900
	s_add_u32 s100, s90, s99
	s_addc_u32 s101, s91, 0
	v_pk_mul_f32 v[16:17], v[16:17], v[106:107] op_sel_hi:[1,0]
	v_pk_mul_f32 v[18:19], v[18:19], v[106:107] op_sel_hi:[1,0]
	v_pk_mul_f32 v[16:17], v[32:33], v[16:17]
	v_pk_mul_f32 v[18:19], v[34:35], v[18:19]
	v_pk_add_f32 v[48:49], v[48:49], 1.0 op_sel_hi:[1,0]
	v_pk_add_f32 v[50:51], v[50:51], 1.0 op_sel_hi:[1,0]
	v_pk_fma_f32 v[16:17], v[48:49], v[16:17], v[64:65]
	v_pk_fma_f32 v[18:19], v[50:51], v[18:19], v[66:67]
	v_cvt_pk_bf16_f32 v16, v16, v17
	v_cvt_pk_bf16_f32 v17, v18, v19
	global_store_dwordx2 v97, v[16:17], s[100:101] offset:0
	v_pk_mul_f32 v[20:21], v[20:21], v[106:107] op_sel_hi:[1,0]
	v_pk_mul_f32 v[22:23], v[22:23], v[106:107] op_sel_hi:[1,0]
	v_pk_mul_f32 v[20:21], v[36:37], v[20:21]
	v_pk_mul_f32 v[22:23], v[38:39], v[22:23]
	v_pk_add_f32 v[52:53], v[52:53], 1.0 op_sel_hi:[1,0]
	v_pk_add_f32 v[54:55], v[54:55], 1.0 op_sel_hi:[1,0]
	v_pk_fma_f32 v[20:21], v[52:53], v[20:21], v[68:69]
	v_pk_fma_f32 v[22:23], v[54:55], v[22:23], v[70:71]
	v_cvt_pk_bf16_f32 v20, v20, v21
	v_cvt_pk_bf16_f32 v21, v22, v23
	global_store_dwordx2 v97, v[20:21], s[100:101] offset:512
	v_pk_mul_f32 v[24:25], v[24:25], v[106:107] op_sel_hi:[1,0]
	v_pk_mul_f32 v[26:27], v[26:27], v[106:107] op_sel_hi:[1,0]
	v_pk_mul_f32 v[24:25], v[40:41], v[24:25]
	v_pk_mul_f32 v[26:27], v[42:43], v[26:27]
	v_pk_add_f32 v[56:57], v[56:57], 1.0 op_sel_hi:[1,0]
	v_pk_add_f32 v[58:59], v[58:59], 1.0 op_sel_hi:[1,0]
	v_pk_fma_f32 v[24:25], v[56:57], v[24:25], v[72:73]
	v_pk_fma_f32 v[26:27], v[58:59], v[26:27], v[74:75]
	v_cvt_pk_bf16_f32 v24, v24, v25
	v_cvt_pk_bf16_f32 v25, v26, v27
	global_store_dwordx2 v97, v[24:25], s[100:101] offset:1024
	v_pk_mul_f32 v[28:29], v[28:29], v[106:107] op_sel_hi:[1,0]
	v_pk_mul_f32 v[30:31], v[30:31], v[106:107] op_sel_hi:[1,0]
	v_pk_mul_f32 v[28:29], v[44:45], v[28:29]
	v_pk_mul_f32 v[30:31], v[46:47], v[30:31]
	v_pk_add_f32 v[60:61], v[60:61], 1.0 op_sel_hi:[1,0]
	v_pk_add_f32 v[62:63], v[62:63], 1.0 op_sel_hi:[1,0]
	v_pk_fma_f32 v[28:29], v[60:61], v[28:29], v[76:77]
	v_pk_fma_f32 v[30:31], v[62:63], v[30:31], v[78:79]
	v_cvt_pk_bf16_f32 v28, v28, v29
	v_cvt_pk_bf16_f32 v29, v30, v31
	global_store_dwordx2 v97, v[28:29], s[100:101] offset:1536
	s_add_u32 s98, s98, 0x800
	s_sub_u32 s99, s98, 0x2000
	s_lshr_b32 s99, s99, 11
	s_add_u32 s99, s99, 1
	s_cmp_lt_u32 s98, 0x2000
	s_cmov_b32 s99, 0
	s_mul_i32 s99, s99, 0x6000
	s_add_u32 s99, s99, 0x3444000
	s_add_u32 s100, s90, s99
	s_addc_u32 s101, s91, 0
	global_load_dwordx4 v[48:51], v96, s[100:101] offset:0
	global_load_dwordx4 v[52:55], v96, s[100:101] offset:1024
	global_load_dwordx4 v[56:59], v96, s[100:101] offset:2048
	global_load_dwordx4 v[60:63], v96, s[100:101] offset:3072
	s_sub_u32 s99, s98, 0x2000
	s_lshr_b32 s99, s99, 11
	s_add_u32 s99, s99, 1
	s_cmp_lt_u32 s98, 0x2000
	s_cmov_b32 s99, 0
	s_mul_i32 s99, s99, 0x6000
	s_add_u32 s99, s99, 0x3443000
	s_add_u32 s100, s90, s99
	s_addc_u32 s101, s91, 0
	global_load_dwordx4 v[64:67], v96, s[100:101] offset:0
	global_load_dwordx4 v[68:71], v96, s[100:101] offset:1024
	global_load_dwordx4 v[72:75], v96, s[100:101] offset:2048
	global_load_dwordx4 v[76:79], v96, s[100:101] offset:3072
	s_add_u32 s98, s98, 0x800
	s_lshl_b32 s99, s98, 12
	s_add_u32 s100, s88, s99
	s_addc_u32 s101, s89, 0
	global_load_dwordx4 v[16:19], v96, s[100:101] offset:0
	global_load_dwordx4 v[20:23], v96, s[100:101] offset:1024
	global_load_dwordx4 v[24:27], v96, s[100:101] offset:2048
	global_load_dwordx4 v[28:31], v96, s[100:101] offset:3072
	s_sub_u32 s98, s98, 0x800
	s_waitcnt vmcnt(16)
	v_mul_f32_e32 v80, v1, v1
	v_mul_f32_e32 v81, v5, v5
	v_mul_f32_e32 v82, v9, v9
	v_mul_f32_e32 v83, v13, v13
	v_fmac_f32_e32 v80, v0, v0
	v_fmac_f32_e32 v81, v4, v4
	v_fmac_f32_e32 v82, v8, v8
	v_fmac_f32_e32 v83, v12, v12
	v_fmac_f32_e32 v80, v2, v2
	v_fmac_f32_e32 v81, v6, v6
	v_fmac_f32_e32 v82, v10, v10
	v_fmac_f32_e32 v83, v14, v14
	v_fmac_f32_e32 v80, v3, v3
	v_fmac_f32_e32 v81, v7, v7
	v_fmac_f32_e32 v82, v11, v11
	v_fmac_f32_e32 v83, v15, v15
	v_add_f32_e32 v84, v80, v81
	v_add_f32_e32 v84, v84, v82
	v_add_f32_e32 v84, v84, v83
	ds_bpermute_b32 v85, v98, v84
	s_waitcnt lgkmcnt(0)
	v_add_f32_e32 v84, v84, v85
	ds_bpermute_b32 v85, v99, v84
	s_waitcnt lgkmcnt(0)
	v_add_f32_e32 v84, v84, v85
	ds_bpermute_b32 v85, v100, v84
	s_waitcnt lgkmcnt(0)
	v_add_f32_e32 v84, v84, v85
	ds_bpermute_b32 v85, v101, v84
	s_waitcnt lgkmcnt(0)
	v_add_f32_e32 v84, v84, v85
	ds_bpermute_b32 v85, v102, v84
	s_waitcnt lgkmcnt(0)
	v_add_f32_e32 v84, v84, v85
	ds_bpermute_b32 v85, v103, v84
	s_waitcnt lgkmcnt(0)
	v_add_f32_e32 v84, v84, v85
	v_fmamk_f32 v84, v84, 0x3a800000, v104
	v_mul_f32_e32 v85, 0x4b800000, v84
	v_cmp_gt_f32_e32 vcc, 0x800000, v84
	s_nop 1
	v_cndmask_b32_e32 v84, v84, v85, vcc
	v_rsq_f32_e32 v84, v84
	s_nop 0
	v_mul_f32_e32 v85, 0x45800000, v84
	v_cndmask_b32_e32 v106, v84, v85, vcc
	s_waitcnt vmcnt(4)
	s_lshl_b32 s99, s98, 11
	s_add_u32 s99, s99, 0xb171900
	s_add_u32 s100, s90, s99
	s_addc_u32 s101, s91, 0
	v_pk_mul_f32 v[0:1], v[0:1], v[106:107] op_sel_hi:[1,0]
	v_pk_mul_f32 v[2:3], v[2:3], v[106:107] op_sel_hi:[1,0]
	v_pk_mul_f32 v[0:1], v[32:33], v[0:1]
	v_pk_mul_f32 v[2:3], v[34:35], v[2:3]
	v_pk_add_f32 v[48:49], v[48:49], 1.0 op_sel_hi:[1,0]
	v_pk_add_f32 v[50:51], v[50:51], 1.0 op_sel_hi:[1,0]
	v_pk_fma_f32 v[0:1], v[48:49], v[0:1], v[64:65]
	v_pk_fma_f32 v[2:3], v[50:51], v[2:3], v[66:67]
	v_cvt_pk_bf16_f32 v0, v0, v1
	v_cvt_pk_bf16_f32 v1, v2, v3
	global_store_dwordx2 v97, v[0:1], s[100:101] offset:0
	v_pk_mul_f32 v[4:5], v[4:5], v[106:107] op_sel_hi:[1,0]
	v_pk_mul_f32 v[6:7], v[6:7], v[106:107] op_sel_hi:[1,0]
	v_pk_mul_f32 v[4:5], v[36:37], v[4:5]
	v_pk_mul_f32 v[6:7], v[38:39], v[6:7]
	v_pk_add_f32 v[52:53], v[52:53], 1.0 op_sel_hi:[1,0]
	v_pk_add_f32 v[54:55], v[54:55], 1.0 op_sel_hi:[1,0]
	v_pk_fma_f32 v[4:5], v[52:53], v[4:5], v[68:69]
	v_pk_fma_f32 v[6:7], v[54:55], v[6:7], v[70:71]
	v_cvt_pk_bf16_f32 v4, v4, v5
	v_cvt_pk_bf16_f32 v5, v6, v7
	global_store_dwordx2 v97, v[4:5], s[100:101] offset:512
	v_pk_mul_f32 v[8:9], v[8:9], v[106:107] op_sel_hi:[1,0]
	v_pk_mul_f32 v[10:11], v[10:11], v[106:107] op_sel_hi:[1,0]
	v_pk_mul_f32 v[8:9], v[40:41], v[8:9]
	v_pk_mul_f32 v[10:11], v[42:43], v[10:11]
	v_pk_add_f32 v[56:57], v[56:57], 1.0 op_sel_hi:[1,0]
	v_pk_add_f32 v[58:59], v[58:59], 1.0 op_sel_hi:[1,0]
	v_pk_fma_f32 v[8:9], v[56:57], v[8:9], v[72:73]
	v_pk_fma_f32 v[10:11], v[58:59], v[10:11], v[74:75]
	v_cvt_pk_bf16_f32 v8, v8, v9
	v_cvt_pk_bf16_f32 v9, v10, v11
	global_store_dwordx2 v97, v[8:9], s[100:101] offset:1024
	v_pk_mul_f32 v[12:13], v[12:13], v[106:107] op_sel_hi:[1,0]
	v_pk_mul_f32 v[14:15], v[14:15], v[106:107] op_sel_hi:[1,0]
	v_pk_mul_f32 v[12:13], v[44:45], v[12:13]
	v_pk_mul_f32 v[14:15], v[46:47], v[14:15]
	v_pk_add_f32 v[60:61], v[60:61], 1.0 op_sel_hi:[1,0]
	v_pk_add_f32 v[62:63], v[62:63], 1.0 op_sel_hi:[1,0]
	v_pk_fma_f32 v[12:13], v[60:61], v[12:13], v[76:77]
	v_pk_fma_f32 v[14:15], v[62:63], v[14:15], v[78:79]
	v_cvt_pk_bf16_f32 v12, v12, v13
	v_cvt_pk_bf16_f32 v13, v14, v15
	global_store_dwordx2 v97, v[12:13], s[100:101] offset:1536
	s_add_u32 s98, s98, 0x800
	s_sub_u32 s99, s98, 0x2000
	s_lshr_b32 s99, s99, 11
	s_add_u32 s99, s99, 1
	s_cmp_lt_u32 s98, 0x2000
	s_cmov_b32 s99, 0
	s_mul_i32 s99, s99, 0x6000
	s_add_u32 s99, s99, 0x3444000
	s_add_u32 s100, s90, s99
	s_addc_u32 s101, s91, 0
	global_load_dwordx4 v[48:51], v96, s[100:101] offset:0
	global_load_dwordx4 v[52:55], v96, s[100:101] offset:1024
	global_load_dwordx4 v[56:59], v96, s[100:101] offset:2048
	global_load_dwordx4 v[60:63], v96, s[100:101] offset:3072
	s_sub_u32 s99, s98, 0x2000
	s_lshr_b32 s99, s99, 11
	s_add_u32 s99, s99, 1
	s_cmp_lt_u32 s98, 0x2000
	s_cmov_b32 s99, 0
	s_mul_i32 s99, s99, 0x6000
	s_add_u32 s99, s99, 0x3443000
	s_add_u32 s100, s90, s99
	s_addc_u32 s101, s91, 0
	global_load_dwordx4 v[64:67], v96, s[100:101] offset:0
	global_load_dwordx4 v[68:71], v96, s[100:101] offset:1024
	global_load_dwordx4 v[72:75], v96, s[100:101] offset:2048
	global_load_dwordx4 v[76:79], v96, s[100:101] offset:3072
	s_waitcnt vmcnt(12)
	v_mul_f32_e32 v80, v17, v17
	v_mul_f32_e32 v81, v21, v21
	v_mul_f32_e32 v82, v25, v25
	v_mul_f32_e32 v83, v29, v29
	v_fmac_f32_e32 v80, v16, v16
	v_fmac_f32_e32 v81, v20, v20
	v_fmac_f32_e32 v82, v24, v24
	v_fmac_f32_e32 v83, v28, v28
	v_fmac_f32_e32 v80, v18, v18
	v_fmac_f32_e32 v81, v22, v22
	v_fmac_f32_e32 v82, v26, v26
	v_fmac_f32_e32 v83, v30, v30
	v_fmac_f32_e32 v80, v19, v19
	v_fmac_f32_e32 v81, v23, v23
	v_fmac_f32_e32 v82, v27, v27
	v_fmac_f32_e32 v83, v31, v31
	v_add_f32_e32 v84, v80, v81
	v_add_f32_e32 v84, v84, v82
	v_add_f32_e32 v84, v84, v83
	ds_bpermute_b32 v85, v98, v84
	s_waitcnt lgkmcnt(0)
	v_add_f32_e32 v84, v84, v85
	ds_bpermute_b32 v85, v99, v84
	s_waitcnt lgkmcnt(0)
	v_add_f32_e32 v84, v84, v85
	ds_bpermute_b32 v85, v100, v84
	s_waitcnt lgkmcnt(0)
	v_add_f32_e32 v84, v84, v85
	ds_bpermute_b32 v85, v101, v84
	s_waitcnt lgkmcnt(0)
	v_add_f32_e32 v84, v84, v85
	ds_bpermute_b32 v85, v102, v84
	s_waitcnt lgkmcnt(0)
	v_add_f32_e32 v84, v84, v85
	ds_bpermute_b32 v85, v103, v84
	s_waitcnt lgkmcnt(0)
	v_add_f32_e32 v84, v84, v85
	v_fmamk_f32 v84, v84, 0x3a800000, v104
	v_mul_f32_e32 v85, 0x4b800000, v84
	v_cmp_gt_f32_e32 vcc, 0x800000, v84
	s_nop 1
	v_cndmask_b32_e32 v84, v84, v85, vcc
	v_rsq_f32_e32 v84, v84
	s_nop 0
	v_mul_f32_e32 v85, 0x45800000, v84
	v_cndmask_b32_e32 v106, v84, v85, vcc
	s_waitcnt vmcnt(0)
	s_lshl_b32 s99, s98, 11
	s_add_u32 s99, s99, 0xb171900
	s_add_u32 s100, s90, s99
	s_addc_u32 s101, s91, 0
	v_pk_mul_f32 v[16:17], v[16:17], v[106:107] op_sel_hi:[1,0]
	v_pk_mul_f32 v[18:19], v[18:19], v[106:107] op_sel_hi:[1,0]
	v_pk_mul_f32 v[16:17], v[32:33], v[16:17]
	v_pk_mul_f32 v[18:19], v[34:35], v[18:19]
	v_pk_add_f32 v[48:49], v[48:49], 1.0 op_sel_hi:[1,0]
	v_pk_add_f32 v[50:51], v[50:51], 1.0 op_sel_hi:[1,0]
	v_pk_fma_f32 v[16:17], v[48:49], v[16:17], v[64:65]
	v_pk_fma_f32 v[18:19], v[50:51], v[18:19], v[66:67]
	v_cvt_pk_bf16_f32 v16, v16, v17
	v_cvt_pk_bf16_f32 v17, v18, v19
	global_store_dwordx2 v97, v[16:17], s[100:101] offset:0
	v_pk_mul_f32 v[20:21], v[20:21], v[106:107] op_sel_hi:[1,0]
	v_pk_mul_f32 v[22:23], v[22:23], v[106:107] op_sel_hi:[1,0]
	v_pk_mul_f32 v[20:21], v[36:37], v[20:21]
	v_pk_mul_f32 v[22:23], v[38:39], v[22:23]
	v_pk_add_f32 v[52:53], v[52:53], 1.0 op_sel_hi:[1,0]
	v_pk_add_f32 v[54:55], v[54:55], 1.0 op_sel_hi:[1,0]
	v_pk_fma_f32 v[20:21], v[52:53], v[20:21], v[68:69]
	v_pk_fma_f32 v[22:23], v[54:55], v[22:23], v[70:71]
	v_cvt_pk_bf16_f32 v20, v20, v21
	v_cvt_pk_bf16_f32 v21, v22, v23
	global_store_dwordx2 v97, v[20:21], s[100:101] offset:512
	v_pk_mul_f32 v[24:25], v[24:25], v[106:107] op_sel_hi:[1,0]
	v_pk_mul_f32 v[26:27], v[26:27], v[106:107] op_sel_hi:[1,0]
	v_pk_mul_f32 v[24:25], v[40:41], v[24:25]
	v_pk_mul_f32 v[26:27], v[42:43], v[26:27]
	v_pk_add_f32 v[56:57], v[56:57], 1.0 op_sel_hi:[1,0]
	v_pk_add_f32 v[58:59], v[58:59], 1.0 op_sel_hi:[1,0]
	v_pk_fma_f32 v[24:25], v[56:57], v[24:25], v[72:73]
	v_pk_fma_f32 v[26:27], v[58:59], v[26:27], v[74:75]
	v_cvt_pk_bf16_f32 v24, v24, v25
	v_cvt_pk_bf16_f32 v25, v26, v27
	global_store_dwordx2 v97, v[24:25], s[100:101] offset:1024
	v_pk_mul_f32 v[28:29], v[28:29], v[106:107] op_sel_hi:[1,0]
	v_pk_mul_f32 v[30:31], v[30:31], v[106:107] op_sel_hi:[1,0]
	v_pk_mul_f32 v[28:29], v[44:45], v[28:29]
	v_pk_mul_f32 v[30:31], v[46:47], v[30:31]
	v_pk_add_f32 v[60:61], v[60:61], 1.0 op_sel_hi:[1,0]
	v_pk_add_f32 v[62:63], v[62:63], 1.0 op_sel_hi:[1,0]
	v_pk_fma_f32 v[28:29], v[60:61], v[28:29], v[76:77]
	v_pk_fma_f32 v[30:31], v[62:63], v[30:31], v[78:79]
	v_cvt_pk_bf16_f32 v28, v28, v29
	v_cvt_pk_bf16_f32 v29, v30, v31
	global_store_dwordx2 v97, v[28:29], s[100:101] offset:1536

.LBB0_1448:
	s_or_b64 exec, exec, s[0:1]
	s_add_u32 s24, s90, 0x3452000
	s_addc_u32 s25, s91, 0
	s_waitcnt lgkmcnt(0)
	s_barrier
	s_and_saveexec_b64 s[2:3], s[78:79]
	s_cbranch_execz .LBB0_1455
	v_mbcnt_hi_u32_b32 v0, -1, v182
	v_and_b32_e32 v2, 64, v0
	v_add_u32_e32 v2, 64, v2
	v_xor_b32_e32 v3, 32, v0
	v_cmp_lt_i32_e32 vcc, v3, v2
	v_readlane_b32 s44, v250, 3
	v_readlane_b32 s52, v250, 11
	v_cndmask_b32_e32 v3, v0, v3, vcc
	v_lshlrev_b32_e32 v24, 2, v3
	v_xor_b32_e32 v3, 16, v0
	v_cmp_lt_i32_e32 vcc, v3, v2
	v_readlane_b32 s53, v250, 12
	v_readlane_b32 s54, v250, 13
	v_cndmask_b32_e32 v3, v0, v3, vcc
	v_lshlrev_b32_e32 v25, 2, v3
	v_xor_b32_e32 v3, 8, v0
	v_cmp_lt_i32_e32 vcc, v3, v2
	v_readlane_b32 s55, v250, 14
	s_mov_b64 s[8:9], s[52:53]
	v_cndmask_b32_e32 v3, v0, v3, vcc
	v_lshlrev_b32_e32 v26, 2, v3
	v_xor_b32_e32 v3, 4, v0
	v_cmp_lt_i32_e32 vcc, v3, v2
	s_add_u32 s0, s8, 0x1000
	v_and_b32_e32 v12, 0xfc, v149
	v_cndmask_b32_e32 v3, v0, v3, vcc
	v_lshlrev_b32_e32 v27, 2, v3
	v_xor_b32_e32 v3, 2, v0
	v_cmp_lt_i32_e32 vcc, v3, v2
	s_addc_u32 s1, s9, 0
	v_mov_b32_e32 v1, 0
	v_cndmask_b32_e32 v3, v0, v3, vcc
	v_lshlrev_b32_e32 v28, 2, v3
	v_xor_b32_e32 v3, 1, v0
	v_cmp_lt_i32_e32 vcc, v3, v2
	v_or_b32_e32 v14, 0x100, v12
	v_or_b32_e32 v16, 0x200, v12
	v_cndmask_b32_e32 v0, v0, v3, vcc
	v_lshlrev_b32_e32 v29, 2, v0
	v_lshlrev_b32_e32 v0, 2, v12
	v_lshl_add_u64 v[2:3], s[0:1], 0, v[0:1]
	v_lshlrev_b32_e32 v0, 2, v14
	v_lshl_add_u64 v[4:5], s[0:1], 0, v[0:1]
	v_lshlrev_b32_e32 v0, 2, v16
	s_waitcnt vmcnt(1)
	v_or_b32_e32 v18, 0x300, v12
	v_lshl_add_u64 v[6:7], s[0:1], 0, v[0:1]
	v_lshlrev_b32_e32 v0, 2, v18
	v_lshl_add_u64 v[8:9], s[0:1], 0, v[0:1]
	v_readlane_b32 s0, v250, 19
	s_mov_b64 s[10:11], s[54:55]
	v_lshlrev_b32_e32 v0, 1, v12
	v_readlane_b32 s1, v250, 20
	s_mov_b64 s[6:7], 0x1000
	s_lshl_b32 s10, s92, 2
	v_lshl_add_u64 v[10:11], s[0:1], 0, v[0:1]
	s_mov_b64 s[8:9], 0
	s_movk_i32 s11, 0x2000
	s_movk_i32 s12, 0x1fff
	v_lshlrev_b32_e32 v12, 2, v12
	v_mov_b32_e32 v13, v1
	s_movk_i32 s13, 0x1800
	v_lshlrev_b32_e32 v14, 2, v14
	v_mov_b32_e32 v15, v1
	v_lshlrev_b32_e32 v16, 2, v16
	v_mov_b32_e32 v17, v1
	v_lshlrev_b32_e32 v18, 2, v18
	v_mov_b32_e32 v19, v1
	v_mov_b32_e32 v30, 0x358637bd
	s_mov_b32 s14, 0x800000
	s_movk_i32 s15, 0x2fff
	s_waitcnt vmcnt(0)
	v_mov_b32_e32 v20, v148
	v_readlane_b32 s45, v250, 4
	v_readlane_b32 s46, v250, 5
	v_readlane_b32 s47, v250, 6
	v_readlane_b32 s48, v250, 7
	v_readlane_b32 s49, v250, 8
	v_readlane_b32 s50, v250, 9
	v_readlane_b32 s51, v250, 10
	v_readlane_b32 s56, v250, 15
	v_readlane_b32 s57, v250, 16
	v_readlane_b32 s58, v250, 17
	v_readlane_b32 s59, v250, 18
	v_mbcnt_lo_u32_b32 v80, -1, 0
	v_mbcnt_hi_u32_b32 v80, -1, v80
	v_lshlrev_b32_e32 v96, 4, v80
	v_lshlrev_b32_e32 v97, 3, v80
	v_xor_b32_e32 v98, 32, v80
	v_lshlrev_b32_e32 v98, 2, v98
	v_xor_b32_e32 v99, 16, v80
	v_lshlrev_b32_e32 v99, 2, v99
	v_xor_b32_e32 v100, 8, v80
	v_lshlrev_b32_e32 v100, 2, v100
	v_xor_b32_e32 v101, 4, v80
	v_lshlrev_b32_e32 v101, 2, v101
	v_xor_b32_e32 v102, 2, v80
	v_lshlrev_b32_e32 v102, 2, v102
	v_xor_b32_e32 v103, 1, v80
	v_lshlrev_b32_e32 v103, 2, v103
	v_mov_b32_e32 v104, 0x358637bd
	v_mov_b32_e32 v107, 0
	v_readlane_b32 s100, v250, 11
	v_readlane_b32 s101, v250, 12
	s_nop 5
	s_add_u32 s100, s100, 0x1000
	s_addc_u32 s101, s101, 0
	global_load_dwordx4 v[32:35], v96, s[100:101] offset:0
	global_load_dwordx4 v[36:39], v96, s[100:101] offset:1024
	global_load_dwordx4 v[40:43], v96, s[100:101] offset:2048
	global_load_dwordx4 v[44:47], v96, s[100:101] offset:3072
	v_readfirstlane_b32 s98, v148
	s_nop 3
	s_lshl_b32 s99, s98, 12
	s_add_u32 s100, s88, s99
	s_addc_u32 s101, s89, 0
	global_load_dwordx4 v[0:3], v96, s[100:101] offset:0
	global_load_dwordx4 v[4:7], v96, s[100:101] offset:1024
	global_load_dwordx4 v[8:11], v96, s[100:101] offset:2048
	global_load_dwordx4 v[12:15], v96, s[100:101] offset:3072
	s_sub_u32 s99, s98, 0x2000
	s_lshr_b32 s99, s99, 11
	s_add_u32 s99, s99, 1
	s_cmp_lt_u32 s98, 0x2000
	s_cmov_b32 s99, 0
	s_mul_i32 s99, s99, 0x6000
	s_add_u32 s99, s99, 0x3453000
	s_add_u32 s100, s90, s99
	s_addc_u32 s101, s91, 0
	global_load_dwordx4 v[48:51], v96, s[100:101] offset:0
	global_load_dwordx4 v[52:55], v96, s[100:101] offset:1024
	global_load_dwordx4 v[56:59], v96, s[100:101] offset:2048
	global_load_dwordx4 v[60:63], v96, s[100:101] offset:3072
	s_sub_u32 s99, s98, 0x2000
	s_lshr_b32 s99, s99, 11
	s_add_u32 s99, s99, 1
	s_cmp_lt_u32 s98, 0x2000
	s_cmov_b32 s99, 0
	s_mul_i32 s99, s99, 0x6000
	s_add_u32 s99, s99, 0x3452000
	s_add_u32 s100, s90, s99
	s_addc_u32 s101, s91, 0
	global_load_dwordx4 v[64:67], v96, s[100:101] offset:0
	global_load_dwordx4 v[68:71], v96, s[100:101] offset:1024
	global_load_dwordx4 v[72:75], v96, s[100:101] offset:2048
	global_load_dwordx4 v[76:79], v96, s[100:101] offset:3072
	s_add_u32 s98, s98, 0x800
	s_lshl_b32 s99, s98, 12
	s_add_u32 s100, s88, s99
	s_addc_u32 s101, s89, 0
	global_load_dwordx4 v[16:19], v96, s[100:101] offset:0
	global_load_dwordx4 v[20:23], v96, s[100:101] offset:1024
	global_load_dwordx4 v[24:27], v96, s[100:101] offset:2048
	global_load_dwordx4 v[28:31], v96, s[100:101] offset:3072
	s_sub_u32 s98, s98, 0x800
	s_waitcnt vmcnt(12)
	v_mul_f32_e32 v80, v1, v1
	v_mul_f32_e32 v81, v5, v5
	v_mul_f32_e32 v82, v9, v9
	v_mul_f32_e32 v83, v13, v13
	v_fmac_f32_e32 v80, v0, v0
	v_fmac_f32_e32 v81, v4, v4
	v_fmac_f32_e32 v82, v8, v8
	v_fmac_f32_e32 v83, v12, v12
	v_fmac_f32_e32 v80, v2, v2
	v_fmac_f32_e32 v81, v6, v6
	v_fmac_f32_e32 v82, v10, v10
	v_fmac_f32_e32 v83, v14, v14
	v_fmac_f32_e32 v80, v3, v3
	v_fmac_f32_e32 v81, v7, v7
	v_fmac_f32_e32 v82, v11, v11
	v_fmac_f32_e32 v83, v15, v15
	v_add_f32_e32 v84, v80, v81
	v_add_f32_e32 v84, v84, v82
	v_add_f32_e32 v84, v84, v83
	ds_bpermute_b32 v85, v98, v84
	s_waitcnt lgkmcnt(0)
	v_add_f32_e32 v84, v84, v85
	ds_bpermute_b32 v85, v99, v84
	s_waitcnt lgkmcnt(0)
	v_add_f32_e32 v84, v84, v85
	ds_bpermute_b32 v85, v100, v84
	s_waitcnt lgkmcnt(0)
	v_add_f32_e32 v84, v84, v85
	ds_bpermute_b32 v85, v101, v84
	s_waitcnt lgkmcnt(0)
	v_add_f32_e32 v84, v84, v85
	ds_bpermute_b32 v85, v102, v84
	s_waitcnt lgkmcnt(0)
	v_add_f32_e32 v84, v84, v85
	ds_bpermute_b32 v85, v103, v84
	s_waitcnt lgkmcnt(0)
	v_add_f32_e32 v84, v84, v85
	v_fmamk_f32 v84, v84, 0x3a800000, v104
	v_mul_f32_e32 v85, 0x4b800000, v84
	v_cmp_gt_f32_e32 vcc, 0x800000, v84
	s_nop 1
	v_cndmask_b32_e32 v84, v84, v85, vcc
	v_rsq_f32_e32 v84, v84
	s_nop 0
	v_mul_f32_e32 v85, 0x45800000, v84
	v_cndmask_b32_e32 v106, v84, v85, vcc
	s_waitcnt vmcnt(4)
	s_lshl_b32 s99, s98, 11
	s_add_u32 s99, s99, 0xb171900
	s_add_u32 s100, s90, s99
	s_addc_u32 s101, s91, 0
	v_pk_mul_f32 v[0:1], v[0:1], v[106:107] op_sel_hi:[1,0]
	v_pk_mul_f32 v[2:3], v[2:3], v[106:107] op_sel_hi:[1,0]
	v_pk_mul_f32 v[0:1], v[32:33], v[0:1]
	v_pk_mul_f32 v[2:3], v[34:35], v[2:3]
	v_pk_add_f32 v[48:49], v[48:49], 1.0 op_sel_hi:[1,0]
	v_pk_add_f32 v[50:51], v[50:51], 1.0 op_sel_hi:[1,0]
	v_pk_fma_f32 v[0:1], v[48:49], v[0:1], v[64:65]
	v_pk_fma_f32 v[2:3], v[50:51], v[2:3], v[66:67]
	v_cvt_pk_bf16_f32 v0, v0, v1
	v_cvt_pk_bf16_f32 v1, v2, v3
	global_store_dwordx2 v97, v[0:1], s[100:101] offset:0
	v_pk_mul_f32 v[4:5], v[4:5], v[106:107] op_sel_hi:[1,0]
	v_pk_mul_f32 v[6:7], v[6:7], v[106:107] op_sel_hi:[1,0]
	v_pk_mul_f32 v[4:5], v[36:37], v[4:5]
	v_pk_mul_f32 v[6:7], v[38:39], v[6:7]
	v_pk_add_f32 v[52:53], v[52:53], 1.0 op_sel_hi:[1,0]
	v_pk_add_f32 v[54:55], v[54:55], 1.0 op_sel_hi:[1,0]
	v_pk_fma_f32 v[4:5], v[52:53], v[4:5], v[68:69]
	v_pk_fma_f32 v[6:7], v[54:55], v[6:7], v[70:71]
	v_cvt_pk_bf16_f32 v4, v4, v5
	v_cvt_pk_bf16_f32 v5, v6, v7
	global_store_dwordx2 v97, v[4:5], s[100:101] offset:512
	v_pk_mul_f32 v[8:9], v[8:9], v[106:107] op_sel_hi:[1,0]
	v_pk_mul_f32 v[10:11], v[10:11], v[106:107] op_sel_hi:[1,0]
	v_pk_mul_f32 v[8:9], v[40:41], v[8:9]
	v_pk_mul_f32 v[10:11], v[42:43], v[10:11]
	v_pk_add_f32 v[56:57], v[56:57], 1.0 op_sel_hi:[1,0]
	v_pk_add_f32 v[58:59], v[58:59], 1.0 op_sel_hi:[1,0]
	v_pk_fma_f32 v[8:9], v[56:57], v[8:9], v[72:73]
	v_pk_fma_f32 v[10:11], v[58:59], v[10:11], v[74:75]
	v_cvt_pk_bf16_f32 v8, v8, v9
	v_cvt_pk_bf16_f32 v9, v10, v11
	global_store_dwordx2 v97, v[8:9], s[100:101] offset:1024
	v_pk_mul_f32 v[12:13], v[12:13], v[106:107] op_sel_hi:[1,0]
	v_pk_mul_f32 v[14:15], v[14:15], v[106:107] op_sel_hi:[1,0]
	v_pk_mul_f32 v[12:13], v[44:45], v[12:13]
	v_pk_mul_f32 v[14:15], v[46:47], v[14:15]
	v_pk_add_f32 v[60:61], v[60:61], 1.0 op_sel_hi:[1,0]
	v_pk_add_f32 v[62:63], v[62:63], 1.0 op_sel_hi:[1,0]
	v_pk_fma_f32 v[12:13], v[60:61], v[12:13], v[76:77]
	v_pk_fma_f32 v[14:15], v[62:63], v[14:15], v[78:79]
	v_cvt_pk_bf16_f32 v12, v12, v13
	v_cvt_pk_bf16_f32 v13, v14, v15
	global_store_dwordx2 v97, v[12:13], s[100:101] offset:1536
	s_add_u32 s98, s98, 0x800
	s_sub_u32 s99, s98, 0x2000
	s_lshr_b32 s99, s99, 11
	s_add_u32 s99, s99, 1
	s_cmp_lt_u32 s98, 0x2000
	s_cmov_b32 s99, 0
	s_mul_i32 s99, s99, 0x6000
	s_add_u32 s99, s99, 0x3453000
	s_add_u32 s100, s90, s99
	s_addc_u32 s101, s91, 0
	global_load_dwordx4 v[48:51], v96, s[100:101] offset:0
	global_load_dwordx4 v[52:55], v96, s[100:101] offset:1024
	global_load_dwordx4 v[56:59], v96, s[100:101] offset:2048
	global_load_dwordx4 v[60:63], v96, s[100:101] offset:3072
	s_sub_u32 s99, s98, 0x2000
	s_lshr_b32 s99, s99, 11
	s_add_u32 s99, s99, 1
	s_cmp_lt_u32 s98, 0x2000
	s_cmov_b32 s99, 0
	s_mul_i32 s99, s99, 0x6000
	s_add_u32 s99, s99, 0x3452000
	s_add_u32 s100, s90, s99
	s_addc_u32 s101, s91, 0
	global_load_dwordx4 v[64:67], v96, s[100:101] offset:0
	global_load_dwordx4 v[68:71], v96, s[100:101] offset:1024
	global_load_dwordx4 v[72:75], v96, s[100:101] offset:2048
	global_load_dwordx4 v[76:79], v96, s[100:101] offset:3072
	s_add_u32 s98, s98, 0x800
	s_lshl_b32 s99, s98, 12
	s_add_u32 s100, s88, s99
	s_addc_u32 s101, s89, 0
	global_load_dwordx4 v[0:3], v96, s[100:101] offset:0
	global_load_dwordx4 v[4:7], v96, s[100:101] offset:1024
	global_load_dwordx4 v[8:11], v96, s[100:101] offset:2048
	global_load_dwordx4 v[12:15], v96, s[100:101] offset:3072
	s_sub_u32 s98, s98, 0x800
	s_waitcnt vmcnt(16)
	v_mul_f32_e32 v80, v17, v17
	v_mul_f32_e32 v81, v21, v21
	v_mul_f32_e32 v82, v25, v25
	v_mul_f32_e32 v83, v29, v29
	v_fmac_f32_e32 v80, v16, v16
	v_fmac_f32_e32 v81, v20, v20
	v_fmac_f32_e32 v82, v24, v24
	v_fmac_f32_e32 v83, v28, v28
	v_fmac_f32_e32 v80, v18, v18
	v_fmac_f32_e32 v81, v22, v22
	v_fmac_f32_e32 v82, v26, v26
	v_fmac_f32_e32 v83, v30, v30
	v_fmac_f32_e32 v80, v19, v19
	v_fmac_f32_e32 v81, v23, v23
	v_fmac_f32_e32 v82, v27, v27
	v_fmac_f32_e32 v83, v31, v31
	v_add_f32_e32 v84, v80, v81
	v_add_f32_e32 v84, v84, v82
	v_add_f32_e32 v84, v84, v83
	ds_bpermute_b32 v85, v98, v84
	s_waitcnt lgkmcnt(0)
	v_add_f32_e32 v84, v84, v85
	ds_bpermute_b32 v85, v99, v84
	s_waitcnt lgkmcnt(0)
	v_add_f32_e32 v84, v84, v85
	ds_bpermute_b32 v85, v100, v84
	s_waitcnt lgkmcnt(0)
	v_add_f32_e32 v84, v84, v85
	ds_bpermute_b32 v85, v101, v84
	s_waitcnt lgkmcnt(0)
	v_add_f32_e32 v84, v84, v85
	ds_bpermute_b32 v85, v102, v84
	s_waitcnt lgkmcnt(0)
	v_add_f32_e32 v84, v84, v85
	ds_bpermute_b32 v85, v103, v84
	s_waitcnt lgkmcnt(0)
	v_add_f32_e32 v84, v84, v85
	v_fmamk_f32 v84, v84, 0x3a800000, v104
	v_mul_f32_e32 v85, 0x4b800000, v84
	v_cmp_gt_f32_e32 vcc, 0x800000, v84
	s_nop 1
	v_cndmask_b32_e32 v84, v84, v85, vcc
	v_rsq_f32_e32 v84, v84
	s_nop 0
	v_mul_f32_e32 v85, 0x45800000, v84
	v_cndmask_b32_e32 v106, v84, v85, vcc
	s_waitcnt vmcnt(4)
	s_lshl_b32 s99, s98, 11
	s_add_u32 s99, s99, 0xb171900
	s_add_u32 s100, s90, s99
	s_addc_u32 s101, s91, 0
	v_pk_mul_f32 v[16:17], v[16:17], v[106:107] op_sel_hi:[1,0]
	v_pk_mul_f32 v[18:19], v[18:19], v[106:107] op_sel_hi:[1,0]
	v_pk_mul_f32 v[16:17], v[32:33], v[16:17]
	v_pk_mul_f32 v[18:19], v[34:35], v[18:19]
	v_pk_add_f32 v[48:49], v[48:49], 1.0 op_sel_hi:[1,0]
	v_pk_add_f32 v[50:51], v[50:51], 1.0 op_sel_hi:[1,0]
	v_pk_fma_f32 v[16:17], v[48:49], v[16:17], v[64:65]
	v_pk_fma_f32 v[18:19], v[50:51], v[18:19], v[66:67]
	v_cvt_pk_bf16_f32 v16, v16, v17
	v_cvt_pk_bf16_f32 v17, v18, v19
	global_store_dwordx2 v97, v[16:17], s[100:101] offset:0
	v_pk_mul_f32 v[20:21], v[20:21], v[106:107] op_sel_hi:[1,0]
	v_pk_mul_f32 v[22:23], v[22:23], v[106:107] op_sel_hi:[1,0]
	v_pk_mul_f32 v[20:21], v[36:37], v[20:21]
	v_pk_mul_f32 v[22:23], v[38:39], v[22:23]
	v_pk_add_f32 v[52:53], v[52:53], 1.0 op_sel_hi:[1,0]
	v_pk_add_f32 v[54:55], v[54:55], 1.0 op_sel_hi:[1,0]
	v_pk_fma_f32 v[20:21], v[52:53], v[20:21], v[68:69]
	v_pk_fma_f32 v[22:23], v[54:55], v[22:23], v[70:71]
	v_cvt_pk_bf16_f32 v20, v20, v21
	v_cvt_pk_bf16_f32 v21, v22, v23
	global_store_dwordx2 v97, v[20:21], s[100:101] offset:512
	v_pk_mul_f32 v[24:25], v[24:25], v[106:107] op_sel_hi:[1,0]
	v_pk_mul_f32 v[26:27], v[26:27], v[106:107] op_sel_hi:[1,0]
	v_pk_mul_f32 v[24:25], v[40:41], v[24:25]
	v_pk_mul_f32 v[26:27], v[42:43], v[26:27]
	v_pk_add_f32 v[56:57], v[56:57], 1.0 op_sel_hi:[1,0]
	v_pk_add_f32 v[58:59], v[58:59], 1.0 op_sel_hi:[1,0]
	v_pk_fma_f32 v[24:25], v[56:57], v[24:25], v[72:73]
	v_pk_fma_f32 v[26:27], v[58:59], v[26:27], v[74:75]
	v_cvt_pk_bf16_f32 v24, v24, v25
	v_cvt_pk_bf16_f32 v25, v26, v27
	global_store_dwordx2 v97, v[24:25], s[100:101] offset:1024
	v_pk_mul_f32 v[28:29], v[28:29], v[106:107] op_sel_hi:[1,0]
	v_pk_mul_f32 v[30:31], v[30:31], v[106:107] op_sel_hi:[1,0]
	v_pk_mul_f32 v[28:29], v[44:45], v[28:29]
	v_pk_mul_f32 v[30:31], v[46:47], v[30:31]
	v_pk_add_f32 v[60:61], v[60:61], 1.0 op_sel_hi:[1,0]
	v_pk_add_f32 v[62:63], v[62:63], 1.0 op_sel_hi:[1,0]
	v_pk_fma_f32 v[28:29], v[60:61], v[28:29], v[76:77]
	v_pk_fma_f32 v[30:31], v[62:63], v[30:31], v[78:79]
	v_cvt_pk_bf16_f32 v28, v28, v29
	v_cvt_pk_bf16_f32 v29, v30, v31
	global_store_dwordx2 v97, v[28:29], s[100:101] offset:1536
	s_add_u32 s98, s98, 0x800
	s_sub_u32 s99, s98, 0x2000
	s_lshr_b32 s99, s99, 11
	s_add_u32 s99, s99, 1
	s_cmp_lt_u32 s98, 0x2000
	s_cmov_b32 s99, 0
	s_mul_i32 s99, s99, 0x6000
	s_add_u32 s99, s99, 0x3453000
	s_add_u32 s100, s90, s99
	s_addc_u32 s101, s91, 0
	global_load_dwordx4 v[48:51], v96, s[100:101] offset:0
	global_load_dwordx4 v[52:55], v96, s[100:101] offset:1024
	global_load_dwordx4 v[56:59], v96, s[100:101] offset:2048
	global_load_dwordx4 v[60:63], v96, s[100:101] offset:3072
	s_sub_u32 s99, s98, 0x2000
	s_lshr_b32 s99, s99, 11
	s_add_u32 s99, s99, 1
	s_cmp_lt_u32 s98, 0x2000
	s_cmov_b32 s99, 0
	s_mul_i32 s99, s99, 0x6000
	s_add_u32 s99, s99, 0x3452000
	s_add_u32 s100, s90, s99
	s_addc_u32 s101, s91, 0
	global_load_dwordx4 v[64:67], v96, s[100:101] offset:0
	global_load_dwordx4 v[68:71], v96, s[100:101] offset:1024
	global_load_dwordx4 v[72:75], v96, s[100:101] offset:2048
	global_load_dwordx4 v[76:79], v96, s[100:101] offset:3072
	s_add_u32 s98, s98, 0x800
	s_lshl_b32 s99, s98, 12
	s_add_u32 s100, s88, s99
	s_addc_u32 s101, s89, 0
	global_load_dwordx4 v[16:19], v96, s[100:101] offset:0
	global_load_dwordx4 v[20:23], v96, s[100:101] offset:1024
	global_load_dwordx4 v[24:27], v96, s[100:101] offset:2048
	global_load_dwordx4 v[28:31], v96, s[100:101] offset:3072
	s_sub_u32 s98, s98, 0x800
	s_waitcnt vmcnt(16)
	v_mul_f32_e32 v80, v1, v1
	v_mul_f32_e32 v81, v5, v5
	v_mul_f32_e32 v82, v9, v9
	v_mul_f32_e32 v83, v13, v13
	v_fmac_f32_e32 v80, v0, v0
	v_fmac_f32_e32 v81, v4, v4
	v_fmac_f32_e32 v82, v8, v8
	v_fmac_f32_e32 v83, v12, v12
	v_fmac_f32_e32 v80, v2, v2
	v_fmac_f32_e32 v81, v6, v6
	v_fmac_f32_e32 v82, v10, v10
	v_fmac_f32_e32 v83, v14, v14
	v_fmac_f32_e32 v80, v3, v3
	v_fmac_f32_e32 v81, v7, v7
	v_fmac_f32_e32 v82, v11, v11
	v_fmac_f32_e32 v83, v15, v15
	v_add_f32_e32 v84, v80, v81
	v_add_f32_e32 v84, v84, v82
	v_add_f32_e32 v84, v84, v83
	ds_bpermute_b32 v85, v98, v84
	s_waitcnt lgkmcnt(0)
	v_add_f32_e32 v84, v84, v85
	ds_bpermute_b32 v85, v99, v84
	s_waitcnt lgkmcnt(0)
	v_add_f32_e32 v84, v84, v85
	ds_bpermute_b32 v85, v100, v84
	s_waitcnt lgkmcnt(0)
	v_add_f32_e32 v84, v84, v85
	ds_bpermute_b32 v85, v101, v84
	s_waitcnt lgkmcnt(0)
	v_add_f32_e32 v84, v84, v85
	ds_bpermute_b32 v85, v102, v84
	s_waitcnt lgkmcnt(0)
	v_add_f32_e32 v84, v84, v85
	ds_bpermute_b32 v85, v103, v84
	s_waitcnt lgkmcnt(0)
	v_add_f32_e32 v84, v84, v85
	v_fmamk_f32 v84, v84, 0x3a800000, v104
	v_mul_f32_e32 v85, 0x4b800000, v84
	v_cmp_gt_f32_e32 vcc, 0x800000, v84
	s_nop 1
	v_cndmask_b32_e32 v84, v84, v85, vcc
	v_rsq_f32_e32 v84, v84
	s_nop 0
	v_mul_f32_e32 v85, 0x45800000, v84
	v_cndmask_b32_e32 v106, v84, v85, vcc
	s_waitcnt vmcnt(4)
	s_lshl_b32 s99, s98, 11
	s_add_u32 s99, s99, 0xb171900
	s_add_u32 s100, s90, s99
	s_addc_u32 s101, s91, 0
	v_pk_mul_f32 v[0:1], v[0:1], v[106:107] op_sel_hi:[1,0]
	v_pk_mul_f32 v[2:3], v[2:3], v[106:107] op_sel_hi:[1,0]
	v_pk_mul_f32 v[0:1], v[32:33], v[0:1]
	v_pk_mul_f32 v[2:3], v[34:35], v[2:3]
	v_pk_add_f32 v[48:49], v[48:49], 1.0 op_sel_hi:[1,0]
	v_pk_add_f32 v[50:51], v[50:51], 1.0 op_sel_hi:[1,0]
	v_pk_fma_f32 v[0:1], v[48:49], v[0:1], v[64:65]
	v_pk_fma_f32 v[2:3], v[50:51], v[2:3], v[66:67]
	v_cvt_pk_bf16_f32 v0, v0, v1
	v_cvt_pk_bf16_f32 v1, v2, v3
	global_store_dwordx2 v97, v[0:1], s[100:101] offset:0
	v_pk_mul_f32 v[4:5], v[4:5], v[106:107] op_sel_hi:[1,0]
	v_pk_mul_f32 v[6:7], v[6:7], v[106:107] op_sel_hi:[1,0]
	v_pk_mul_f32 v[4:5], v[36:37], v[4:5]
	v_pk_mul_f32 v[6:7], v[38:39], v[6:7]
	v_pk_add_f32 v[52:53], v[52:53], 1.0 op_sel_hi:[1,0]
	v_pk_add_f32 v[54:55], v[54:55], 1.0 op_sel_hi:[1,0]
	v_pk_fma_f32 v[4:5], v[52:53], v[4:5], v[68:69]
	v_pk_fma_f32 v[6:7], v[54:55], v[6:7], v[70:71]
	v_cvt_pk_bf16_f32 v4, v4, v5
	v_cvt_pk_bf16_f32 v5, v6, v7
	global_store_dwordx2 v97, v[4:5], s[100:101] offset:512
	v_pk_mul_f32 v[8:9], v[8:9], v[106:107] op_sel_hi:[1,0]
	v_pk_mul_f32 v[10:11], v[10:11], v[106:107] op_sel_hi:[1,0]
	v_pk_mul_f32 v[8:9], v[40:41], v[8:9]
	v_pk_mul_f32 v[10:11], v[42:43], v[10:11]
	v_pk_add_f32 v[56:57], v[56:57], 1.0 op_sel_hi:[1,0]
	v_pk_add_f32 v[58:59], v[58:59], 1.0 op_sel_hi:[1,0]
	v_pk_fma_f32 v[8:9], v[56:57], v[8:9], v[72:73]
	v_pk_fma_f32 v[10:11], v[58:59], v[10:11], v[74:75]
	v_cvt_pk_bf16_f32 v8, v8, v9
	v_cvt_pk_bf16_f32 v9, v10, v11
	global_store_dwordx2 v97, v[8:9], s[100:101] offset:1024
	v_pk_mul_f32 v[12:13], v[12:13], v[106:107] op_sel_hi:[1,0]
	v_pk_mul_f32 v[14:15], v[14:15], v[106:107] op_sel_hi:[1,0]
	v_pk_mul_f32 v[12:13], v[44:45], v[12:13]
	v_pk_mul_f32 v[14:15], v[46:47], v[14:15]
	v_pk_add_f32 v[60:61], v[60:61], 1.0 op_sel_hi:[1,0]
	v_pk_add_f32 v[62:63], v[62:63], 1.0 op_sel_hi:[1,0]
	v_pk_fma_f32 v[12:13], v[60:61], v[12:13], v[76:77]
	v_pk_fma_f32 v[14:15], v[62:63], v[14:15], v[78:79]
	v_cvt_pk_bf16_f32 v12, v12, v13
	v_cvt_pk_bf16_f32 v13, v14, v15
	global_store_dwordx2 v97, v[12:13], s[100:101] offset:1536
	s_add_u32 s98, s98, 0x800
	s_sub_u32 s99, s98, 0x2000
	s_lshr_b32 s99, s99, 11
	s_add_u32 s99, s99, 1
	s_cmp_lt_u32 s98, 0x2000
	s_cmov_b32 s99, 0
	s_mul_i32 s99, s99, 0x6000
	s_add_u32 s99, s99, 0x3453000
	s_add_u32 s100, s90, s99
	s_addc_u32 s101, s91, 0
	global_load_dwordx4 v[48:51], v96, s[100:101] offset:0
	global_load_dwordx4 v[52:55], v96, s[100:101] offset:1024
	global_load_dwordx4 v[56:59], v96, s[100:101] offset:2048
	global_load_dwordx4 v[60:63], v96, s[100:101] offset:3072
	s_sub_u32 s99, s98, 0x2000
	s_lshr_b32 s99, s99, 11
	s_add_u32 s99, s99, 1
	s_cmp_lt_u32 s98, 0x2000
	s_cmov_b32 s99, 0
	s_mul_i32 s99, s99, 0x6000
	s_add_u32 s99, s99, 0x3452000
	s_add_u32 s100, s90, s99
	s_addc_u32 s101, s91, 0
	global_load_dwordx4 v[64:67], v96, s[100:101] offset:0
	global_load_dwordx4 v[68:71], v96, s[100:101] offset:1024
	global_load_dwordx4 v[72:75], v96, s[100:101] offset:2048
	global_load_dwordx4 v[76:79], v96, s[100:101] offset:3072
	s_add_u32 s98, s98, 0x800
	s_lshl_b32 s99, s98, 12
	s_add_u32 s100, s88, s99
	s_addc_u32 s101, s89, 0
	global_load_dwordx4 v[0:3], v96, s[100:101] offset:0
	global_load_dwordx4 v[4:7], v96, s[100:101] offset:1024
	global_load_dwordx4 v[8:11], v96, s[100:101] offset:2048
	global_load_dwordx4 v[12:15], v96, s[100:101] offset:3072
	s_sub_u32 s98, s98, 0x800
	s_waitcnt vmcnt(16)
	v_mul_f32_e32 v80, v17, v17
	v_mul_f32_e32 v81, v21, v21
	v_mul_f32_e32 v82, v25, v25
	v_mul_f32_e32 v83, v29, v29
	v_fmac_f32_e32 v80, v16, v16
	v_fmac_f32_e32 v81, v20, v20
	v_fmac_f32_e32 v82, v24, v24
	v_fmac_f32_e32 v83, v28, v28
	v_fmac_f32_e32 v80, v18, v18
	v_fmac_f32_e32 v81, v22, v22
	v_fmac_f32_e32 v82, v26, v26
	v_fmac_f32_e32 v83, v30, v30
	v_fmac_f32_e32 v80, v19, v19
	v_fmac_f32_e32 v81, v23, v23
	v_fmac_f32_e32 v82, v27, v27
	v_fmac_f32_e32 v83, v31, v31
	v_add_f32_e32 v84, v80, v81
	v_add_f32_e32 v84, v84, v82
	v_add_f32_e32 v84, v84, v83
	ds_bpermute_b32 v85, v98, v84
	s_waitcnt lgkmcnt(0)
	v_add_f32_e32 v84, v84, v85
	ds_bpermute_b32 v85, v99, v84
	s_waitcnt lgkmcnt(0)
	v_add_f32_e32 v84, v84, v85
	ds_bpermute_b32 v85, v100, v84
	s_waitcnt lgkmcnt(0)
	v_add_f32_e32 v84, v84, v85
	ds_bpermute_b32 v85, v101, v84
	s_waitcnt lgkmcnt(0)
	v_add_f32_e32 v84, v84, v85
	ds_bpermute_b32 v85, v102, v84
	s_waitcnt lgkmcnt(0)
	v_add_f32_e32 v84, v84, v85
	ds_bpermute_b32 v85, v103, v84
	s_waitcnt lgkmcnt(0)
	v_add_f32_e32 v84, v84, v85
	v_fmamk_f32 v84, v84, 0x3a800000, v104
	v_mul_f32_e32 v85, 0x4b800000, v84
	v_cmp_gt_f32_e32 vcc, 0x800000, v84
	s_nop 1
	v_cndmask_b32_e32 v84, v84, v85, vcc
	v_rsq_f32_e32 v84, v84
	s_nop 0
	v_mul_f32_e32 v85, 0x45800000, v84
	v_cndmask_b32_e32 v106, v84, v85, vcc
	s_waitcnt vmcnt(4)
	s_lshl_b32 s99, s98, 11
	s_add_u32 s99, s99, 0xb171900
	s_add_u32 s100, s90, s99
	s_addc_u32 s101, s91, 0
	v_pk_mul_f32 v[16:17], v[16:17], v[106:107] op_sel_hi:[1,0]
	v_pk_mul_f32 v[18:19], v[18:19], v[106:107] op_sel_hi:[1,0]
	v_pk_mul_f32 v[16:17], v[32:33], v[16:17]
	v_pk_mul_f32 v[18:19], v[34:35], v[18:19]
	v_pk_add_f32 v[48:49], v[48:49], 1.0 op_sel_hi:[1,0]
	v_pk_add_f32 v[50:51], v[50:51], 1.0 op_sel_hi:[1,0]
	v_pk_fma_f32 v[16:17], v[48:49], v[16:17], v[64:65]
	v_pk_fma_f32 v[18:19], v[50:51], v[18:19], v[66:67]
	v_cvt_pk_bf16_f32 v16, v16, v17
	v_cvt_pk_bf16_f32 v17, v18, v19
	global_store_dwordx2 v97, v[16:17], s[100:101] offset:0
	v_pk_mul_f32 v[20:21], v[20:21], v[106:107] op_sel_hi:[1,0]
	v_pk_mul_f32 v[22:23], v[22:23], v[106:107] op_sel_hi:[1,0]
	v_pk_mul_f32 v[20:21], v[36:37], v[20:21]
	v_pk_mul_f32 v[22:23], v[38:39], v[22:23]
	v_pk_add_f32 v[52:53], v[52:53], 1.0 op_sel_hi:[1,0]
	v_pk_add_f32 v[54:55], v[54:55], 1.0 op_sel_hi:[1,0]
	v_pk_fma_f32 v[20:21], v[52:53], v[20:21], v[68:69]
	v_pk_fma_f32 v[22:23], v[54:55], v[22:23], v[70:71]
	v_cvt_pk_bf16_f32 v20, v20, v21
	v_cvt_pk_bf16_f32 v21, v22, v23
	global_store_dwordx2 v97, v[20:21], s[100:101] offset:512
	v_pk_mul_f32 v[24:25], v[24:25], v[106:107] op_sel_hi:[1,0]
	v_pk_mul_f32 v[26:27], v[26:27], v[106:107] op_sel_hi:[1,0]
	v_pk_mul_f32 v[24:25], v[40:41], v[24:25]
	v_pk_mul_f32 v[26:27], v[42:43], v[26:27]
	v_pk_add_f32 v[56:57], v[56:57], 1.0 op_sel_hi:[1,0]
	v_pk_add_f32 v[58:59], v[58:59], 1.0 op_sel_hi:[1,0]
	v_pk_fma_f32 v[24:25], v[56:57], v[24:25], v[72:73]
	v_pk_fma_f32 v[26:27], v[58:59], v[26:27], v[74:75]
	v_cvt_pk_bf16_f32 v24, v24, v25
	v_cvt_pk_bf16_f32 v25, v26, v27
	global_store_dwordx2 v97, v[24:25], s[100:101] offset:1024
	v_pk_mul_f32 v[28:29], v[28:29], v[106:107] op_sel_hi:[1,0]
	v_pk_mul_f32 v[30:31], v[30:31], v[106:107] op_sel_hi:[1,0]
	v_pk_mul_f32 v[28:29], v[44:45], v[28:29]
	v_pk_mul_f32 v[30:31], v[46:47], v[30:31]
	v_pk_add_f32 v[60:61], v[60:61], 1.0 op_sel_hi:[1,0]
	v_pk_add_f32 v[62:63], v[62:63], 1.0 op_sel_hi:[1,0]
	v_pk_fma_f32 v[28:29], v[60:61], v[28:29], v[76:77]
	v_pk_fma_f32 v[30:31], v[62:63], v[30:31], v[78:79]
	v_cvt_pk_bf16_f32 v28, v28, v29
	v_cvt_pk_bf16_f32 v29, v30, v31
	global_store_dwordx2 v97, v[28:29], s[100:101] offset:1536
	s_add_u32 s98, s98, 0x800
	s_sub_u32 s99, s98, 0x2000
	s_lshr_b32 s99, s99, 11
	s_add_u32 s99, s99, 1
	s_cmp_lt_u32 s98, 0x2000
	s_cmov_b32 s99, 0
	s_mul_i32 s99, s99, 0x6000
	s_add_u32 s99, s99, 0x3453000
	s_add_u32 s100, s90, s99
	s_addc_u32 s101, s91, 0
	global_load_dwordx4 v[48:51], v96, s[100:101] offset:0
	global_load_dwordx4 v[52:55], v96, s[100:101] offset:1024
	global_load_dwordx4 v[56:59], v96, s[100:101] offset:2048
	global_load_dwordx4 v[60:63], v96, s[100:101] offset:3072
	s_sub_u32 s99, s98, 0x2000
	s_lshr_b32 s99, s99, 11
	s_add_u32 s99, s99, 1
	s_cmp_lt_u32 s98, 0x2000
	s_cmov_b32 s99, 0
	s_mul_i32 s99, s99, 0x6000
	s_add_u32 s99, s99, 0x3452000
	s_add_u32 s100, s90, s99
	s_addc_u32 s101, s91, 0
	global_load_dwordx4 v[64:67], v96, s[100:101] offset:0
	global_load_dwordx4 v[68:71], v96, s[100:101] offset:1024
	global_load_dwordx4 v[72:75], v96, s[100:101] offset:2048
	global_load_dwordx4 v[76:79], v96, s[100:101] offset:3072
	s_add_u32 s98, s98, 0x800
	s_lshl_b32 s99, s98, 12
	s_add_u32 s100, s88, s99
	s_addc_u32 s101, s89, 0
	global_load_dwordx4 v[16:19], v96, s[100:101] offset:0
	global_load_dwordx4 v[20:23], v96, s[100:101] offset:1024
	global_load_dwordx4 v[24:27], v96, s[100:101] offset:2048
	global_load_dwordx4 v[28:31], v96, s[100:101] offset:3072
	s_sub_u32 s98, s98, 0x800
	s_waitcnt vmcnt(16)
	v_mul_f32_e32 v80, v1, v1
	v_mul_f32_e32 v81, v5, v5
	v_mul_f32_e32 v82, v9, v9
	v_mul_f32_e32 v83, v13, v13
	v_fmac_f32_e32 v80, v0, v0
	v_fmac_f32_e32 v81, v4, v4
	v_fmac_f32_e32 v82, v8, v8
	v_fmac_f32_e32 v83, v12, v12
	v_fmac_f32_e32 v80, v2, v2
	v_fmac_f32_e32 v81, v6, v6
	v_fmac_f32_e32 v82, v10, v10
	v_fmac_f32_e32 v83, v14, v14
	v_fmac_f32_e32 v80, v3, v3
	v_fmac_f32_e32 v81, v7, v7
	v_fmac_f32_e32 v82, v11, v11
	v_fmac_f32_e32 v83, v15, v15
	v_add_f32_e32 v84, v80, v81
	v_add_f32_e32 v84, v84, v82
	v_add_f32_e32 v84, v84, v83
	ds_bpermute_b32 v85, v98, v84
	s_waitcnt lgkmcnt(0)
	v_add_f32_e32 v84, v84, v85
	ds_bpermute_b32 v85, v99, v84
	s_waitcnt lgkmcnt(0)
	v_add_f32_e32 v84, v84, v85
	ds_bpermute_b32 v85, v100, v84
	s_waitcnt lgkmcnt(0)
	v_add_f32_e32 v84, v84, v85
	ds_bpermute_b32 v85, v101, v84
	s_waitcnt lgkmcnt(0)
	v_add_f32_e32 v84, v84, v85
	ds_bpermute_b32 v85, v102, v84
	s_waitcnt lgkmcnt(0)
	v_add_f32_e32 v84, v84, v85
	ds_bpermute_b32 v85, v103, v84
	s_waitcnt lgkmcnt(0)
	v_add_f32_e32 v84, v84, v85
	v_fmamk_f32 v84, v84, 0x3a800000, v104
	v_mul_f32_e32 v85, 0x4b800000, v84
	v_cmp_gt_f32_e32 vcc, 0x800000, v84
	s_nop 1
	v_cndmask_b32_e32 v84, v84, v85, vcc
	v_rsq_f32_e32 v84, v84
	s_nop 0
	v_mul_f32_e32 v85, 0x45800000, v84
	v_cndmask_b32_e32 v106, v84, v85, vcc
	s_waitcnt vmcnt(4)
	s_lshl_b32 s99, s98, 11
	s_add_u32 s99, s99, 0xb171900
	s_add_u32 s100, s90, s99
	s_addc_u32 s101, s91, 0
	v_pk_mul_f32 v[0:1], v[0:1], v[106:107] op_sel_hi:[1,0]
	v_pk_mul_f32 v[2:3], v[2:3], v[106:107] op_sel_hi:[1,0]
	v_pk_mul_f32 v[0:1], v[32:33], v[0:1]
	v_pk_mul_f32 v[2:3], v[34:35], v[2:3]
	v_pk_add_f32 v[48:49], v[48:49], 1.0 op_sel_hi:[1,0]
	v_pk_add_f32 v[50:51], v[50:51], 1.0 op_sel_hi:[1,0]
	v_pk_fma_f32 v[0:1], v[48:49], v[0:1], v[64:65]
	v_pk_fma_f32 v[2:3], v[50:51], v[2:3], v[66:67]
	v_cvt_pk_bf16_f32 v0, v0, v1
	v_cvt_pk_bf16_f32 v1, v2, v3
	global_store_dwordx2 v97, v[0:1], s[100:101] offset:0
	v_pk_mul_f32 v[4:5], v[4:5], v[106:107] op_sel_hi:[1,0]
	v_pk_mul_f32 v[6:7], v[6:7], v[106:107] op_sel_hi:[1,0]
	v_pk_mul_f32 v[4:5], v[36:37], v[4:5]
	v_pk_mul_f32 v[6:7], v[38:39], v[6:7]
	v_pk_add_f32 v[52:53], v[52:53], 1.0 op_sel_hi:[1,0]
	v_pk_add_f32 v[54:55], v[54:55], 1.0 op_sel_hi:[1,0]
	v_pk_fma_f32 v[4:5], v[52:53], v[4:5], v[68:69]
	v_pk_fma_f32 v[6:7], v[54:55], v[6:7], v[70:71]
	v_cvt_pk_bf16_f32 v4, v4, v5
	v_cvt_pk_bf16_f32 v5, v6, v7
	global_store_dwordx2 v97, v[4:5], s[100:101] offset:512
	v_pk_mul_f32 v[8:9], v[8:9], v[106:107] op_sel_hi:[1,0]
	v_pk_mul_f32 v[10:11], v[10:11], v[106:107] op_sel_hi:[1,0]
	v_pk_mul_f32 v[8:9], v[40:41], v[8:9]
	v_pk_mul_f32 v[10:11], v[42:43], v[10:11]
	v_pk_add_f32 v[56:57], v[56:57], 1.0 op_sel_hi:[1,0]
	v_pk_add_f32 v[58:59], v[58:59], 1.0 op_sel_hi:[1,0]
	v_pk_fma_f32 v[8:9], v[56:57], v[8:9], v[72:73]
	v_pk_fma_f32 v[10:11], v[58:59], v[10:11], v[74:75]
	v_cvt_pk_bf16_f32 v8, v8, v9
	v_cvt_pk_bf16_f32 v9, v10, v11
	global_store_dwordx2 v97, v[8:9], s[100:101] offset:1024
	v_pk_mul_f32 v[12:13], v[12:13], v[106:107] op_sel_hi:[1,0]
	v_pk_mul_f32 v[14:15], v[14:15], v[106:107] op_sel_hi:[1,0]
	v_pk_mul_f32 v[12:13], v[44:45], v[12:13]
	v_pk_mul_f32 v[14:15], v[46:47], v[14:15]
	v_pk_add_f32 v[60:61], v[60:61], 1.0 op_sel_hi:[1,0]
	v_pk_add_f32 v[62:63], v[62:63], 1.0 op_sel_hi:[1,0]
	v_pk_fma_f32 v[12:13], v[60:61], v[12:13], v[76:77]
	v_pk_fma_f32 v[14:15], v[62:63], v[14:15], v[78:79]
	v_cvt_pk_bf16_f32 v12, v12, v13
	v_cvt_pk_bf16_f32 v13, v14, v15
	global_store_dwordx2 v97, v[12:13], s[100:101] offset:1536
	s_add_u32 s98, s98, 0x800
	s_sub_u32 s99, s98, 0x2000
	s_lshr_b32 s99, s99, 11
	s_add_u32 s99, s99, 1
	s_cmp_lt_u32 s98, 0x2000
	s_cmov_b32 s99, 0
	s_mul_i32 s99, s99, 0x6000
	s_add_u32 s99, s99, 0x3453000
	s_add_u32 s100, s90, s99
	s_addc_u32 s101, s91, 0
	global_load_dwordx4 v[48:51], v96, s[100:101] offset:0
	global_load_dwordx4 v[52:55], v96, s[100:101] offset:1024
	global_load_dwordx4 v[56:59], v96, s[100:101] offset:2048
	global_load_dwordx4 v[60:63], v96, s[100:101] offset:3072
	s_sub_u32 s99, s98, 0x2000
	s_lshr_b32 s99, s99, 11
	s_add_u32 s99, s99, 1
	s_cmp_lt_u32 s98, 0x2000
	s_cmov_b32 s99, 0
	s_mul_i32 s99, s99, 0x6000
	s_add_u32 s99, s99, 0x3452000
	s_add_u32 s100, s90, s99
	s_addc_u32 s101, s91, 0
	global_load_dwordx4 v[64:67], v96, s[100:101] offset:0
	global_load_dwordx4 v[68:71], v96, s[100:101] offset:1024
	global_load_dwordx4 v[72:75], v96, s[100:101] offset:2048
	global_load_dwordx4 v[76:79], v96, s[100:101] offset:3072
	s_waitcnt vmcnt(12)
	v_mul_f32_e32 v80, v17, v17
	v_mul_f32_e32 v81, v21, v21
	v_mul_f32_e32 v82, v25, v25
	v_mul_f32_e32 v83, v29, v29
	v_fmac_f32_e32 v80, v16, v16
	v_fmac_f32_e32 v81, v20, v20
	v_fmac_f32_e32 v82, v24, v24
	v_fmac_f32_e32 v83, v28, v28
	v_fmac_f32_e32 v80, v18, v18
	v_fmac_f32_e32 v81, v22, v22
	v_fmac_f32_e32 v82, v26, v26
	v_fmac_f32_e32 v83, v30, v30
	v_fmac_f32_e32 v80, v19, v19
	v_fmac_f32_e32 v81, v23, v23
	v_fmac_f32_e32 v82, v27, v27
	v_fmac_f32_e32 v83, v31, v31
	v_add_f32_e32 v84, v80, v81
	v_add_f32_e32 v84, v84, v82
	v_add_f32_e32 v84, v84, v83
	ds_bpermute_b32 v85, v98, v84
	s_waitcnt lgkmcnt(0)
	v_add_f32_e32 v84, v84, v85
	ds_bpermute_b32 v85, v99, v84
	s_waitcnt lgkmcnt(0)
	v_add_f32_e32 v84, v84, v85
	ds_bpermute_b32 v85, v100, v84
	s_waitcnt lgkmcnt(0)
	v_add_f32_e32 v84, v84, v85
	ds_bpermute_b32 v85, v101, v84
	s_waitcnt lgkmcnt(0)
	v_add_f32_e32 v84, v84, v85
	ds_bpermute_b32 v85, v102, v84
	s_waitcnt lgkmcnt(0)
	v_add_f32_e32 v84, v84, v85
	ds_bpermute_b32 v85, v103, v84
	s_waitcnt lgkmcnt(0)
	v_add_f32_e32 v84, v84, v85
	v_fmamk_f32 v84, v84, 0x3a800000, v104
	v_mul_f32_e32 v85, 0x4b800000, v84
	v_cmp_gt_f32_e32 vcc, 0x800000, v84
	s_nop 1
	v_cndmask_b32_e32 v84, v84, v85, vcc
	v_rsq_f32_e32 v84, v84
	s_nop 0
	v_mul_f32_e32 v85, 0x45800000, v84
	v_cndmask_b32_e32 v106, v84, v85, vcc
	s_waitcnt vmcnt(0)
	s_lshl_b32 s99, s98, 11
	s_add_u32 s99, s99, 0xb171900
	s_add_u32 s100, s90, s99
	s_addc_u32 s101, s91, 0
	v_pk_mul_f32 v[16:17], v[16:17], v[106:107] op_sel_hi:[1,0]
	v_pk_mul_f32 v[18:19], v[18:19], v[106:107] op_sel_hi:[1,0]
	v_pk_mul_f32 v[16:17], v[32:33], v[16:17]
	v_pk_mul_f32 v[18:19], v[34:35], v[18:19]
	v_pk_add_f32 v[48:49], v[48:49], 1.0 op_sel_hi:[1,0]
	v_pk_add_f32 v[50:51], v[50:51], 1.0 op_sel_hi:[1,0]
	v_pk_fma_f32 v[16:17], v[48:49], v[16:17], v[64:65]
	v_pk_fma_f32 v[18:19], v[50:51], v[18:19], v[66:67]
	v_cvt_pk_bf16_f32 v16, v16, v17
	v_cvt_pk_bf16_f32 v17, v18, v19
	global_store_dwordx2 v97, v[16:17], s[100:101] offset:0
	v_pk_mul_f32 v[20:21], v[20:21], v[106:107] op_sel_hi:[1,0]
	v_pk_mul_f32 v[22:23], v[22:23], v[106:107] op_sel_hi:[1,0]
	v_pk_mul_f32 v[20:21], v[36:37], v[20:21]
	v_pk_mul_f32 v[22:23], v[38:39], v[22:23]
	v_pk_add_f32 v[52:53], v[52:53], 1.0 op_sel_hi:[1,0]
	v_pk_add_f32 v[54:55], v[54:55], 1.0 op_sel_hi:[1,0]
	v_pk_fma_f32 v[20:21], v[52:53], v[20:21], v[68:69]
	v_pk_fma_f32 v[22:23], v[54:55], v[22:23], v[70:71]
	v_cvt_pk_bf16_f32 v20, v20, v21
	v_cvt_pk_bf16_f32 v21, v22, v23
	global_store_dwordx2 v97, v[20:21], s[100:101] offset:512
	v_pk_mul_f32 v[24:25], v[24:25], v[106:107] op_sel_hi:[1,0]
	v_pk_mul_f32 v[26:27], v[26:27], v[106:107] op_sel_hi:[1,0]
	v_pk_mul_f32 v[24:25], v[40:41], v[24:25]
	v_pk_mul_f32 v[26:27], v[42:43], v[26:27]
	v_pk_add_f32 v[56:57], v[56:57], 1.0 op_sel_hi:[1,0]
	v_pk_add_f32 v[58:59], v[58:59], 1.0 op_sel_hi:[1,0]
	v_pk_fma_f32 v[24:25], v[56:57], v[24:25], v[72:73]
	v_pk_fma_f32 v[26:27], v[58:59], v[26:27], v[74:75]
	v_cvt_pk_bf16_f32 v24, v24, v25
	v_cvt_pk_bf16_f32 v25, v26, v27
	global_store_dwordx2 v97, v[24:25], s[100:101] offset:1024
	v_pk_mul_f32 v[28:29], v[28:29], v[106:107] op_sel_hi:[1,0]
	v_pk_mul_f32 v[30:31], v[30:31], v[106:107] op_sel_hi:[1,0]
	v_pk_mul_f32 v[28:29], v[44:45], v[28:29]
	v_pk_mul_f32 v[30:31], v[46:47], v[30:31]
	v_pk_add_f32 v[60:61], v[60:61], 1.0 op_sel_hi:[1,0]
	v_pk_add_f32 v[62:63], v[62:63], 1.0 op_sel_hi:[1,0]
	v_pk_fma_f32 v[28:29], v[60:61], v[28:29], v[76:77]
	v_pk_fma_f32 v[30:31], v[62:63], v[30:31], v[78:79]
	v_cvt_pk_bf16_f32 v28, v28, v29
	v_cvt_pk_bf16_f32 v29, v30, v31
	global_store_dwordx2 v97, v[28:29], s[100:101] offset:1536

.LBB0_2222:
	s_or_b64 exec, exec, s[0:1]
	s_waitcnt lgkmcnt(0)
	s_barrier
	s_and_saveexec_b64 s[4:5], s[78:79]
	s_cbranch_execz .LBB0_2229
	v_mbcnt_hi_u32_b32 v0, -1, v182
	v_and_b32_e32 v2, 64, v0
	v_add_u32_e32 v2, 64, v2
	v_xor_b32_e32 v3, 32, v0
	v_cmp_lt_i32_e32 vcc, v3, v2
	v_readlane_b32 s36, v250, 3
	v_readlane_b32 s46, v250, 13
	v_cndmask_b32_e32 v3, v0, v3, vcc
	v_lshlrev_b32_e32 v24, 2, v3
	v_xor_b32_e32 v3, 16, v0
	v_cmp_lt_i32_e32 vcc, v3, v2
	v_readlane_b32 s47, v250, 14
	s_mov_b64 s[10:11], s[46:47]
	v_cndmask_b32_e32 v3, v0, v3, vcc
	v_lshlrev_b32_e32 v25, 2, v3
	v_xor_b32_e32 v3, 8, v0
	v_cmp_lt_i32_e32 vcc, v3, v2
	s_add_u32 s0, s10, 0x1000
	v_and_b32_e32 v12, 0xfc, v149
	v_cndmask_b32_e32 v3, v0, v3, vcc
	v_lshlrev_b32_e32 v26, 2, v3
	v_xor_b32_e32 v3, 4, v0
	v_cmp_lt_i32_e32 vcc, v3, v2
	s_addc_u32 s1, s11, 0
	v_mov_b32_e32 v1, 0
	v_cndmask_b32_e32 v3, v0, v3, vcc
	v_lshlrev_b32_e32 v27, 2, v3
	v_xor_b32_e32 v3, 2, v0
	v_cmp_lt_i32_e32 vcc, v3, v2
	v_or_b32_e32 v14, 0x100, v12
	v_or_b32_e32 v16, 0x200, v12
	v_cndmask_b32_e32 v3, v0, v3, vcc
	v_lshlrev_b32_e32 v28, 2, v3
	v_xor_b32_e32 v3, 1, v0
	v_cmp_lt_i32_e32 vcc, v3, v2
	s_waitcnt vmcnt(1)
	v_or_b32_e32 v18, 0x300, v12
	s_lshl_b32 s12, s92, 2
	v_cndmask_b32_e32 v0, v0, v3, vcc
	v_lshlrev_b32_e32 v29, 2, v0
	v_lshlrev_b32_e32 v0, 2, v12
	v_lshl_add_u64 v[2:3], s[0:1], 0, v[0:1]
	v_lshlrev_b32_e32 v0, 2, v14
	v_lshl_add_u64 v[4:5], s[0:1], 0, v[0:1]
	v_lshlrev_b32_e32 v0, 2, v16
	v_lshl_add_u64 v[6:7], s[0:1], 0, v[0:1]
	v_lshlrev_b32_e32 v0, 2, v18
	v_lshl_add_u64 v[8:9], s[0:1], 0, v[0:1]
	v_readlane_b32 s0, v250, 19
	v_lshlrev_b32_e32 v0, 1, v12
	v_readlane_b32 s1, v250, 20
	s_mov_b64 s[6:7], 0
	s_movk_i32 s13, 0x2000
	v_lshl_add_u64 v[10:11], s[0:1], 0, v[0:1]
	s_movk_i32 s14, 0x1fff
	v_lshlrev_b32_e32 v12, 2, v12
	v_mov_b32_e32 v13, v1
	s_movk_i32 s15, 0x1800
	s_mov_b64 s[8:9], 0x4000
	s_mov_b64 s[10:11], 0x3000
	v_lshlrev_b32_e32 v14, 2, v14
	v_mov_b32_e32 v15, v1
	v_lshlrev_b32_e32 v16, 2, v16
	v_mov_b32_e32 v17, v1
	v_lshlrev_b32_e32 v18, 2, v18
	v_mov_b32_e32 v19, v1
	v_mov_b32_e32 v30, 0x358637bd
	s_mov_b32 s16, 0x800000
	s_movk_i32 s17, 0x2fff
	s_waitcnt vmcnt(0)
	v_mov_b32_e32 v20, v148
	v_readlane_b32 s37, v250, 4
	v_readlane_b32 s38, v250, 5
	v_readlane_b32 s39, v250, 6
	v_readlane_b32 s40, v250, 7
	v_readlane_b32 s41, v250, 8
	v_readlane_b32 s42, v250, 9
	v_readlane_b32 s43, v250, 10
	v_readlane_b32 s44, v250, 11
	v_readlane_b32 s45, v250, 12
	v_readlane_b32 s48, v250, 15
	v_readlane_b32 s49, v250, 16
	v_readlane_b32 s50, v250, 17
	v_readlane_b32 s51, v250, 18
	v_mbcnt_lo_u32_b32 v80, -1, 0
	v_mbcnt_hi_u32_b32 v80, -1, v80
	v_lshlrev_b32_e32 v96, 4, v80
	v_lshlrev_b32_e32 v97, 3, v80
	v_xor_b32_e32 v98, 32, v80
	v_lshlrev_b32_e32 v98, 2, v98
	v_xor_b32_e32 v99, 16, v80
	v_lshlrev_b32_e32 v99, 2, v99
	v_xor_b32_e32 v100, 8, v80
	v_lshlrev_b32_e32 v100, 2, v100
	v_xor_b32_e32 v101, 4, v80
	v_lshlrev_b32_e32 v101, 2, v101
	v_xor_b32_e32 v102, 2, v80
	v_lshlrev_b32_e32 v102, 2, v102
	v_xor_b32_e32 v103, 1, v80
	v_lshlrev_b32_e32 v103, 2, v103
	v_mov_b32_e32 v104, 0x358637bd
	v_mov_b32_e32 v107, 0
	v_readlane_b32 s100, v250, 13
	v_readlane_b32 s101, v250, 14
	s_nop 5
	s_add_u32 s100, s100, 0x1000
	s_addc_u32 s101, s101, 0
	global_load_dwordx4 v[32:35], v96, s[100:101] offset:0
	global_load_dwordx4 v[36:39], v96, s[100:101] offset:1024
	global_load_dwordx4 v[40:43], v96, s[100:101] offset:2048
	global_load_dwordx4 v[44:47], v96, s[100:101] offset:3072
	v_readfirstlane_b32 s98, v148
	s_nop 3
	s_lshl_b32 s99, s98, 12
	s_add_u32 s100, s88, s99
	s_addc_u32 s101, s89, 0
	global_load_dwordx4 v[0:3], v96, s[100:101] offset:0
	global_load_dwordx4 v[4:7], v96, s[100:101] offset:1024
	global_load_dwordx4 v[8:11], v96, s[100:101] offset:2048
	global_load_dwordx4 v[12:15], v96, s[100:101] offset:3072
	s_sub_u32 s99, s98, 0x2000
	s_lshr_b32 s99, s99, 11
	s_add_u32 s99, s99, 1
	s_cmp_lt_u32 s98, 0x2000
	s_cmov_b32 s99, 0
	s_mul_i32 s99, s99, 0x6000
	s_add_u32 s99, s99, 0x3456000
	s_add_u32 s100, s90, s99
	s_addc_u32 s101, s91, 0
	global_load_dwordx4 v[48:51], v96, s[100:101] offset:0
	global_load_dwordx4 v[52:55], v96, s[100:101] offset:1024
	global_load_dwordx4 v[56:59], v96, s[100:101] offset:2048
	global_load_dwordx4 v[60:63], v96, s[100:101] offset:3072
	s_sub_u32 s99, s98, 0x2000
	s_lshr_b32 s99, s99, 11
	s_add_u32 s99, s99, 1
	s_cmp_lt_u32 s98, 0x2000
	s_cmov_b32 s99, 0
	s_mul_i32 s99, s99, 0x6000
	s_add_u32 s99, s99, 0x3455000
	s_add_u32 s100, s90, s99
	s_addc_u32 s101, s91, 0
	global_load_dwordx4 v[64:67], v96, s[100:101] offset:0
	global_load_dwordx4 v[68:71], v96, s[100:101] offset:1024
	global_load_dwordx4 v[72:75], v96, s[100:101] offset:2048
	global_load_dwordx4 v[76:79], v96, s[100:101] offset:3072
	s_add_u32 s98, s98, 0x800
	s_lshl_b32 s99, s98, 12
	s_add_u32 s100, s88, s99
	s_addc_u32 s101, s89, 0
	global_load_dwordx4 v[16:19], v96, s[100:101] offset:0
	global_load_dwordx4 v[20:23], v96, s[100:101] offset:1024
	global_load_dwordx4 v[24:27], v96, s[100:101] offset:2048
	global_load_dwordx4 v[28:31], v96, s[100:101] offset:3072
	s_sub_u32 s98, s98, 0x800
	s_waitcnt vmcnt(12)
	v_mul_f32_e32 v80, v1, v1
	v_mul_f32_e32 v81, v5, v5
	v_mul_f32_e32 v82, v9, v9
	v_mul_f32_e32 v83, v13, v13
	v_fmac_f32_e32 v80, v0, v0
	v_fmac_f32_e32 v81, v4, v4
	v_fmac_f32_e32 v82, v8, v8
	v_fmac_f32_e32 v83, v12, v12
	v_fmac_f32_e32 v80, v2, v2
	v_fmac_f32_e32 v81, v6, v6
	v_fmac_f32_e32 v82, v10, v10
	v_fmac_f32_e32 v83, v14, v14
	v_fmac_f32_e32 v80, v3, v3
	v_fmac_f32_e32 v81, v7, v7
	v_fmac_f32_e32 v82, v11, v11
	v_fmac_f32_e32 v83, v15, v15
	v_add_f32_e32 v84, v80, v81
	v_add_f32_e32 v84, v84, v82
	v_add_f32_e32 v84, v84, v83
	ds_bpermute_b32 v85, v98, v84
	s_waitcnt lgkmcnt(0)
	v_add_f32_e32 v84, v84, v85
	ds_bpermute_b32 v85, v99, v84
	s_waitcnt lgkmcnt(0)
	v_add_f32_e32 v84, v84, v85
	ds_bpermute_b32 v85, v100, v84
	s_waitcnt lgkmcnt(0)
	v_add_f32_e32 v84, v84, v85
	ds_bpermute_b32 v85, v101, v84
	s_waitcnt lgkmcnt(0)
	v_add_f32_e32 v84, v84, v85
	ds_bpermute_b32 v85, v102, v84
	s_waitcnt lgkmcnt(0)
	v_add_f32_e32 v84, v84, v85
	ds_bpermute_b32 v85, v103, v84
	s_waitcnt lgkmcnt(0)
	v_add_f32_e32 v84, v84, v85
	v_fmamk_f32 v84, v84, 0x3a800000, v104
	v_mul_f32_e32 v85, 0x4b800000, v84
	v_cmp_gt_f32_e32 vcc, 0x800000, v84
	s_nop 1
	v_cndmask_b32_e32 v84, v84, v85, vcc
	v_rsq_f32_e32 v84, v84
	s_nop 0
	v_mul_f32_e32 v85, 0x45800000, v84
	v_cndmask_b32_e32 v106, v84, v85, vcc
	s_waitcnt vmcnt(4)
	s_lshl_b32 s99, s98, 11
	s_add_u32 s99, s99, 0xb171900
	s_add_u32 s100, s90, s99
	s_addc_u32 s101, s91, 0
	v_pk_mul_f32 v[0:1], v[0:1], v[106:107] op_sel_hi:[1,0]
	v_pk_mul_f32 v[2:3], v[2:3], v[106:107] op_sel_hi:[1,0]
	v_pk_mul_f32 v[0:1], v[32:33], v[0:1]
	v_pk_mul_f32 v[2:3], v[34:35], v[2:3]
	v_pk_add_f32 v[48:49], v[48:49], 1.0 op_sel_hi:[1,0]
	v_pk_add_f32 v[50:51], v[50:51], 1.0 op_sel_hi:[1,0]
	v_pk_fma_f32 v[0:1], v[48:49], v[0:1], v[64:65]
	v_pk_fma_f32 v[2:3], v[50:51], v[2:3], v[66:67]
	v_cvt_pk_bf16_f32 v0, v0, v1
	v_cvt_pk_bf16_f32 v1, v2, v3
	global_store_dwordx2 v97, v[0:1], s[100:101] offset:0
	v_pk_mul_f32 v[4:5], v[4:5], v[106:107] op_sel_hi:[1,0]
	v_pk_mul_f32 v[6:7], v[6:7], v[106:107] op_sel_hi:[1,0]
	v_pk_mul_f32 v[4:5], v[36:37], v[4:5]
	v_pk_mul_f32 v[6:7], v[38:39], v[6:7]
	v_pk_add_f32 v[52:53], v[52:53], 1.0 op_sel_hi:[1,0]
	v_pk_add_f32 v[54:55], v[54:55], 1.0 op_sel_hi:[1,0]
	v_pk_fma_f32 v[4:5], v[52:53], v[4:5], v[68:69]
	v_pk_fma_f32 v[6:7], v[54:55], v[6:7], v[70:71]
	v_cvt_pk_bf16_f32 v4, v4, v5
	v_cvt_pk_bf16_f32 v5, v6, v7
	global_store_dwordx2 v97, v[4:5], s[100:101] offset:512
	v_pk_mul_f32 v[8:9], v[8:9], v[106:107] op_sel_hi:[1,0]
	v_pk_mul_f32 v[10:11], v[10:11], v[106:107] op_sel_hi:[1,0]
	v_pk_mul_f32 v[8:9], v[40:41], v[8:9]
	v_pk_mul_f32 v[10:11], v[42:43], v[10:11]
	v_pk_add_f32 v[56:57], v[56:57], 1.0 op_sel_hi:[1,0]
	v_pk_add_f32 v[58:59], v[58:59], 1.0 op_sel_hi:[1,0]
	v_pk_fma_f32 v[8:9], v[56:57], v[8:9], v[72:73]
	v_pk_fma_f32 v[10:11], v[58:59], v[10:11], v[74:75]
	v_cvt_pk_bf16_f32 v8, v8, v9
	v_cvt_pk_bf16_f32 v9, v10, v11
	global_store_dwordx2 v97, v[8:9], s[100:101] offset:1024
	v_pk_mul_f32 v[12:13], v[12:13], v[106:107] op_sel_hi:[1,0]
	v_pk_mul_f32 v[14:15], v[14:15], v[106:107] op_sel_hi:[1,0]
	v_pk_mul_f32 v[12:13], v[44:45], v[12:13]
	v_pk_mul_f32 v[14:15], v[46:47], v[14:15]
	v_pk_add_f32 v[60:61], v[60:61], 1.0 op_sel_hi:[1,0]
	v_pk_add_f32 v[62:63], v[62:63], 1.0 op_sel_hi:[1,0]
	v_pk_fma_f32 v[12:13], v[60:61], v[12:13], v[76:77]
	v_pk_fma_f32 v[14:15], v[62:63], v[14:15], v[78:79]
	v_cvt_pk_bf16_f32 v12, v12, v13
	v_cvt_pk_bf16_f32 v13, v14, v15
	global_store_dwordx2 v97, v[12:13], s[100:101] offset:1536
	s_add_u32 s98, s98, 0x800
	s_sub_u32 s99, s98, 0x2000
	s_lshr_b32 s99, s99, 11
	s_add_u32 s99, s99, 1
	s_cmp_lt_u32 s98, 0x2000
	s_cmov_b32 s99, 0
	s_mul_i32 s99, s99, 0x6000
	s_add_u32 s99, s99, 0x3456000
	s_add_u32 s100, s90, s99
	s_addc_u32 s101, s91, 0
	global_load_dwordx4 v[48:51], v96, s[100:101] offset:0
	global_load_dwordx4 v[52:55], v96, s[100:101] offset:1024
	global_load_dwordx4 v[56:59], v96, s[100:101] offset:2048
	global_load_dwordx4 v[60:63], v96, s[100:101] offset:3072
	s_sub_u32 s99, s98, 0x2000
	s_lshr_b32 s99, s99, 11
	s_add_u32 s99, s99, 1
	s_cmp_lt_u32 s98, 0x2000
	s_cmov_b32 s99, 0
	s_mul_i32 s99, s99, 0x6000
	s_add_u32 s99, s99, 0x3455000
	s_add_u32 s100, s90, s99
	s_addc_u32 s101, s91, 0
	global_load_dwordx4 v[64:67], v96, s[100:101] offset:0
	global_load_dwordx4 v[68:71], v96, s[100:101] offset:1024
	global_load_dwordx4 v[72:75], v96, s[100:101] offset:2048
	global_load_dwordx4 v[76:79], v96, s[100:101] offset:3072
	s_add_u32 s98, s98, 0x800
	s_lshl_b32 s99, s98, 12
	s_add_u32 s100, s88, s99
	s_addc_u32 s101, s89, 0
	global_load_dwordx4 v[0:3], v96, s[100:101] offset:0
	global_load_dwordx4 v[4:7], v96, s[100:101] offset:1024
	global_load_dwordx4 v[8:11], v96, s[100:101] offset:2048
	global_load_dwordx4 v[12:15], v96, s[100:101] offset:3072
	s_sub_u32 s98, s98, 0x800
	s_waitcnt vmcnt(16)
	v_mul_f32_e32 v80, v17, v17
	v_mul_f32_e32 v81, v21, v21
	v_mul_f32_e32 v82, v25, v25
	v_mul_f32_e32 v83, v29, v29
	v_fmac_f32_e32 v80, v16, v16
	v_fmac_f32_e32 v81, v20, v20
	v_fmac_f32_e32 v82, v24, v24
	v_fmac_f32_e32 v83, v28, v28
	v_fmac_f32_e32 v80, v18, v18
	v_fmac_f32_e32 v81, v22, v22
	v_fmac_f32_e32 v82, v26, v26
	v_fmac_f32_e32 v83, v30, v30
	v_fmac_f32_e32 v80, v19, v19
	v_fmac_f32_e32 v81, v23, v23
	v_fmac_f32_e32 v82, v27, v27
	v_fmac_f32_e32 v83, v31, v31
	v_add_f32_e32 v84, v80, v81
	v_add_f32_e32 v84, v84, v82
	v_add_f32_e32 v84, v84, v83
	ds_bpermute_b32 v85, v98, v84
	s_waitcnt lgkmcnt(0)
	v_add_f32_e32 v84, v84, v85
	ds_bpermute_b32 v85, v99, v84
	s_waitcnt lgkmcnt(0)
	v_add_f32_e32 v84, v84, v85
	ds_bpermute_b32 v85, v100, v84
	s_waitcnt lgkmcnt(0)
	v_add_f32_e32 v84, v84, v85
	ds_bpermute_b32 v85, v101, v84
	s_waitcnt lgkmcnt(0)
	v_add_f32_e32 v84, v84, v85
	ds_bpermute_b32 v85, v102, v84
	s_waitcnt lgkmcnt(0)
	v_add_f32_e32 v84, v84, v85
	ds_bpermute_b32 v85, v103, v84
	s_waitcnt lgkmcnt(0)
	v_add_f32_e32 v84, v84, v85
	v_fmamk_f32 v84, v84, 0x3a800000, v104
	v_mul_f32_e32 v85, 0x4b800000, v84
	v_cmp_gt_f32_e32 vcc, 0x800000, v84
	s_nop 1
	v_cndmask_b32_e32 v84, v84, v85, vcc
	v_rsq_f32_e32 v84, v84
	s_nop 0
	v_mul_f32_e32 v85, 0x45800000, v84
	v_cndmask_b32_e32 v106, v84, v85, vcc
	s_waitcnt vmcnt(4)
	s_lshl_b32 s99, s98, 11
	s_add_u32 s99, s99, 0xb171900
	s_add_u32 s100, s90, s99
	s_addc_u32 s101, s91, 0
	v_pk_mul_f32 v[16:17], v[16:17], v[106:107] op_sel_hi:[1,0]
	v_pk_mul_f32 v[18:19], v[18:19], v[106:107] op_sel_hi:[1,0]
	v_pk_mul_f32 v[16:17], v[32:33], v[16:17]
	v_pk_mul_f32 v[18:19], v[34:35], v[18:19]
	v_pk_add_f32 v[48:49], v[48:49], 1.0 op_sel_hi:[1,0]
	v_pk_add_f32 v[50:51], v[50:51], 1.0 op_sel_hi:[1,0]
	v_pk_fma_f32 v[16:17], v[48:49], v[16:17], v[64:65]
	v_pk_fma_f32 v[18:19], v[50:51], v[18:19], v[66:67]
	v_cvt_pk_bf16_f32 v16, v16, v17
	v_cvt_pk_bf16_f32 v17, v18, v19
	global_store_dwordx2 v97, v[16:17], s[100:101] offset:0
	v_pk_mul_f32 v[20:21], v[20:21], v[106:107] op_sel_hi:[1,0]
	v_pk_mul_f32 v[22:23], v[22:23], v[106:107] op_sel_hi:[1,0]
	v_pk_mul_f32 v[20:21], v[36:37], v[20:21]
	v_pk_mul_f32 v[22:23], v[38:39], v[22:23]
	v_pk_add_f32 v[52:53], v[52:53], 1.0 op_sel_hi:[1,0]
	v_pk_add_f32 v[54:55], v[54:55], 1.0 op_sel_hi:[1,0]
	v_pk_fma_f32 v[20:21], v[52:53], v[20:21], v[68:69]
	v_pk_fma_f32 v[22:23], v[54:55], v[22:23], v[70:71]
	v_cvt_pk_bf16_f32 v20, v20, v21
	v_cvt_pk_bf16_f32 v21, v22, v23
	global_store_dwordx2 v97, v[20:21], s[100:101] offset:512
	v_pk_mul_f32 v[24:25], v[24:25], v[106:107] op_sel_hi:[1,0]
	v_pk_mul_f32 v[26:27], v[26:27], v[106:107] op_sel_hi:[1,0]
	v_pk_mul_f32 v[24:25], v[40:41], v[24:25]
	v_pk_mul_f32 v[26:27], v[42:43], v[26:27]
	v_pk_add_f32 v[56:57], v[56:57], 1.0 op_sel_hi:[1,0]
	v_pk_add_f32 v[58:59], v[58:59], 1.0 op_sel_hi:[1,0]
	v_pk_fma_f32 v[24:25], v[56:57], v[24:25], v[72:73]
	v_pk_fma_f32 v[26:27], v[58:59], v[26:27], v[74:75]
	v_cvt_pk_bf16_f32 v24, v24, v25
	v_cvt_pk_bf16_f32 v25, v26, v27
	global_store_dwordx2 v97, v[24:25], s[100:101] offset:1024
	v_pk_mul_f32 v[28:29], v[28:29], v[106:107] op_sel_hi:[1,0]
	v_pk_mul_f32 v[30:31], v[30:31], v[106:107] op_sel_hi:[1,0]
	v_pk_mul_f32 v[28:29], v[44:45], v[28:29]
	v_pk_mul_f32 v[30:31], v[46:47], v[30:31]
	v_pk_add_f32 v[60:61], v[60:61], 1.0 op_sel_hi:[1,0]
	v_pk_add_f32 v[62:63], v[62:63], 1.0 op_sel_hi:[1,0]
	v_pk_fma_f32 v[28:29], v[60:61], v[28:29], v[76:77]
	v_pk_fma_f32 v[30:31], v[62:63], v[30:31], v[78:79]
	v_cvt_pk_bf16_f32 v28, v28, v29
	v_cvt_pk_bf16_f32 v29, v30, v31
	global_store_dwordx2 v97, v[28:29], s[100:101] offset:1536
	s_add_u32 s98, s98, 0x800
	s_sub_u32 s99, s98, 0x2000
	s_lshr_b32 s99, s99, 11
	s_add_u32 s99, s99, 1
	s_cmp_lt_u32 s98, 0x2000
	s_cmov_b32 s99, 0
	s_mul_i32 s99, s99, 0x6000
	s_add_u32 s99, s99, 0x3456000
	s_add_u32 s100, s90, s99
	s_addc_u32 s101, s91, 0
	global_load_dwordx4 v[48:51], v96, s[100:101] offset:0
	global_load_dwordx4 v[52:55], v96, s[100:101] offset:1024
	global_load_dwordx4 v[56:59], v96, s[100:101] offset:2048
	global_load_dwordx4 v[60:63], v96, s[100:101] offset:3072
	s_sub_u32 s99, s98, 0x2000
	s_lshr_b32 s99, s99, 11
	s_add_u32 s99, s99, 1
	s_cmp_lt_u32 s98, 0x2000
	s_cmov_b32 s99, 0
	s_mul_i32 s99, s99, 0x6000
	s_add_u32 s99, s99, 0x3455000
	s_add_u32 s100, s90, s99
	s_addc_u32 s101, s91, 0
	global_load_dwordx4 v[64:67], v96, s[100:101] offset:0
	global_load_dwordx4 v[68:71], v96, s[100:101] offset:1024
	global_load_dwordx4 v[72:75], v96, s[100:101] offset:2048
	global_load_dwordx4 v[76:79], v96, s[100:101] offset:3072
	s_add_u32 s98, s98, 0x800
	s_lshl_b32 s99, s98, 12
	s_add_u32 s100, s88, s99
	s_addc_u32 s101, s89, 0
	global_load_dwordx4 v[16:19], v96, s[100:101] offset:0
	global_load_dwordx4 v[20:23], v96, s[100:101] offset:1024
	global_load_dwordx4 v[24:27], v96, s[100:101] offset:2048
	global_load_dwordx4 v[28:31], v96, s[100:101] offset:3072
	s_sub_u32 s98, s98, 0x800
	s_waitcnt vmcnt(16)
	v_mul_f32_e32 v80, v1, v1
	v_mul_f32_e32 v81, v5, v5
	v_mul_f32_e32 v82, v9, v9
	v_mul_f32_e32 v83, v13, v13
	v_fmac_f32_e32 v80, v0, v0
	v_fmac_f32_e32 v81, v4, v4
	v_fmac_f32_e32 v82, v8, v8
	v_fmac_f32_e32 v83, v12, v12
	v_fmac_f32_e32 v80, v2, v2
	v_fmac_f32_e32 v81, v6, v6
	v_fmac_f32_e32 v82, v10, v10
	v_fmac_f32_e32 v83, v14, v14
	v_fmac_f32_e32 v80, v3, v3
	v_fmac_f32_e32 v81, v7, v7
	v_fmac_f32_e32 v82, v11, v11
	v_fmac_f32_e32 v83, v15, v15
	v_add_f32_e32 v84, v80, v81
	v_add_f32_e32 v84, v84, v82
	v_add_f32_e32 v84, v84, v83
	ds_bpermute_b32 v85, v98, v84
	s_waitcnt lgkmcnt(0)
	v_add_f32_e32 v84, v84, v85
	ds_bpermute_b32 v85, v99, v84
	s_waitcnt lgkmcnt(0)
	v_add_f32_e32 v84, v84, v85
	ds_bpermute_b32 v85, v100, v84
	s_waitcnt lgkmcnt(0)
	v_add_f32_e32 v84, v84, v85
	ds_bpermute_b32 v85, v101, v84
	s_waitcnt lgkmcnt(0)
	v_add_f32_e32 v84, v84, v85
	ds_bpermute_b32 v85, v102, v84
	s_waitcnt lgkmcnt(0)
	v_add_f32_e32 v84, v84, v85
	ds_bpermute_b32 v85, v103, v84
	s_waitcnt lgkmcnt(0)
	v_add_f32_e32 v84, v84, v85
	v_fmamk_f32 v84, v84, 0x3a800000, v104
	v_mul_f32_e32 v85, 0x4b800000, v84
	v_cmp_gt_f32_e32 vcc, 0x800000, v84
	s_nop 1
	v_cndmask_b32_e32 v84, v84, v85, vcc
	v_rsq_f32_e32 v84, v84
	s_nop 0
	v_mul_f32_e32 v85, 0x45800000, v84
	v_cndmask_b32_e32 v106, v84, v85, vcc
	s_waitcnt vmcnt(4)
	s_lshl_b32 s99, s98, 11
	s_add_u32 s99, s99, 0xb171900
	s_add_u32 s100, s90, s99
	s_addc_u32 s101, s91, 0
	v_pk_mul_f32 v[0:1], v[0:1], v[106:107] op_sel_hi:[1,0]
	v_pk_mul_f32 v[2:3], v[2:3], v[106:107] op_sel_hi:[1,0]
	v_pk_mul_f32 v[0:1], v[32:33], v[0:1]
	v_pk_mul_f32 v[2:3], v[34:35], v[2:3]
	v_pk_add_f32 v[48:49], v[48:49], 1.0 op_sel_hi:[1,0]
	v_pk_add_f32 v[50:51], v[50:51], 1.0 op_sel_hi:[1,0]
	v_pk_fma_f32 v[0:1], v[48:49], v[0:1], v[64:65]
	v_pk_fma_f32 v[2:3], v[50:51], v[2:3], v[66:67]
	v_cvt_pk_bf16_f32 v0, v0, v1
	v_cvt_pk_bf16_f32 v1, v2, v3
	global_store_dwordx2 v97, v[0:1], s[100:101] offset:0
	v_pk_mul_f32 v[4:5], v[4:5], v[106:107] op_sel_hi:[1,0]
	v_pk_mul_f32 v[6:7], v[6:7], v[106:107] op_sel_hi:[1,0]
	v_pk_mul_f32 v[4:5], v[36:37], v[4:5]
	v_pk_mul_f32 v[6:7], v[38:39], v[6:7]
	v_pk_add_f32 v[52:53], v[52:53], 1.0 op_sel_hi:[1,0]
	v_pk_add_f32 v[54:55], v[54:55], 1.0 op_sel_hi:[1,0]
	v_pk_fma_f32 v[4:5], v[52:53], v[4:5], v[68:69]
	v_pk_fma_f32 v[6:7], v[54:55], v[6:7], v[70:71]
	v_cvt_pk_bf16_f32 v4, v4, v5
	v_cvt_pk_bf16_f32 v5, v6, v7
	global_store_dwordx2 v97, v[4:5], s[100:101] offset:512
	v_pk_mul_f32 v[8:9], v[8:9], v[106:107] op_sel_hi:[1,0]
	v_pk_mul_f32 v[10:11], v[10:11], v[106:107] op_sel_hi:[1,0]
	v_pk_mul_f32 v[8:9], v[40:41], v[8:9]
	v_pk_mul_f32 v[10:11], v[42:43], v[10:11]
	v_pk_add_f32 v[56:57], v[56:57], 1.0 op_sel_hi:[1,0]
	v_pk_add_f32 v[58:59], v[58:59], 1.0 op_sel_hi:[1,0]
	v_pk_fma_f32 v[8:9], v[56:57], v[8:9], v[72:73]
	v_pk_fma_f32 v[10:11], v[58:59], v[10:11], v[74:75]
	v_cvt_pk_bf16_f32 v8, v8, v9
	v_cvt_pk_bf16_f32 v9, v10, v11
	global_store_dwordx2 v97, v[8:9], s[100:101] offset:1024
	v_pk_mul_f32 v[12:13], v[12:13], v[106:107] op_sel_hi:[1,0]
	v_pk_mul_f32 v[14:15], v[14:15], v[106:107] op_sel_hi:[1,0]
	v_pk_mul_f32 v[12:13], v[44:45], v[12:13]
	v_pk_mul_f32 v[14:15], v[46:47], v[14:15]
	v_pk_add_f32 v[60:61], v[60:61], 1.0 op_sel_hi:[1,0]
	v_pk_add_f32 v[62:63], v[62:63], 1.0 op_sel_hi:[1,0]
	v_pk_fma_f32 v[12:13], v[60:61], v[12:13], v[76:77]
	v_pk_fma_f32 v[14:15], v[62:63], v[14:15], v[78:79]
	v_cvt_pk_bf16_f32 v12, v12, v13
	v_cvt_pk_bf16_f32 v13, v14, v15
	global_store_dwordx2 v97, v[12:13], s[100:101] offset:1536
	s_add_u32 s98, s98, 0x800
	s_sub_u32 s99, s98, 0x2000
	s_lshr_b32 s99, s99, 11
	s_add_u32 s99, s99, 1
	s_cmp_lt_u32 s98, 0x2000
	s_cmov_b32 s99, 0
	s_mul_i32 s99, s99, 0x6000
	s_add_u32 s99, s99, 0x3456000
	s_add_u32 s100, s90, s99
	s_addc_u32 s101, s91, 0
	global_load_dwordx4 v[48:51], v96, s[100:101] offset:0
	global_load_dwordx4 v[52:55], v96, s[100:101] offset:1024
	global_load_dwordx4 v[56:59], v96, s[100:101] offset:2048
	global_load_dwordx4 v[60:63], v96, s[100:101] offset:3072
	s_sub_u32 s99, s98, 0x2000
	s_lshr_b32 s99, s99, 11
	s_add_u32 s99, s99, 1
	s_cmp_lt_u32 s98, 0x2000
	s_cmov_b32 s99, 0
	s_mul_i32 s99, s99, 0x6000
	s_add_u32 s99, s99, 0x3455000
	s_add_u32 s100, s90, s99
	s_addc_u32 s101, s91, 0
	global_load_dwordx4 v[64:67], v96, s[100:101] offset:0
	global_load_dwordx4 v[68:71], v96, s[100:101] offset:1024
	global_load_dwordx4 v[72:75], v96, s[100:101] offset:2048
	global_load_dwordx4 v[76:79], v96, s[100:101] offset:3072
	s_add_u32 s98, s98, 0x800
	s_lshl_b32 s99, s98, 12
	s_add_u32 s100, s88, s99
	s_addc_u32 s101, s89, 0
	global_load_dwordx4 v[0:3], v96, s[100:101] offset:0
	global_load_dwordx4 v[4:7], v96, s[100:101] offset:1024
	global_load_dwordx4 v[8:11], v96, s[100:101] offset:2048
	global_load_dwordx4 v[12:15], v96, s[100:101] offset:3072
	s_sub_u32 s98, s98, 0x800
	s_waitcnt vmcnt(16)
	v_mul_f32_e32 v80, v17, v17
	v_mul_f32_e32 v81, v21, v21
	v_mul_f32_e32 v82, v25, v25
	v_mul_f32_e32 v83, v29, v29
	v_fmac_f32_e32 v80, v16, v16
	v_fmac_f32_e32 v81, v20, v20
	v_fmac_f32_e32 v82, v24, v24
	v_fmac_f32_e32 v83, v28, v28
	v_fmac_f32_e32 v80, v18, v18
	v_fmac_f32_e32 v81, v22, v22
	v_fmac_f32_e32 v82, v26, v26
	v_fmac_f32_e32 v83, v30, v30
	v_fmac_f32_e32 v80, v19, v19
	v_fmac_f32_e32 v81, v23, v23
	v_fmac_f32_e32 v82, v27, v27
	v_fmac_f32_e32 v83, v31, v31
	v_add_f32_e32 v84, v80, v81
	v_add_f32_e32 v84, v84, v82
	v_add_f32_e32 v84, v84, v83
	ds_bpermute_b32 v85, v98, v84
	s_waitcnt lgkmcnt(0)
	v_add_f32_e32 v84, v84, v85
	ds_bpermute_b32 v85, v99, v84
	s_waitcnt lgkmcnt(0)
	v_add_f32_e32 v84, v84, v85
	ds_bpermute_b32 v85, v100, v84
	s_waitcnt lgkmcnt(0)
	v_add_f32_e32 v84, v84, v85
	ds_bpermute_b32 v85, v101, v84
	s_waitcnt lgkmcnt(0)
	v_add_f32_e32 v84, v84, v85
	ds_bpermute_b32 v85, v102, v84
	s_waitcnt lgkmcnt(0)
	v_add_f32_e32 v84, v84, v85
	ds_bpermute_b32 v85, v103, v84
	s_waitcnt lgkmcnt(0)
	v_add_f32_e32 v84, v84, v85
	v_fmamk_f32 v84, v84, 0x3a800000, v104
	v_mul_f32_e32 v85, 0x4b800000, v84
	v_cmp_gt_f32_e32 vcc, 0x800000, v84
	s_nop 1
	v_cndmask_b32_e32 v84, v84, v85, vcc
	v_rsq_f32_e32 v84, v84
	s_nop 0
	v_mul_f32_e32 v85, 0x45800000, v84
	v_cndmask_b32_e32 v106, v84, v85, vcc
	s_waitcnt vmcnt(4)
	s_lshl_b32 s99, s98, 11
	s_add_u32 s99, s99, 0xb171900
	s_add_u32 s100, s90, s99
	s_addc_u32 s101, s91, 0
	v_pk_mul_f32 v[16:17], v[16:17], v[106:107] op_sel_hi:[1,0]
	v_pk_mul_f32 v[18:19], v[18:19], v[106:107] op_sel_hi:[1,0]
	v_pk_mul_f32 v[16:17], v[32:33], v[16:17]
	v_pk_mul_f32 v[18:19], v[34:35], v[18:19]
	v_pk_add_f32 v[48:49], v[48:49], 1.0 op_sel_hi:[1,0]
	v_pk_add_f32 v[50:51], v[50:51], 1.0 op_sel_hi:[1,0]
	v_pk_fma_f32 v[16:17], v[48:49], v[16:17], v[64:65]
	v_pk_fma_f32 v[18:19], v[50:51], v[18:19], v[66:67]
	v_cvt_pk_bf16_f32 v16, v16, v17
	v_cvt_pk_bf16_f32 v17, v18, v19
	global_store_dwordx2 v97, v[16:17], s[100:101] offset:0
	v_pk_mul_f32 v[20:21], v[20:21], v[106:107] op_sel_hi:[1,0]
	v_pk_mul_f32 v[22:23], v[22:23], v[106:107] op_sel_hi:[1,0]
	v_pk_mul_f32 v[20:21], v[36:37], v[20:21]
	v_pk_mul_f32 v[22:23], v[38:39], v[22:23]
	v_pk_add_f32 v[52:53], v[52:53], 1.0 op_sel_hi:[1,0]
	v_pk_add_f32 v[54:55], v[54:55], 1.0 op_sel_hi:[1,0]
	v_pk_fma_f32 v[20:21], v[52:53], v[20:21], v[68:69]
	v_pk_fma_f32 v[22:23], v[54:55], v[22:23], v[70:71]
	v_cvt_pk_bf16_f32 v20, v20, v21
	v_cvt_pk_bf16_f32 v21, v22, v23
	global_store_dwordx2 v97, v[20:21], s[100:101] offset:512
	v_pk_mul_f32 v[24:25], v[24:25], v[106:107] op_sel_hi:[1,0]
	v_pk_mul_f32 v[26:27], v[26:27], v[106:107] op_sel_hi:[1,0]
	v_pk_mul_f32 v[24:25], v[40:41], v[24:25]
	v_pk_mul_f32 v[26:27], v[42:43], v[26:27]
	v_pk_add_f32 v[56:57], v[56:57], 1.0 op_sel_hi:[1,0]
	v_pk_add_f32 v[58:59], v[58:59], 1.0 op_sel_hi:[1,0]
	v_pk_fma_f32 v[24:25], v[56:57], v[24:25], v[72:73]
	v_pk_fma_f32 v[26:27], v[58:59], v[26:27], v[74:75]
	v_cvt_pk_bf16_f32 v24, v24, v25
	v_cvt_pk_bf16_f32 v25, v26, v27
	global_store_dwordx2 v97, v[24:25], s[100:101] offset:1024
	v_pk_mul_f32 v[28:29], v[28:29], v[106:107] op_sel_hi:[1,0]
	v_pk_mul_f32 v[30:31], v[30:31], v[106:107] op_sel_hi:[1,0]
	v_pk_mul_f32 v[28:29], v[44:45], v[28:29]
	v_pk_mul_f32 v[30:31], v[46:47], v[30:31]
	v_pk_add_f32 v[60:61], v[60:61], 1.0 op_sel_hi:[1,0]
	v_pk_add_f32 v[62:63], v[62:63], 1.0 op_sel_hi:[1,0]
	v_pk_fma_f32 v[28:29], v[60:61], v[28:29], v[76:77]
	v_pk_fma_f32 v[30:31], v[62:63], v[30:31], v[78:79]
	v_cvt_pk_bf16_f32 v28, v28, v29
	v_cvt_pk_bf16_f32 v29, v30, v31
	global_store_dwordx2 v97, v[28:29], s[100:101] offset:1536
	s_add_u32 s98, s98, 0x800
	s_sub_u32 s99, s98, 0x2000
	s_lshr_b32 s99, s99, 11
	s_add_u32 s99, s99, 1
	s_cmp_lt_u32 s98, 0x2000
	s_cmov_b32 s99, 0
	s_mul_i32 s99, s99, 0x6000
	s_add_u32 s99, s99, 0x3456000
	s_add_u32 s100, s90, s99
	s_addc_u32 s101, s91, 0
	global_load_dwordx4 v[48:51], v96, s[100:101] offset:0
	global_load_dwordx4 v[52:55], v96, s[100:101] offset:1024
	global_load_dwordx4 v[56:59], v96, s[100:101] offset:2048
	global_load_dwordx4 v[60:63], v96, s[100:101] offset:3072
	s_sub_u32 s99, s98, 0x2000
	s_lshr_b32 s99, s99, 11
	s_add_u32 s99, s99, 1
	s_cmp_lt_u32 s98, 0x2000
	s_cmov_b32 s99, 0
	s_mul_i32 s99, s99, 0x6000
	s_add_u32 s99, s99, 0x3455000
	s_add_u32 s100, s90, s99
	s_addc_u32 s101, s91, 0
	global_load_dwordx4 v[64:67], v96, s[100:101] offset:0
	global_load_dwordx4 v[68:71], v96, s[100:101] offset:1024
	global_load_dwordx4 v[72:75], v96, s[100:101] offset:2048
	global_load_dwordx4 v[76:79], v96, s[100:101] offset:3072
	s_add_u32 s98, s98, 0x800
	s_lshl_b32 s99, s98, 12
	s_add_u32 s100, s88, s99
	s_addc_u32 s101, s89, 0
	global_load_dwordx4 v[16:19], v96, s[100:101] offset:0
	global_load_dwordx4 v[20:23], v96, s[100:101] offset:1024
	global_load_dwordx4 v[24:27], v96, s[100:101] offset:2048
	global_load_dwordx4 v[28:31], v96, s[100:101] offset:3072
	s_sub_u32 s98, s98, 0x800
	s_waitcnt vmcnt(16)
	v_mul_f32_e32 v80, v1, v1
	v_mul_f32_e32 v81, v5, v5
	v_mul_f32_e32 v82, v9, v9
	v_mul_f32_e32 v83, v13, v13
	v_fmac_f32_e32 v80, v0, v0
	v_fmac_f32_e32 v81, v4, v4
	v_fmac_f32_e32 v82, v8, v8
	v_fmac_f32_e32 v83, v12, v12
	v_fmac_f32_e32 v80, v2, v2
	v_fmac_f32_e32 v81, v6, v6
	v_fmac_f32_e32 v82, v10, v10
	v_fmac_f32_e32 v83, v14, v14
	v_fmac_f32_e32 v80, v3, v3
	v_fmac_f32_e32 v81, v7, v7
	v_fmac_f32_e32 v82, v11, v11
	v_fmac_f32_e32 v83, v15, v15
	v_add_f32_e32 v84, v80, v81
	v_add_f32_e32 v84, v84, v82
	v_add_f32_e32 v84, v84, v83
	ds_bpermute_b32 v85, v98, v84
	s_waitcnt lgkmcnt(0)
	v_add_f32_e32 v84, v84, v85
	ds_bpermute_b32 v85, v99, v84
	s_waitcnt lgkmcnt(0)
	v_add_f32_e32 v84, v84, v85
	ds_bpermute_b32 v85, v100, v84
	s_waitcnt lgkmcnt(0)
	v_add_f32_e32 v84, v84, v85
	ds_bpermute_b32 v85, v101, v84
	s_waitcnt lgkmcnt(0)
	v_add_f32_e32 v84, v84, v85
	ds_bpermute_b32 v85, v102, v84
	s_waitcnt lgkmcnt(0)
	v_add_f32_e32 v84, v84, v85
	ds_bpermute_b32 v85, v103, v84
	s_waitcnt lgkmcnt(0)
	v_add_f32_e32 v84, v84, v85
	v_fmamk_f32 v84, v84, 0x3a800000, v104
	v_mul_f32_e32 v85, 0x4b800000, v84
	v_cmp_gt_f32_e32 vcc, 0x800000, v84
	s_nop 1
	v_cndmask_b32_e32 v84, v84, v85, vcc
	v_rsq_f32_e32 v84, v84
	s_nop 0
	v_mul_f32_e32 v85, 0x45800000, v84
	v_cndmask_b32_e32 v106, v84, v85, vcc
	s_waitcnt vmcnt(4)
	s_lshl_b32 s99, s98, 11
	s_add_u32 s99, s99, 0xb171900
	s_add_u32 s100, s90, s99
	s_addc_u32 s101, s91, 0
	v_pk_mul_f32 v[0:1], v[0:1], v[106:107] op_sel_hi:[1,0]
	v_pk_mul_f32 v[2:3], v[2:3], v[106:107] op_sel_hi:[1,0]
	v_pk_mul_f32 v[0:1], v[32:33], v[0:1]
	v_pk_mul_f32 v[2:3], v[34:35], v[2:3]
	v_pk_add_f32 v[48:49], v[48:49], 1.0 op_sel_hi:[1,0]
	v_pk_add_f32 v[50:51], v[50:51], 1.0 op_sel_hi:[1,0]
	v_pk_fma_f32 v[0:1], v[48:49], v[0:1], v[64:65]
	v_pk_fma_f32 v[2:3], v[50:51], v[2:3], v[66:67]
	v_cvt_pk_bf16_f32 v0, v0, v1
	v_cvt_pk_bf16_f32 v1, v2, v3
	global_store_dwordx2 v97, v[0:1], s[100:101] offset:0
	v_pk_mul_f32 v[4:5], v[4:5], v[106:107] op_sel_hi:[1,0]
	v_pk_mul_f32 v[6:7], v[6:7], v[106:107] op_sel_hi:[1,0]
	v_pk_mul_f32 v[4:5], v[36:37], v[4:5]
	v_pk_mul_f32 v[6:7], v[38:39], v[6:7]
	v_pk_add_f32 v[52:53], v[52:53], 1.0 op_sel_hi:[1,0]
	v_pk_add_f32 v[54:55], v[54:55], 1.0 op_sel_hi:[1,0]
	v_pk_fma_f32 v[4:5], v[52:53], v[4:5], v[68:69]
	v_pk_fma_f32 v[6:7], v[54:55], v[6:7], v[70:71]
	v_cvt_pk_bf16_f32 v4, v4, v5
	v_cvt_pk_bf16_f32 v5, v6, v7
	global_store_dwordx2 v97, v[4:5], s[100:101] offset:512
	v_pk_mul_f32 v[8:9], v[8:9], v[106:107] op_sel_hi:[1,0]
	v_pk_mul_f32 v[10:11], v[10:11], v[106:107] op_sel_hi:[1,0]
	v_pk_mul_f32 v[8:9], v[40:41], v[8:9]
	v_pk_mul_f32 v[10:11], v[42:43], v[10:11]
	v_pk_add_f32 v[56:57], v[56:57], 1.0 op_sel_hi:[1,0]
	v_pk_add_f32 v[58:59], v[58:59], 1.0 op_sel_hi:[1,0]
	v_pk_fma_f32 v[8:9], v[56:57], v[8:9], v[72:73]
	v_pk_fma_f32 v[10:11], v[58:59], v[10:11], v[74:75]
	v_cvt_pk_bf16_f32 v8, v8, v9
	v_cvt_pk_bf16_f32 v9, v10, v11
	global_store_dwordx2 v97, v[8:9], s[100:101] offset:1024
	v_pk_mul_f32 v[12:13], v[12:13], v[106:107] op_sel_hi:[1,0]
	v_pk_mul_f32 v[14:15], v[14:15], v[106:107] op_sel_hi:[1,0]
	v_pk_mul_f32 v[12:13], v[44:45], v[12:13]
	v_pk_mul_f32 v[14:15], v[46:47], v[14:15]
	v_pk_add_f32 v[60:61], v[60:61], 1.0 op_sel_hi:[1,0]
	v_pk_add_f32 v[62:63], v[62:63], 1.0 op_sel_hi:[1,0]
	v_pk_fma_f32 v[12:13], v[60:61], v[12:13], v[76:77]
	v_pk_fma_f32 v[14:15], v[62:63], v[14:15], v[78:79]
	v_cvt_pk_bf16_f32 v12, v12, v13
	v_cvt_pk_bf16_f32 v13, v14, v15
	global_store_dwordx2 v97, v[12:13], s[100:101] offset:1536
	s_add_u32 s98, s98, 0x800
	s_sub_u32 s99, s98, 0x2000
	s_lshr_b32 s99, s99, 11
	s_add_u32 s99, s99, 1
	s_cmp_lt_u32 s98, 0x2000
	s_cmov_b32 s99, 0
	s_mul_i32 s99, s99, 0x6000
	s_add_u32 s99, s99, 0x3456000
	s_add_u32 s100, s90, s99
	s_addc_u32 s101, s91, 0
	global_load_dwordx4 v[48:51], v96, s[100:101] offset:0
	global_load_dwordx4 v[52:55], v96, s[100:101] offset:1024
	global_load_dwordx4 v[56:59], v96, s[100:101] offset:2048
	global_load_dwordx4 v[60:63], v96, s[100:101] offset:3072
	s_sub_u32 s99, s98, 0x2000
	s_lshr_b32 s99, s99, 11
	s_add_u32 s99, s99, 1
	s_cmp_lt_u32 s98, 0x2000
	s_cmov_b32 s99, 0
	s_mul_i32 s99, s99, 0x6000
	s_add_u32 s99, s99, 0x3455000
	s_add_u32 s100, s90, s99
	s_addc_u32 s101, s91, 0
	global_load_dwordx4 v[64:67], v96, s[100:101] offset:0
	global_load_dwordx4 v[68:71], v96, s[100:101] offset:1024
	global_load_dwordx4 v[72:75], v96, s[100:101] offset:2048
	global_load_dwordx4 v[76:79], v96, s[100:101] offset:3072
	s_waitcnt vmcnt(12)
	v_mul_f32_e32 v80, v17, v17
	v_mul_f32_e32 v81, v21, v21
	v_mul_f32_e32 v82, v25, v25
	v_mul_f32_e32 v83, v29, v29
	v_fmac_f32_e32 v80, v16, v16
	v_fmac_f32_e32 v81, v20, v20
	v_fmac_f32_e32 v82, v24, v24
	v_fmac_f32_e32 v83, v28, v28
	v_fmac_f32_e32 v80, v18, v18
	v_fmac_f32_e32 v81, v22, v22
	v_fmac_f32_e32 v82, v26, v26
	v_fmac_f32_e32 v83, v30, v30
	v_fmac_f32_e32 v80, v19, v19
	v_fmac_f32_e32 v81, v23, v23
	v_fmac_f32_e32 v82, v27, v27
	v_fmac_f32_e32 v83, v31, v31
	v_add_f32_e32 v84, v80, v81
	v_add_f32_e32 v84, v84, v82
	v_add_f32_e32 v84, v84, v83
	ds_bpermute_b32 v85, v98, v84
	s_waitcnt lgkmcnt(0)
	v_add_f32_e32 v84, v84, v85
	ds_bpermute_b32 v85, v99, v84
	s_waitcnt lgkmcnt(0)
	v_add_f32_e32 v84, v84, v85
	ds_bpermute_b32 v85, v100, v84
	s_waitcnt lgkmcnt(0)
	v_add_f32_e32 v84, v84, v85
	ds_bpermute_b32 v85, v101, v84
	s_waitcnt lgkmcnt(0)
	v_add_f32_e32 v84, v84, v85
	ds_bpermute_b32 v85, v102, v84
	s_waitcnt lgkmcnt(0)
	v_add_f32_e32 v84, v84, v85
	ds_bpermute_b32 v85, v103, v84
	s_waitcnt lgkmcnt(0)
	v_add_f32_e32 v84, v84, v85
	v_fmamk_f32 v84, v84, 0x3a800000, v104
	v_mul_f32_e32 v85, 0x4b800000, v84
	v_cmp_gt_f32_e32 vcc, 0x800000, v84
	s_nop 1
	v_cndmask_b32_e32 v84, v84, v85, vcc
	v_rsq_f32_e32 v84, v84
	s_nop 0
	v_mul_f32_e32 v85, 0x45800000, v84
	v_cndmask_b32_e32 v106, v84, v85, vcc
	s_waitcnt vmcnt(0)
	s_lshl_b32 s99, s98, 11
	s_add_u32 s99, s99, 0xb171900
	s_add_u32 s100, s90, s99
	s_addc_u32 s101, s91, 0
	v_pk_mul_f32 v[16:17], v[16:17], v[106:107] op_sel_hi:[1,0]
	v_pk_mul_f32 v[18:19], v[18:19], v[106:107] op_sel_hi:[1,0]
	v_pk_mul_f32 v[16:17], v[32:33], v[16:17]
	v_pk_mul_f32 v[18:19], v[34:35], v[18:19]
	v_pk_add_f32 v[48:49], v[48:49], 1.0 op_sel_hi:[1,0]
	v_pk_add_f32 v[50:51], v[50:51], 1.0 op_sel_hi:[1,0]
	v_pk_fma_f32 v[16:17], v[48:49], v[16:17], v[64:65]
	v_pk_fma_f32 v[18:19], v[50:51], v[18:19], v[66:67]
	v_cvt_pk_bf16_f32 v16, v16, v17
	v_cvt_pk_bf16_f32 v17, v18, v19
	global_store_dwordx2 v97, v[16:17], s[100:101] offset:0
	v_pk_mul_f32 v[20:21], v[20:21], v[106:107] op_sel_hi:[1,0]
	v_pk_mul_f32 v[22:23], v[22:23], v[106:107] op_sel_hi:[1,0]
	v_pk_mul_f32 v[20:21], v[36:37], v[20:21]
	v_pk_mul_f32 v[22:23], v[38:39], v[22:23]
	v_pk_add_f32 v[52:53], v[52:53], 1.0 op_sel_hi:[1,0]
	v_pk_add_f32 v[54:55], v[54:55], 1.0 op_sel_hi:[1,0]
	v_pk_fma_f32 v[20:21], v[52:53], v[20:21], v[68:69]
	v_pk_fma_f32 v[22:23], v[54:55], v[22:23], v[70:71]
	v_cvt_pk_bf16_f32 v20, v20, v21
	v_cvt_pk_bf16_f32 v21, v22, v23
	global_store_dwordx2 v97, v[20:21], s[100:101] offset:512
	v_pk_mul_f32 v[24:25], v[24:25], v[106:107] op_sel_hi:[1,0]
	v_pk_mul_f32 v[26:27], v[26:27], v[106:107] op_sel_hi:[1,0]
	v_pk_mul_f32 v[24:25], v[40:41], v[24:25]
	v_pk_mul_f32 v[26:27], v[42:43], v[26:27]
	v_pk_add_f32 v[56:57], v[56:57], 1.0 op_sel_hi:[1,0]
	v_pk_add_f32 v[58:59], v[58:59], 1.0 op_sel_hi:[1,0]
	v_pk_fma_f32 v[24:25], v[56:57], v[24:25], v[72:73]
	v_pk_fma_f32 v[26:27], v[58:59], v[26:27], v[74:75]
	v_cvt_pk_bf16_f32 v24, v24, v25
	v_cvt_pk_bf16_f32 v25, v26, v27
	global_store_dwordx2 v97, v[24:25], s[100:101] offset:1024
	v_pk_mul_f32 v[28:29], v[28:29], v[106:107] op_sel_hi:[1,0]
	v_pk_mul_f32 v[30:31], v[30:31], v[106:107] op_sel_hi:[1,0]
	v_pk_mul_f32 v[28:29], v[44:45], v[28:29]
	v_pk_mul_f32 v[30:31], v[46:47], v[30:31]
	v_pk_add_f32 v[60:61], v[60:61], 1.0 op_sel_hi:[1,0]
	v_pk_add_f32 v[62:63], v[62:63], 1.0 op_sel_hi:[1,0]
	v_pk_fma_f32 v[28:29], v[60:61], v[28:29], v[76:77]
	v_pk_fma_f32 v[30:31], v[62:63], v[30:31], v[78:79]
	v_cvt_pk_bf16_f32 v28, v28, v29
	v_cvt_pk_bf16_f32 v29, v30, v31
	global_store_dwordx2 v97, v[28:29], s[100:101] offset:1536
